# GEMM K-loops: back-edge counter/compare SALU rotated above the closing barrier
# baseline (speedup 1.0000x reference)
; #define PG8_STAGE(bufoff, gbase, voff) do { _Pragma("unroll") for (int _i = 0; _i < 2; ++_i) \
;         __builtin_amdgcn_global_load_lds((const unsigned*)((const char*)(gbase) + (voff)[_i]), (LAS unsigned*)(lds + (bufoff) + ldsw + _i * 8192), 16, 0, 0); } while (0)
; #define PG8_LDA(dst, b, h) do { _Pragma("unroll") for (int m = 0; m < 4; ++m) _Pragma("unroll") for (int k = 0; k < 2; ++k) dst[m][k] = *(const LAS bf16x8*)(lds + PG8_SA(b, h) + aoff + m * 2048 + k * 1024); } while (0)
; #define PG8_LDB(dst, b, h) do { _Pragma("unroll") for (int n = 0; n < 2; ++n) _Pragma("unroll") for (int k = 0; k < 2; ++k) dst[n][k] = *(const LAS bf16x8*)(lds + PG8_SB(b, h) + boff + n * 2048 + k * 1024); } while (0)
; #define PG8_MMA(ai, bj, At, Bt) do { __builtin_amdgcn_s_setprio(1); _Pragma("unroll") for (int m = 0; m < 4; ++m) _Pragma("unroll") for (int n = 0; n < 2; ++n) _Pragma("unroll") for (int k = 0; k < 2; ++k) \
;         acc[ai][bj][m][n] = __builtin_amdgcn_mfma_f32_16x16x32_bf16(Bt[n][k], At[m][k], acc[ai][bj][m][n], 0, 0, 0); __builtin_amdgcn_s_setprio(0); } while (0)
; #define PG8_WAIT_V(n) asm volatile("s_waitcnt vmcnt(" #n ")" ::: "memory")
; #define PG8_WAIT_L(n) asm volatile("s_waitcnt lgkmcnt(" #n ")" ::: "memory")
; #define PG8_BAR __builtin_amdgcn_s_barrier()
; #define PG8_SCHED __builtin_amdgcn_sched_barrier(0)
; template <class Epi, class Sched, bool ALIGN_EPI = false, bool SP2 = false>
; __device__ __forceinline__ void gemm_phase(LAS unsigned char* lds, const Gemm g, const Sched S, const Epi E) {
;     ...
;             const char* a1 = cA + (size_t)(t + 1) * kstep;
;             const char* a2 = last ? nA : cA + (size_t)(t + 2) * kstep; const char* b2 = last ? nB : cB + (size_t)(t + 2) * kstep;
;             const char* a3 = a2 + kstep; const char* b3 = b2 + kstep;
;             if (last && has_next) S.a_ready(nxt);
;             if constexpr (SP2) {
;             PG8_LDB(B0, 0, 0); PG8_LDB(B1, 0, 1); PG8_SCHED; PG8_LDA(At, 0, 0); PG8_STAGE(PG8_SA(1, 1), a1 + hstepA, voffA);
;             PG8_WAIT_V(8); PG8_WAIT_L(0); PG8_BAR; PG8_MMA(0, 0, At, B0); PG8_MMA(0, 1, At, B1); PG8_BAR; PG8_SCHED;
;             PG8_LDA(At, 0, 1); PG8_STAGE(PG8_SB(0, 0), b2, voffB); PG8_STAGE(PG8_SB(0, 1), b2 + hstepB, voffB); PG8_STAGE(PG8_SA(0, 0), a2, voffA);
;             PG8_WAIT_V(8); PG8_WAIT_L(0); PG8_BAR; PG8_MMA(1, 0, At, B0); PG8_MMA(1, 1, At, B1); PG8_BAR; PG8_SCHED;
.LBB0_623:
	ds_read_b128 v[152:155], v149
	ds_read_b128 v[156:159], v149 offset:1024
	ds_read_b128 v[160:163], v149 offset:2048
	ds_read_b128 v[164:167], v149 offset:3072
	ds_read_b128 v[168:171], v150
	ds_read_b128 v[172:175], v150 offset:1024
	ds_read_b128 v[176:179], v150 offset:2048
	ds_read_b128 v[180:183], v150 offset:3072
	s_add_u32 s34, s68, 0xfffc0080
	s_addc_u32 s35, s69, -1
	s_cmp_eq_u32 s84, 12
	s_cselect_b32 s73, s61, s35
	s_cselect_b32 s72, s80, s34
	s_cselect_b32 s71, s51, s83
	s_cselect_b32 s70, s81, s82
	s_add_i32 m0, s29, 0xc000
	ds_read_b128 v[184:187], v151
	ds_read_b128 v[188:191], v151 offset:1024
	ds_read_b128 v[192:195], v151 offset:2048
	ds_read_b128 v[196:199], v151 offset:3072
	ds_read_b128 v[200:203], v151 offset:4096
	ds_read_b128 v[204:207], v151 offset:5120
	ds_read_b128 v[208:211], v151 offset:6144
	ds_read_b128 v[212:215], v151 offset:7168
	global_load_lds_dwordx4 v136, s[68:69]
	s_add_i32 m0, s29, 0xe000
	s_nop 0
	global_load_lds_dwordx4 v138, s[68:69]
	s_waitcnt vmcnt(8)
	s_waitcnt lgkmcnt(0)
	s_barrier
	s_setprio 1
	s_waitcnt lgkmcnt(0)
	v_mfma_f32_16x16x32_bf16 v[124:127], v[152:155], v[184:187], v[124:127]
	v_mfma_f32_16x16x32_bf16 v[120:123], v[160:163], v[184:187], v[120:123]
	v_mfma_f32_16x16x32_bf16 v[108:111], v[152:155], v[192:195], v[108:111]
	v_mfma_f32_16x16x32_bf16 v[104:107], v[160:163], v[192:195], v[104:107]
	v_mfma_f32_16x16x32_bf16 v[92:95], v[152:155], v[200:203], v[92:95]
	v_mfma_f32_16x16x32_bf16 v[88:91], v[160:163], v[200:203], v[88:91]
	v_mfma_f32_16x16x32_bf16 v[76:79], v[152:155], v[208:211], v[76:79]
	v_mfma_f32_16x16x32_bf16 v[72:75], v[160:163], v[208:211], v[72:75]
	v_mfma_f32_16x16x32_bf16 v[124:127], v[156:159], v[188:191], v[124:127]
	v_mfma_f32_16x16x32_bf16 v[120:123], v[164:167], v[188:191], v[120:123]
	v_mfma_f32_16x16x32_bf16 v[108:111], v[156:159], v[196:199], v[108:111]
	v_mfma_f32_16x16x32_bf16 v[104:107], v[164:167], v[196:199], v[104:107]
	v_mfma_f32_16x16x32_bf16 v[92:95], v[156:159], v[204:207], v[92:95]
	v_mfma_f32_16x16x32_bf16 v[88:91], v[164:167], v[204:207], v[88:91]
	v_mfma_f32_16x16x32_bf16 v[76:79], v[156:159], v[212:215], v[76:79]
	v_mfma_f32_16x16x32_bf16 v[72:75], v[164:167], v[212:215], v[72:75]
	s_setprio 0
	s_setprio 1
	v_mfma_f32_16x16x32_bf16 v[116:119], v[168:171], v[184:187], v[116:119]
	v_mfma_f32_16x16x32_bf16 v[112:115], v[176:179], v[184:187], v[112:115]
	v_mfma_f32_16x16x32_bf16 v[100:103], v[168:171], v[192:195], v[100:103]
	v_mfma_f32_16x16x32_bf16 v[96:99], v[176:179], v[192:195], v[96:99]
	v_mfma_f32_16x16x32_bf16 v[84:87], v[168:171], v[200:203], v[84:87]
	v_mfma_f32_16x16x32_bf16 v[80:83], v[176:179], v[200:203], v[80:83]
	v_mfma_f32_16x16x32_bf16 v[68:71], v[168:171], v[208:211], v[68:71]
	v_mfma_f32_16x16x32_bf16 v[64:67], v[176:179], v[208:211], v[64:67]
	v_mfma_f32_16x16x32_bf16 v[116:119], v[172:175], v[188:191], v[116:119]
	v_mfma_f32_16x16x32_bf16 v[112:115], v[180:183], v[188:191], v[112:115]
	v_mfma_f32_16x16x32_bf16 v[100:103], v[172:175], v[196:199], v[100:103]
	v_mfma_f32_16x16x32_bf16 v[96:99], v[180:183], v[196:199], v[96:99]
	v_mfma_f32_16x16x32_bf16 v[84:87], v[172:175], v[204:207], v[84:87]
	v_mfma_f32_16x16x32_bf16 v[80:83], v[180:183], v[204:207], v[80:83]
	v_mfma_f32_16x16x32_bf16 v[68:71], v[172:175], v[212:215], v[68:71]
	v_mfma_f32_16x16x32_bf16 v[64:67], v[180:183], v[212:215], v[64:67]
	s_setprio 0
	s_barrier
	s_add_i32 s34, s76, s20
	v_lshl_add_u64 v[144:145], s[70:71], 0, v[132:133]
	s_mov_b32 m0, s34
	ds_read_b128 v[184:187], v151 offset:16384
	ds_read_b128 v[188:191], v151 offset:17408
	ds_read_b128 v[192:195], v151 offset:18432
	ds_read_b128 v[196:199], v151 offset:19456
	ds_read_b128 v[200:203], v151 offset:20480
	ds_read_b128 v[204:207], v151 offset:21504
	ds_read_b128 v[208:211], v151 offset:22528
	ds_read_b128 v[212:215], v151 offset:23552
	global_load_lds_dwordx4 v[144:145], off
	s_add_i32 m0, s34, 0x2000
	s_add_u32 s34, s70, 0x40000
	v_lshl_add_u64 v[216:217], s[70:71], 0, v[128:129]
	s_addc_u32 s35, s71, 0
	s_add_i32 s85, s77, s20
	global_load_lds_dwordx4 v[216:217], off
	s_mov_b32 m0, s85
	v_lshl_add_u64 v[220:221], s[72:73], 0, v[130:131]
	global_load_lds_dwordx4 v132, s[34:35]
	s_add_i32 m0, s85, 0x2000
	s_nop 0
	global_load_lds_dwordx4 v128, s[34:35]
	v_lshl_add_u64 v[218:219], s[72:73], 0, v[134:135]
	s_mov_b32 m0, s29
	s_nop 0
	global_load_lds_dwordx4 v[218:219], off
	s_mov_b32 m0, s30
	s_nop 0
	global_load_lds_dwordx4 v[220:221], off
	s_waitcnt vmcnt(8)
	s_waitcnt lgkmcnt(0)
	s_barrier
; #define PG8_STAGE(bufoff, gbase, voff) do { _Pragma("unroll") for (int _i = 0; _i < 2; ++_i) \
;         __builtin_amdgcn_global_load_lds((const unsigned*)((const char*)(gbase) + (voff)[_i]), (LAS unsigned*)(lds + (bufoff) + ldsw + _i * 8192), 16, 0, 0); } while (0)
; #define PG8_LDA(dst, b, h) do { _Pragma("unroll") for (int m = 0; m < 4; ++m) _Pragma("unroll") for (int k = 0; k < 2; ++k) dst[m][k] = *(const LAS bf16x8*)(lds + PG8_SA(b, h) + aoff + m * 2048 + k * 1024); } while (0)
; #define PG8_LDB(dst, b, h) do { _Pragma("unroll") for (int n = 0; n < 2; ++n) _Pragma("unroll") for (int k = 0; k < 2; ++k) dst[n][k] = *(const LAS bf16x8*)(lds + PG8_SB(b, h) + boff + n * 2048 + k * 1024); } while (0)
; #define PG8_MMA(ai, bj, At, Bt) do { __builtin_amdgcn_s_setprio(1); _Pragma("unroll") for (int m = 0; m < 4; ++m) _Pragma("unroll") for (int n = 0; n < 2; ++n) _Pragma("unroll") for (int k = 0; k < 2; ++k) \
;         acc[ai][bj][m][n] = __builtin_amdgcn_mfma_f32_16x16x32_bf16(Bt[n][k], At[m][k], acc[ai][bj][m][n], 0, 0, 0); __builtin_amdgcn_s_setprio(0); } while (0)
; #define PG8_WAIT_V(n) asm volatile("s_waitcnt vmcnt(" #n ")" ::: "memory")
; #define PG8_WAIT_L(n) asm volatile("s_waitcnt lgkmcnt(" #n ")" ::: "memory")
; #define PG8_BAR __builtin_amdgcn_s_barrier()
; #define PG8_SCHED __builtin_amdgcn_sched_barrier(0)
; template <class Epi, class Sched, bool ALIGN_EPI = false, bool SP2 = false>
; __device__ __forceinline__ void gemm_phase(LAS unsigned char* lds, const Gemm g, const Sched S, const Epi E) {
;     ...
;             PG8_WAIT_V(8); PG8_WAIT_L(0); PG8_BAR; PG8_MMA(1, 0, At, B0); PG8_MMA(1, 1, At, B1); PG8_BAR; PG8_SCHED;
;             PG8_LDB(B0, 1, 0); PG8_LDB(B1, 1, 1); PG8_SCHED; PG8_LDA(At, 1, 0); PG8_STAGE(PG8_SA(0, 1), a2 + hstepA, voffA);
;             PG8_WAIT_V(8); PG8_WAIT_L(0); PG8_BAR; PG8_MMA(0, 0, At, B0); PG8_MMA(0, 1, At, B1); PG8_BAR; PG8_SCHED;
	s_setprio 1
	s_waitcnt lgkmcnt(0)
	v_mfma_f32_16x16x32_bf16 v[60:63], v[152:155], v[184:187], v[60:63]
	v_mfma_f32_16x16x32_bf16 v[56:59], v[160:163], v[184:187], v[56:59]
	v_mfma_f32_16x16x32_bf16 v[44:47], v[152:155], v[192:195], v[44:47]
	v_mfma_f32_16x16x32_bf16 v[40:43], v[160:163], v[192:195], v[40:43]
	v_mfma_f32_16x16x32_bf16 v[28:31], v[152:155], v[200:203], v[28:31]
	v_mfma_f32_16x16x32_bf16 v[24:27], v[160:163], v[200:203], v[24:27]
	v_mfma_f32_16x16x32_bf16 v[12:15], v[152:155], v[208:211], v[12:15]
	v_mfma_f32_16x16x32_bf16 v[8:11], v[160:163], v[208:211], v[8:11]
	v_mfma_f32_16x16x32_bf16 v[60:63], v[156:159], v[188:191], v[60:63]
	v_mfma_f32_16x16x32_bf16 v[56:59], v[164:167], v[188:191], v[56:59]
	v_mfma_f32_16x16x32_bf16 v[44:47], v[156:159], v[196:199], v[44:47]
	v_mfma_f32_16x16x32_bf16 v[40:43], v[164:167], v[196:199], v[40:43]
	v_mfma_f32_16x16x32_bf16 v[28:31], v[156:159], v[204:207], v[28:31]
	v_mfma_f32_16x16x32_bf16 v[24:27], v[164:167], v[204:207], v[24:27]
	v_mfma_f32_16x16x32_bf16 v[12:15], v[156:159], v[212:215], v[12:15]
	v_mfma_f32_16x16x32_bf16 v[8:11], v[164:167], v[212:215], v[8:11]
	s_setprio 0
	s_setprio 1
	v_mfma_f32_16x16x32_bf16 v[52:55], v[168:171], v[184:187], v[52:55]
	v_mfma_f32_16x16x32_bf16 v[48:51], v[176:179], v[184:187], v[48:51]
	v_mfma_f32_16x16x32_bf16 v[36:39], v[168:171], v[192:195], v[36:39]
	v_mfma_f32_16x16x32_bf16 v[32:35], v[176:179], v[192:195], v[32:35]
	v_mfma_f32_16x16x32_bf16 v[20:23], v[168:171], v[200:203], v[20:23]
	v_mfma_f32_16x16x32_bf16 v[16:19], v[176:179], v[200:203], v[16:19]
	v_mfma_f32_16x16x32_bf16 v[4:7], v[168:171], v[208:211], v[4:7]
	v_mfma_f32_16x16x32_bf16 v[0:3], v[176:179], v[208:211], v[0:3]
	v_mfma_f32_16x16x32_bf16 v[52:55], v[172:175], v[188:191], v[52:55]
	v_mfma_f32_16x16x32_bf16 v[48:51], v[180:183], v[188:191], v[48:51]
	v_mfma_f32_16x16x32_bf16 v[36:39], v[172:175], v[196:199], v[36:39]
	v_mfma_f32_16x16x32_bf16 v[32:35], v[180:183], v[196:199], v[32:35]
	v_mfma_f32_16x16x32_bf16 v[20:23], v[172:175], v[204:207], v[20:23]
	v_mfma_f32_16x16x32_bf16 v[16:19], v[180:183], v[204:207], v[16:19]
	v_mfma_f32_16x16x32_bf16 v[4:7], v[172:175], v[212:215], v[4:7]
	v_mfma_f32_16x16x32_bf16 v[0:3], v[180:183], v[212:215], v[0:3]
	s_setprio 0
	s_barrier
	s_add_i32 s85, 0, 0x18000
	s_add_i32 s86, 0, 0x1c000
	v_add_u32_e32 v164, s85, v147
	v_add_u32_e32 v180, s86, v147
	ds_read_b128 v[152:155], v164
	ds_read_b128 v[156:159], v164 offset:1024
	ds_read_b128 v[160:163], v164 offset:2048
	ds_read_b128 v[164:167], v164 offset:3072
	ds_read_b128 v[168:171], v180
	ds_read_b128 v[172:175], v180 offset:1024
	ds_read_b128 v[176:179], v180 offset:2048
	ds_read_b128 v[180:183], v180 offset:3072
	s_add_u32 s34, s72, 0x40000
	s_addc_u32 s35, s73, 0
	s_mov_b32 m0, s31
	ds_read_b128 v[184:187], v151 offset:32768
	ds_read_b128 v[188:191], v151 offset:33792
	ds_read_b128 v[192:195], v151 offset:34816
	ds_read_b128 v[196:199], v151 offset:35840
	ds_read_b128 v[200:203], v151 offset:36864
	ds_read_b128 v[204:207], v151 offset:37888
	ds_read_b128 v[208:211], v151 offset:38912
	ds_read_b128 v[212:215], v151 offset:39936
	global_load_lds_dwordx4 v134, s[34:35]
	s_mov_b32 m0, s33
	s_nop 0
	global_load_lds_dwordx4 v130, s[34:35]
	s_waitcnt vmcnt(8)
	s_waitcnt lgkmcnt(0)
	s_barrier
	s_setprio 1
	s_waitcnt lgkmcnt(0)
	v_mfma_f32_16x16x32_bf16 v[124:127], v[152:155], v[184:187], v[124:127]
	v_mfma_f32_16x16x32_bf16 v[120:123], v[160:163], v[184:187], v[120:123]
	v_mfma_f32_16x16x32_bf16 v[108:111], v[152:155], v[192:195], v[108:111]
	v_mfma_f32_16x16x32_bf16 v[104:107], v[160:163], v[192:195], v[104:107]
	v_mfma_f32_16x16x32_bf16 v[92:95], v[152:155], v[200:203], v[92:95]
	v_mfma_f32_16x16x32_bf16 v[88:91], v[160:163], v[200:203], v[88:91]
	v_mfma_f32_16x16x32_bf16 v[76:79], v[152:155], v[208:211], v[76:79]
	v_mfma_f32_16x16x32_bf16 v[72:75], v[160:163], v[208:211], v[72:75]
	v_mfma_f32_16x16x32_bf16 v[124:127], v[156:159], v[188:191], v[124:127]
	v_mfma_f32_16x16x32_bf16 v[120:123], v[164:167], v[188:191], v[120:123]
	v_mfma_f32_16x16x32_bf16 v[108:111], v[156:159], v[196:199], v[108:111]
	v_mfma_f32_16x16x32_bf16 v[104:107], v[164:167], v[196:199], v[104:107]
	v_mfma_f32_16x16x32_bf16 v[92:95], v[156:159], v[204:207], v[92:95]
	v_mfma_f32_16x16x32_bf16 v[88:91], v[164:167], v[204:207], v[88:91]
	v_mfma_f32_16x16x32_bf16 v[76:79], v[156:159], v[212:215], v[76:79]
	v_mfma_f32_16x16x32_bf16 v[72:75], v[164:167], v[212:215], v[72:75]
	s_setprio 0
	s_setprio 1
	v_mfma_f32_16x16x32_bf16 v[116:119], v[168:171], v[184:187], v[116:119]
	v_mfma_f32_16x16x32_bf16 v[112:115], v[176:179], v[184:187], v[112:115]
	v_mfma_f32_16x16x32_bf16 v[100:103], v[168:171], v[192:195], v[100:103]
	v_mfma_f32_16x16x32_bf16 v[96:99], v[176:179], v[192:195], v[96:99]
	v_mfma_f32_16x16x32_bf16 v[84:87], v[168:171], v[200:203], v[84:87]
	v_mfma_f32_16x16x32_bf16 v[80:83], v[176:179], v[200:203], v[80:83]
	v_mfma_f32_16x16x32_bf16 v[68:71], v[168:171], v[208:211], v[68:71]
	v_mfma_f32_16x16x32_bf16 v[64:67], v[176:179], v[208:211], v[64:67]
	v_mfma_f32_16x16x32_bf16 v[116:119], v[172:175], v[188:191], v[116:119]
	v_mfma_f32_16x16x32_bf16 v[112:115], v[180:183], v[188:191], v[112:115]
	v_mfma_f32_16x16x32_bf16 v[100:103], v[172:175], v[196:199], v[100:103]
	v_mfma_f32_16x16x32_bf16 v[96:99], v[180:183], v[196:199], v[96:99]
	v_mfma_f32_16x16x32_bf16 v[84:87], v[172:175], v[204:207], v[84:87]
	v_mfma_f32_16x16x32_bf16 v[80:83], v[180:183], v[204:207], v[80:83]
	v_mfma_f32_16x16x32_bf16 v[68:71], v[172:175], v[212:215], v[68:71]
	v_mfma_f32_16x16x32_bf16 v[64:67], v[180:183], v[212:215], v[64:67]
	s_setprio 0
	s_barrier
; #define PG8_STAGE(bufoff, gbase, voff) do { _Pragma("unroll") for (int _i = 0; _i < 2; ++_i) \
;         __builtin_amdgcn_global_load_lds((const unsigned*)((const char*)(gbase) + (voff)[_i]), (LAS unsigned*)(lds + (bufoff) + ldsw + _i * 8192), 16, 0, 0); } while (0)
; #define PG8_LDA(dst, b, h) do { _Pragma("unroll") for (int m = 0; m < 4; ++m) _Pragma("unroll") for (int k = 0; k < 2; ++k) dst[m][k] = *(const LAS bf16x8*)(lds + PG8_SA(b, h) + aoff + m * 2048 + k * 1024); } while (0)
; #define PG8_MMA(ai, bj, At, Bt) do { __builtin_amdgcn_s_setprio(1); _Pragma("unroll") for (int m = 0; m < 4; ++m) _Pragma("unroll") for (int n = 0; n < 2; ++n) _Pragma("unroll") for (int k = 0; k < 2; ++k) \
;         acc[ai][bj][m][n] = __builtin_amdgcn_mfma_f32_16x16x32_bf16(Bt[n][k], At[m][k], acc[ai][bj][m][n], 0, 0, 0); __builtin_amdgcn_s_setprio(0); } while (0)
; #define PG8_WAIT_V(n) asm volatile("s_waitcnt vmcnt(" #n ")" ::: "memory")
; #define PG8_WAIT_L(n) asm volatile("s_waitcnt lgkmcnt(" #n ")" ::: "memory")
; #define PG8_BAR __builtin_amdgcn_s_barrier()
; #define PG8_SCHED __builtin_amdgcn_sched_barrier(0)
; template <class Epi, class Sched, bool ALIGN_EPI = false, bool SP2 = false>
; __device__ __forceinline__ void gemm_phase(LAS unsigned char* lds, const Gemm g, const Sched S, const Epi E) {
;     ...
;         for (int t = 0; t < nt; t += 2) {
;     ...
;             PG8_LDA(At, 1, 1); PG8_STAGE(PG8_SB(1, 0), b3, voffB); PG8_STAGE(PG8_SB(1, 1), b3 + hstepB, voffB); PG8_STAGE(PG8_SA(1, 0), a3, voffA);
;             PG8_WAIT_V(8); PG8_WAIT_L(0); PG8_BAR; PG8_MMA(1, 0, At, B0); PG8_MMA(1, 1, At, B1); PG8_BAR; PG8_SCHED;
	s_add_i32 s34, s85, s20
	v_lshl_add_u64 v[144:145], v[144:145], 0, s[10:11]
	s_mov_b32 m0, s34
	ds_read_b128 v[184:187], v151 offset:49152
	ds_read_b128 v[188:191], v151 offset:50176
	ds_read_b128 v[192:195], v151 offset:51200
	ds_read_b128 v[196:199], v151 offset:52224
	ds_read_b128 v[200:203], v151 offset:53248
	ds_read_b128 v[204:207], v151 offset:54272
	ds_read_b128 v[208:211], v151 offset:55296
	ds_read_b128 v[212:215], v151 offset:56320
	global_load_lds_dwordx4 v[144:145], off
	s_add_i32 m0, s34, 0x2000
	s_add_u32 s34, s70, 0x40080
	v_lshl_add_u64 v[144:145], v[216:217], 0, s[10:11]
	s_addc_u32 s35, s71, 0
	s_add_i32 s70, s86, s20
	global_load_lds_dwordx4 v[144:145], off
	s_mov_b32 m0, s70
	s_nop 0
	global_load_lds_dwordx4 v132, s[34:35]
	s_add_i32 m0, s70, 0x2000
	s_nop 0
	global_load_lds_dwordx4 v128, s[34:35]
	v_lshl_add_u64 v[144:145], v[218:219], 0, s[10:11]
	s_mov_b32 m0, s45
	s_nop 0
	global_load_lds_dwordx4 v[144:145], off
	v_lshl_add_u64 v[144:145], v[220:221], 0, s[10:11]
	s_mov_b32 m0, s67
	s_nop 0
	global_load_lds_dwordx4 v[144:145], off
	s_waitcnt vmcnt(8)
	s_waitcnt lgkmcnt(0)
	s_barrier
	s_setprio 1
	s_waitcnt lgkmcnt(0)
	v_mfma_f32_16x16x32_bf16 v[60:63], v[152:155], v[184:187], v[60:63]
	v_mfma_f32_16x16x32_bf16 v[56:59], v[160:163], v[184:187], v[56:59]
	v_mfma_f32_16x16x32_bf16 v[44:47], v[152:155], v[192:195], v[44:47]
	v_mfma_f32_16x16x32_bf16 v[40:43], v[160:163], v[192:195], v[40:43]
	v_mfma_f32_16x16x32_bf16 v[28:31], v[152:155], v[200:203], v[28:31]
	v_mfma_f32_16x16x32_bf16 v[24:27], v[160:163], v[200:203], v[24:27]
	v_mfma_f32_16x16x32_bf16 v[12:15], v[152:155], v[208:211], v[12:15]
	v_mfma_f32_16x16x32_bf16 v[8:11], v[160:163], v[208:211], v[8:11]
	v_mfma_f32_16x16x32_bf16 v[60:63], v[156:159], v[188:191], v[60:63]
	v_mfma_f32_16x16x32_bf16 v[56:59], v[164:167], v[188:191], v[56:59]
	v_mfma_f32_16x16x32_bf16 v[44:47], v[156:159], v[196:199], v[44:47]
	v_mfma_f32_16x16x32_bf16 v[40:43], v[164:167], v[196:199], v[40:43]
	v_mfma_f32_16x16x32_bf16 v[28:31], v[156:159], v[204:207], v[28:31]
	v_mfma_f32_16x16x32_bf16 v[24:27], v[164:167], v[204:207], v[24:27]
	v_mfma_f32_16x16x32_bf16 v[12:15], v[156:159], v[212:215], v[12:15]
	v_mfma_f32_16x16x32_bf16 v[8:11], v[164:167], v[212:215], v[8:11]
	s_setprio 0
	s_setprio 1
	v_mfma_f32_16x16x32_bf16 v[52:55], v[168:171], v[184:187], v[52:55]
	v_mfma_f32_16x16x32_bf16 v[48:51], v[176:179], v[184:187], v[48:51]
	v_mfma_f32_16x16x32_bf16 v[36:39], v[168:171], v[192:195], v[36:39]
	v_mfma_f32_16x16x32_bf16 v[32:35], v[176:179], v[192:195], v[32:35]
	v_mfma_f32_16x16x32_bf16 v[20:23], v[168:171], v[200:203], v[20:23]
	v_mfma_f32_16x16x32_bf16 v[16:19], v[176:179], v[200:203], v[16:19]
	v_mfma_f32_16x16x32_bf16 v[4:7], v[168:171], v[208:211], v[4:7]
	v_mfma_f32_16x16x32_bf16 v[0:3], v[176:179], v[208:211], v[0:3]
	v_mfma_f32_16x16x32_bf16 v[52:55], v[172:175], v[188:191], v[52:55]
	v_mfma_f32_16x16x32_bf16 v[48:51], v[180:183], v[188:191], v[48:51]
	v_mfma_f32_16x16x32_bf16 v[36:39], v[172:175], v[196:199], v[36:39]
	v_mfma_f32_16x16x32_bf16 v[32:35], v[180:183], v[196:199], v[32:35]
	v_mfma_f32_16x16x32_bf16 v[20:23], v[172:175], v[204:207], v[20:23]
	v_mfma_f32_16x16x32_bf16 v[16:19], v[180:183], v[204:207], v[16:19]
	v_mfma_f32_16x16x32_bf16 v[4:7], v[172:175], v[212:215], v[4:7]
	v_mfma_f32_16x16x32_bf16 v[0:3], v[180:183], v[212:215], v[0:3]
	s_setprio 0
	s_add_i32 s84, s84, 2
	s_add_u32 s68, s68, 0x100
	s_addc_u32 s69, s69, 0
	s_add_u32 s82, s82, 0x100
	s_addc_u32 s83, s83, 0
	s_cmp_gt_u32 s84, 13
	s_barrier
	s_cbranch_scc0 .LBB0_623
	s_and_b64 vcc, exec, s[14:15]
	s_cbranch_vccz .LBB0_626
	s_barrier

; #define PG8_STAGE(bufoff, gbase, voff) do { _Pragma("unroll") for (int _i = 0; _i < 2; ++_i) \
;         __builtin_amdgcn_global_load_lds((const unsigned*)((const char*)(gbase) + (voff)[_i]), (LAS unsigned*)(lds + (bufoff) + ldsw + _i * 8192), 16, 0, 0); } while (0)
; #define PG8_LDA(dst, b, h) do { _Pragma("unroll") for (int m = 0; m < 4; ++m) _Pragma("unroll") for (int k = 0; k < 2; ++k) dst[m][k] = *(const LAS bf16x8*)(lds + PG8_SA(b, h) + aoff + m * 2048 + k * 1024); } while (0)
; #define PG8_LDB(dst, b, h) do { _Pragma("unroll") for (int n = 0; n < 2; ++n) _Pragma("unroll") for (int k = 0; k < 2; ++k) dst[n][k] = *(const LAS bf16x8*)(lds + PG8_SB(b, h) + boff + n * 2048 + k * 1024); } while (0)
; #define PG8_MMA(ai, bj, At, Bt) do { __builtin_amdgcn_s_setprio(1); _Pragma("unroll") for (int m = 0; m < 4; ++m) _Pragma("unroll") for (int n = 0; n < 2; ++n) _Pragma("unroll") for (int k = 0; k < 2; ++k) \
;         acc[ai][bj][m][n] = __builtin_amdgcn_mfma_f32_16x16x32_bf16(Bt[n][k], At[m][k], acc[ai][bj][m][n], 0, 0, 0); __builtin_amdgcn_s_setprio(0); } while (0)
; #define PG8_WAIT_V(n) asm volatile("s_waitcnt vmcnt(" #n ")" ::: "memory")
; #define PG8_WAIT_L(n) asm volatile("s_waitcnt lgkmcnt(" #n ")" ::: "memory")
; #define PG8_BAR __builtin_amdgcn_s_barrier()
; #define PG8_SCHED __builtin_amdgcn_sched_barrier(0)
; template <class Epi, class Sched, bool ALIGN_EPI = false, bool SP2 = false>
; __device__ __forceinline__ void gemm_phase(LAS unsigned char* lds, const Gemm g, const Sched S, const Epi E) {
;     ...
;             const char* a1 = cA + (size_t)(t + 1) * kstep;
;             const char* a2 = last ? nA : cA + (size_t)(t + 2) * kstep; const char* b2 = last ? nB : cB + (size_t)(t + 2) * kstep;
;             const char* a3 = a2 + kstep; const char* b3 = b2 + kstep;
;             if (last && has_next) S.a_ready(nxt);
;             if constexpr (SP2) {
;             PG8_LDB(B0, 0, 0); PG8_LDB(B1, 0, 1); PG8_SCHED; PG8_LDA(At, 0, 0); PG8_STAGE(PG8_SA(1, 1), a1 + hstepA, voffA);
;             PG8_WAIT_V(8); PG8_WAIT_L(0); PG8_BAR; PG8_MMA(0, 0, At, B0); PG8_MMA(0, 1, At, B1); PG8_BAR; PG8_SCHED;
;             PG8_LDA(At, 0, 1); PG8_STAGE(PG8_SB(0, 0), b2, voffB); PG8_STAGE(PG8_SB(0, 1), b2 + hstepB, voffB); PG8_STAGE(PG8_SA(0, 0), a2, voffA);
;             PG8_WAIT_V(8); PG8_WAIT_L(0); PG8_BAR; PG8_MMA(1, 0, At, B0); PG8_MMA(1, 1, At, B1); PG8_BAR; PG8_SCHED;
.LBB0_705:
	ds_read_b128 v[128:131], v173
	ds_read_b128 v[132:135], v173 offset:1024
	ds_read_b128 v[136:139], v173 offset:2048
	ds_read_b128 v[140:143], v173 offset:3072
	ds_read_b128 v[160:163], v174
	ds_read_b128 v[164:167], v174 offset:1024
	ds_read_b128 v[178:181], v174 offset:2048
	ds_read_b128 v[182:185], v174 offset:3072
	s_add_u32 s74, s72, 0x100
	s_addc_u32 s75, s73, 0
	s_cmp_eq_u32 s88, 40
	s_cselect_b32 s79, s11, s75
	s_cselect_b32 s78, s10, s74
	s_cselect_b32 s77, s71, s87
	s_cselect_b32 s76, s70, s86
	s_add_i32 m0, s5, 0xc000
	ds_read_b128 v[186:189], v175
	ds_read_b128 v[190:193], v175 offset:1024
	ds_read_b128 v[194:197], v175 offset:2048
	ds_read_b128 v[198:201], v175 offset:3072
	ds_read_b128 v[202:205], v175 offset:4096
	ds_read_b128 v[206:209], v175 offset:5120
	ds_read_b128 v[210:213], v175 offset:6144
	ds_read_b128 v[214:217], v175 offset:7168
	global_load_lds_dwordx4 v152, s[72:73]
	s_add_i32 m0, s5, 0xe000
	s_nop 0
	global_load_lds_dwordx4 v154, s[72:73]
	s_waitcnt vmcnt(8)
	s_waitcnt lgkmcnt(0)
	s_barrier
	s_setprio 1
	s_waitcnt lgkmcnt(0)
	v_mfma_f32_16x16x32_bf16 v[124:127], v[128:131], v[186:189], v[124:127]
	v_mfma_f32_16x16x32_bf16 v[120:123], v[136:139], v[186:189], v[120:123]
	v_mfma_f32_16x16x32_bf16 v[108:111], v[128:131], v[194:197], v[108:111]
	v_mfma_f32_16x16x32_bf16 v[104:107], v[136:139], v[194:197], v[104:107]
	v_mfma_f32_16x16x32_bf16 v[92:95], v[128:131], v[202:205], v[92:95]
	v_mfma_f32_16x16x32_bf16 v[88:91], v[136:139], v[202:205], v[88:91]
	v_mfma_f32_16x16x32_bf16 v[76:79], v[128:131], v[210:213], v[76:79]
	v_mfma_f32_16x16x32_bf16 v[72:75], v[136:139], v[210:213], v[72:75]
	v_mfma_f32_16x16x32_bf16 v[124:127], v[132:135], v[190:193], v[124:127]
	v_mfma_f32_16x16x32_bf16 v[120:123], v[140:143], v[190:193], v[120:123]
	v_mfma_f32_16x16x32_bf16 v[108:111], v[132:135], v[198:201], v[108:111]
	v_mfma_f32_16x16x32_bf16 v[104:107], v[140:143], v[198:201], v[104:107]
	v_mfma_f32_16x16x32_bf16 v[92:95], v[132:135], v[206:209], v[92:95]
	v_mfma_f32_16x16x32_bf16 v[88:91], v[140:143], v[206:209], v[88:91]
	v_mfma_f32_16x16x32_bf16 v[76:79], v[132:135], v[214:217], v[76:79]
	v_mfma_f32_16x16x32_bf16 v[72:75], v[140:143], v[214:217], v[72:75]
	s_setprio 0
	s_setprio 1
	v_mfma_f32_16x16x32_bf16 v[116:119], v[160:163], v[186:189], v[116:119]
	v_mfma_f32_16x16x32_bf16 v[112:115], v[178:181], v[186:189], v[112:115]
	v_mfma_f32_16x16x32_bf16 v[100:103], v[160:163], v[194:197], v[100:103]
	v_mfma_f32_16x16x32_bf16 v[96:99], v[178:181], v[194:197], v[96:99]
	v_mfma_f32_16x16x32_bf16 v[84:87], v[160:163], v[202:205], v[84:87]
	v_mfma_f32_16x16x32_bf16 v[80:83], v[178:181], v[202:205], v[80:83]
	v_mfma_f32_16x16x32_bf16 v[68:71], v[160:163], v[210:213], v[68:71]
	v_mfma_f32_16x16x32_bf16 v[64:67], v[178:181], v[210:213], v[64:67]
	v_mfma_f32_16x16x32_bf16 v[116:119], v[164:167], v[190:193], v[116:119]
	v_mfma_f32_16x16x32_bf16 v[112:115], v[182:185], v[190:193], v[112:115]
	v_mfma_f32_16x16x32_bf16 v[100:103], v[164:167], v[198:201], v[100:103]
	v_mfma_f32_16x16x32_bf16 v[96:99], v[182:185], v[198:201], v[96:99]
	v_mfma_f32_16x16x32_bf16 v[84:87], v[164:167], v[206:209], v[84:87]
	v_mfma_f32_16x16x32_bf16 v[80:83], v[182:185], v[206:209], v[80:83]
	v_mfma_f32_16x16x32_bf16 v[68:71], v[164:167], v[214:217], v[68:71]
	v_mfma_f32_16x16x32_bf16 v[64:67], v[182:185], v[214:217], v[64:67]
	s_setprio 0
	s_barrier
	s_add_i32 s34, s80, s4
	v_lshl_add_u64 v[168:169], s[76:77], 0, v[146:147]
	s_mov_b32 m0, s34
	ds_read_b128 v[186:189], v175 offset:16384
	ds_read_b128 v[190:193], v175 offset:17408
	ds_read_b128 v[194:197], v175 offset:18432
	ds_read_b128 v[198:201], v175 offset:19456
	ds_read_b128 v[202:205], v175 offset:20480
	ds_read_b128 v[206:209], v175 offset:21504
	ds_read_b128 v[210:213], v175 offset:22528
	ds_read_b128 v[214:217], v175 offset:23552
	global_load_lds_dwordx4 v[168:169], off
	s_add_i32 m0, s34, 0x2000
	s_add_u32 s34, s76, 0xb0000
	v_lshl_add_u64 v[218:219], s[76:77], 0, v[150:151]
	s_addc_u32 s35, s77, 0
	s_add_i32 s72, s81, s4
	global_load_lds_dwordx4 v[218:219], off
	s_mov_b32 m0, s72
	v_lshl_add_u64 v[222:223], s[78:79], 0, v[148:149]
	global_load_lds_dwordx4 v146, s[34:35]
	s_add_i32 m0, s72, 0x2000
	s_nop 0
	global_load_lds_dwordx4 v150, s[34:35]
	v_lshl_add_u64 v[220:221], s[78:79], 0, v[144:145]
	s_mov_b32 m0, s5
	s_nop 0
	global_load_lds_dwordx4 v[220:221], off
	s_mov_b32 m0, s20
	s_nop 0
	global_load_lds_dwordx4 v[222:223], off
	s_waitcnt vmcnt(8)
	s_waitcnt lgkmcnt(0)
	s_barrier
; #define PG8_STAGE(bufoff, gbase, voff) do { _Pragma("unroll") for (int _i = 0; _i < 2; ++_i) \
;         __builtin_amdgcn_global_load_lds((const unsigned*)((const char*)(gbase) + (voff)[_i]), (LAS unsigned*)(lds + (bufoff) + ldsw + _i * 8192), 16, 0, 0); } while (0)
; #define PG8_LDA(dst, b, h) do { _Pragma("unroll") for (int m = 0; m < 4; ++m) _Pragma("unroll") for (int k = 0; k < 2; ++k) dst[m][k] = *(const LAS bf16x8*)(lds + PG8_SA(b, h) + aoff + m * 2048 + k * 1024); } while (0)
; #define PG8_LDB(dst, b, h) do { _Pragma("unroll") for (int n = 0; n < 2; ++n) _Pragma("unroll") for (int k = 0; k < 2; ++k) dst[n][k] = *(const LAS bf16x8*)(lds + PG8_SB(b, h) + boff + n * 2048 + k * 1024); } while (0)
; #define PG8_MMA(ai, bj, At, Bt) do { __builtin_amdgcn_s_setprio(1); _Pragma("unroll") for (int m = 0; m < 4; ++m) _Pragma("unroll") for (int n = 0; n < 2; ++n) _Pragma("unroll") for (int k = 0; k < 2; ++k) \
;         acc[ai][bj][m][n] = __builtin_amdgcn_mfma_f32_16x16x32_bf16(Bt[n][k], At[m][k], acc[ai][bj][m][n], 0, 0, 0); __builtin_amdgcn_s_setprio(0); } while (0)
; #define PG8_WAIT_V(n) asm volatile("s_waitcnt vmcnt(" #n ")" ::: "memory")
; #define PG8_WAIT_L(n) asm volatile("s_waitcnt lgkmcnt(" #n ")" ::: "memory")
; #define PG8_BAR __builtin_amdgcn_s_barrier()
; #define PG8_SCHED __builtin_amdgcn_sched_barrier(0)
; template <class Epi, class Sched, bool ALIGN_EPI = false, bool SP2 = false>
; __device__ __forceinline__ void gemm_phase(LAS unsigned char* lds, const Gemm g, const Sched S, const Epi E) {
;     ...
;             PG8_WAIT_V(8); PG8_WAIT_L(0); PG8_BAR; PG8_MMA(1, 0, At, B0); PG8_MMA(1, 1, At, B1); PG8_BAR; PG8_SCHED;
;             PG8_LDB(B0, 1, 0); PG8_LDB(B1, 1, 1); PG8_SCHED; PG8_LDA(At, 1, 0); PG8_STAGE(PG8_SA(0, 1), a2 + hstepA, voffA);
;             PG8_WAIT_V(8); PG8_WAIT_L(0); PG8_BAR; PG8_MMA(0, 0, At, B0); PG8_MMA(0, 1, At, B1); PG8_BAR; PG8_SCHED;
	s_setprio 1
	s_waitcnt lgkmcnt(0)
	v_mfma_f32_16x16x32_bf16 v[60:63], v[128:131], v[186:189], v[60:63]
	v_mfma_f32_16x16x32_bf16 v[56:59], v[136:139], v[186:189], v[56:59]
	v_mfma_f32_16x16x32_bf16 v[44:47], v[128:131], v[194:197], v[44:47]
	v_mfma_f32_16x16x32_bf16 v[40:43], v[136:139], v[194:197], v[40:43]
	v_mfma_f32_16x16x32_bf16 v[28:31], v[128:131], v[202:205], v[28:31]
	v_mfma_f32_16x16x32_bf16 v[24:27], v[136:139], v[202:205], v[24:27]
	v_mfma_f32_16x16x32_bf16 v[12:15], v[128:131], v[210:213], v[12:15]
	v_mfma_f32_16x16x32_bf16 v[8:11], v[136:139], v[210:213], v[8:11]
	v_mfma_f32_16x16x32_bf16 v[60:63], v[132:135], v[190:193], v[60:63]
	v_mfma_f32_16x16x32_bf16 v[56:59], v[140:143], v[190:193], v[56:59]
	v_mfma_f32_16x16x32_bf16 v[44:47], v[132:135], v[198:201], v[44:47]
	v_mfma_f32_16x16x32_bf16 v[40:43], v[140:143], v[198:201], v[40:43]
	v_mfma_f32_16x16x32_bf16 v[28:31], v[132:135], v[206:209], v[28:31]
	v_mfma_f32_16x16x32_bf16 v[24:27], v[140:143], v[206:209], v[24:27]
	v_mfma_f32_16x16x32_bf16 v[12:15], v[132:135], v[214:217], v[12:15]
	v_mfma_f32_16x16x32_bf16 v[8:11], v[140:143], v[214:217], v[8:11]
	s_setprio 0
	s_setprio 1
	v_mfma_f32_16x16x32_bf16 v[52:55], v[160:163], v[186:189], v[52:55]
	v_mfma_f32_16x16x32_bf16 v[48:51], v[178:181], v[186:189], v[48:51]
	v_mfma_f32_16x16x32_bf16 v[36:39], v[160:163], v[194:197], v[36:39]
	v_mfma_f32_16x16x32_bf16 v[32:35], v[178:181], v[194:197], v[32:35]
	v_mfma_f32_16x16x32_bf16 v[20:23], v[160:163], v[202:205], v[20:23]
	v_mfma_f32_16x16x32_bf16 v[16:19], v[178:181], v[202:205], v[16:19]
	v_mfma_f32_16x16x32_bf16 v[4:7], v[160:163], v[210:213], v[4:7]
	v_mfma_f32_16x16x32_bf16 v[0:3], v[178:181], v[210:213], v[0:3]
	v_mfma_f32_16x16x32_bf16 v[52:55], v[164:167], v[190:193], v[52:55]
	v_mfma_f32_16x16x32_bf16 v[48:51], v[182:185], v[190:193], v[48:51]
	v_mfma_f32_16x16x32_bf16 v[36:39], v[164:167], v[198:201], v[36:39]
	v_mfma_f32_16x16x32_bf16 v[32:35], v[182:185], v[198:201], v[32:35]
	v_mfma_f32_16x16x32_bf16 v[20:23], v[164:167], v[206:209], v[20:23]
	v_mfma_f32_16x16x32_bf16 v[16:19], v[182:185], v[206:209], v[16:19]
	v_mfma_f32_16x16x32_bf16 v[4:7], v[164:167], v[214:217], v[4:7]
	v_mfma_f32_16x16x32_bf16 v[0:3], v[182:185], v[214:217], v[0:3]
	s_setprio 0
	s_barrier
	s_add_i32 s72, 0, 0x18000
	s_add_i32 s73, 0, 0x1c000
	v_add_u32_e32 v140, s72, v171
	v_add_u32_e32 v177, s73, v171
	ds_read_b128 v[128:131], v140
	ds_read_b128 v[132:135], v140 offset:1024
	ds_read_b128 v[136:139], v140 offset:2048
	ds_read_b128 v[140:143], v140 offset:3072
	ds_read_b128 v[160:163], v177
	ds_read_b128 v[164:167], v177 offset:1024
	ds_read_b128 v[178:181], v177 offset:2048
	ds_read_b128 v[182:185], v177 offset:3072
	s_add_u32 s34, s78, 0xb0000
	s_addc_u32 s35, s79, 0
	s_mov_b32 m0, s21
	ds_read_b128 v[186:189], v175 offset:32768
	ds_read_b128 v[190:193], v175 offset:33792
	ds_read_b128 v[194:197], v175 offset:34816
	ds_read_b128 v[198:201], v175 offset:35840
	ds_read_b128 v[202:205], v175 offset:36864
	ds_read_b128 v[206:209], v175 offset:37888
	ds_read_b128 v[210:213], v175 offset:38912
	ds_read_b128 v[214:217], v175 offset:39936
	global_load_lds_dwordx4 v144, s[34:35]
	s_mov_b32 m0, s29
	s_nop 0
	global_load_lds_dwordx4 v148, s[34:35]
	s_waitcnt vmcnt(8)
	s_waitcnt lgkmcnt(0)
	s_barrier
	s_setprio 1
	s_waitcnt lgkmcnt(0)
	v_mfma_f32_16x16x32_bf16 v[124:127], v[128:131], v[186:189], v[124:127]
	v_mfma_f32_16x16x32_bf16 v[120:123], v[136:139], v[186:189], v[120:123]
	v_mfma_f32_16x16x32_bf16 v[108:111], v[128:131], v[194:197], v[108:111]
	v_mfma_f32_16x16x32_bf16 v[104:107], v[136:139], v[194:197], v[104:107]
	v_mfma_f32_16x16x32_bf16 v[92:95], v[128:131], v[202:205], v[92:95]
	v_mfma_f32_16x16x32_bf16 v[88:91], v[136:139], v[202:205], v[88:91]
	v_mfma_f32_16x16x32_bf16 v[76:79], v[128:131], v[210:213], v[76:79]
	v_mfma_f32_16x16x32_bf16 v[72:75], v[136:139], v[210:213], v[72:75]
	v_mfma_f32_16x16x32_bf16 v[124:127], v[132:135], v[190:193], v[124:127]
	v_mfma_f32_16x16x32_bf16 v[120:123], v[140:143], v[190:193], v[120:123]
	v_mfma_f32_16x16x32_bf16 v[108:111], v[132:135], v[198:201], v[108:111]
	v_mfma_f32_16x16x32_bf16 v[104:107], v[140:143], v[198:201], v[104:107]
	v_mfma_f32_16x16x32_bf16 v[92:95], v[132:135], v[206:209], v[92:95]
	v_mfma_f32_16x16x32_bf16 v[88:91], v[140:143], v[206:209], v[88:91]
	v_mfma_f32_16x16x32_bf16 v[76:79], v[132:135], v[214:217], v[76:79]
	v_mfma_f32_16x16x32_bf16 v[72:75], v[140:143], v[214:217], v[72:75]
	s_setprio 0
	s_setprio 1
	v_mfma_f32_16x16x32_bf16 v[116:119], v[160:163], v[186:189], v[116:119]
	v_mfma_f32_16x16x32_bf16 v[112:115], v[178:181], v[186:189], v[112:115]
	v_mfma_f32_16x16x32_bf16 v[100:103], v[160:163], v[194:197], v[100:103]
	v_mfma_f32_16x16x32_bf16 v[96:99], v[178:181], v[194:197], v[96:99]
	v_mfma_f32_16x16x32_bf16 v[84:87], v[160:163], v[202:205], v[84:87]
	v_mfma_f32_16x16x32_bf16 v[80:83], v[178:181], v[202:205], v[80:83]
	v_mfma_f32_16x16x32_bf16 v[68:71], v[160:163], v[210:213], v[68:71]
	v_mfma_f32_16x16x32_bf16 v[64:67], v[178:181], v[210:213], v[64:67]
	v_mfma_f32_16x16x32_bf16 v[116:119], v[164:167], v[190:193], v[116:119]
	v_mfma_f32_16x16x32_bf16 v[112:115], v[182:185], v[190:193], v[112:115]
	v_mfma_f32_16x16x32_bf16 v[100:103], v[164:167], v[198:201], v[100:103]
	v_mfma_f32_16x16x32_bf16 v[96:99], v[182:185], v[198:201], v[96:99]
	v_mfma_f32_16x16x32_bf16 v[84:87], v[164:167], v[206:209], v[84:87]
	v_mfma_f32_16x16x32_bf16 v[80:83], v[182:185], v[206:209], v[80:83]
	v_mfma_f32_16x16x32_bf16 v[68:71], v[164:167], v[214:217], v[68:71]
	v_mfma_f32_16x16x32_bf16 v[64:67], v[182:185], v[214:217], v[64:67]
	s_setprio 0
	s_barrier
; #define PG8_STAGE(bufoff, gbase, voff) do { _Pragma("unroll") for (int _i = 0; _i < 2; ++_i) \
;         __builtin_amdgcn_global_load_lds((const unsigned*)((const char*)(gbase) + (voff)[_i]), (LAS unsigned*)(lds + (bufoff) + ldsw + _i * 8192), 16, 0, 0); } while (0)
; #define PG8_LDA(dst, b, h) do { _Pragma("unroll") for (int m = 0; m < 4; ++m) _Pragma("unroll") for (int k = 0; k < 2; ++k) dst[m][k] = *(const LAS bf16x8*)(lds + PG8_SA(b, h) + aoff + m * 2048 + k * 1024); } while (0)
; #define PG8_MMA(ai, bj, At, Bt) do { __builtin_amdgcn_s_setprio(1); _Pragma("unroll") for (int m = 0; m < 4; ++m) _Pragma("unroll") for (int n = 0; n < 2; ++n) _Pragma("unroll") for (int k = 0; k < 2; ++k) \
;         acc[ai][bj][m][n] = __builtin_amdgcn_mfma_f32_16x16x32_bf16(Bt[n][k], At[m][k], acc[ai][bj][m][n], 0, 0, 0); __builtin_amdgcn_s_setprio(0); } while (0)
; #define PG8_WAIT_V(n) asm volatile("s_waitcnt vmcnt(" #n ")" ::: "memory")
; #define PG8_WAIT_L(n) asm volatile("s_waitcnt lgkmcnt(" #n ")" ::: "memory")
; #define PG8_BAR __builtin_amdgcn_s_barrier()
; #define PG8_SCHED __builtin_amdgcn_sched_barrier(0)
; template <class Epi, class Sched, bool ALIGN_EPI = false, bool SP2 = false>
; __device__ __forceinline__ void gemm_phase(LAS unsigned char* lds, const Gemm g, const Sched S, const Epi E) {
;     ...
;         for (int t = 0; t < nt; t += 2) {
;     ...
;             PG8_LDA(At, 1, 1); PG8_STAGE(PG8_SB(1, 0), b3, voffB); PG8_STAGE(PG8_SB(1, 1), b3 + hstepB, voffB); PG8_STAGE(PG8_SA(1, 0), a3, voffA);
;             PG8_WAIT_V(8); PG8_WAIT_L(0); PG8_BAR; PG8_MMA(1, 0, At, B0); PG8_MMA(1, 1, At, B1); PG8_BAR; PG8_SCHED;
	s_add_i32 s34, s72, s4
	v_lshl_add_u64 v[168:169], v[168:169], 0, s[60:61]
	s_mov_b32 m0, s34
	ds_read_b128 v[186:189], v175 offset:49152
	ds_read_b128 v[190:193], v175 offset:50176
	ds_read_b128 v[194:197], v175 offset:51200
	ds_read_b128 v[198:201], v175 offset:52224
	ds_read_b128 v[202:205], v175 offset:53248
	ds_read_b128 v[206:209], v175 offset:54272
	ds_read_b128 v[210:213], v175 offset:55296
	ds_read_b128 v[214:217], v175 offset:56320
	global_load_lds_dwordx4 v[168:169], off
	s_add_i32 m0, s34, 0x2000
	s_add_u32 s34, s76, 0xb0080
	v_lshl_add_u64 v[168:169], v[218:219], 0, s[60:61]
	s_addc_u32 s35, s77, 0
	s_add_i32 s72, s73, s4
	global_load_lds_dwordx4 v[168:169], off
	s_mov_b32 m0, s72
	s_nop 0
	global_load_lds_dwordx4 v146, s[34:35]
	s_add_i32 m0, s72, 0x2000
	s_nop 0
	global_load_lds_dwordx4 v150, s[34:35]
	v_lshl_add_u64 v[168:169], v[220:221], 0, s[60:61]
	s_mov_b32 m0, s31
	s_nop 0
	global_load_lds_dwordx4 v[168:169], off
	v_lshl_add_u64 v[168:169], v[222:223], 0, s[60:61]
	s_mov_b32 m0, s33
	s_nop 0
	global_load_lds_dwordx4 v[168:169], off
	s_waitcnt vmcnt(8)
	s_waitcnt lgkmcnt(0)
	s_barrier
	s_setprio 1
	s_waitcnt lgkmcnt(0)
	v_mfma_f32_16x16x32_bf16 v[60:63], v[128:131], v[186:189], v[60:63]
	v_mfma_f32_16x16x32_bf16 v[56:59], v[136:139], v[186:189], v[56:59]
	v_mfma_f32_16x16x32_bf16 v[44:47], v[128:131], v[194:197], v[44:47]
	v_mfma_f32_16x16x32_bf16 v[40:43], v[136:139], v[194:197], v[40:43]
	v_mfma_f32_16x16x32_bf16 v[28:31], v[128:131], v[202:205], v[28:31]
	v_mfma_f32_16x16x32_bf16 v[24:27], v[136:139], v[202:205], v[24:27]
	v_mfma_f32_16x16x32_bf16 v[12:15], v[128:131], v[210:213], v[12:15]
	v_mfma_f32_16x16x32_bf16 v[8:11], v[136:139], v[210:213], v[8:11]
	v_mfma_f32_16x16x32_bf16 v[60:63], v[132:135], v[190:193], v[60:63]
	v_mfma_f32_16x16x32_bf16 v[56:59], v[140:143], v[190:193], v[56:59]
	v_mfma_f32_16x16x32_bf16 v[44:47], v[132:135], v[198:201], v[44:47]
	v_mfma_f32_16x16x32_bf16 v[40:43], v[140:143], v[198:201], v[40:43]
	v_mfma_f32_16x16x32_bf16 v[28:31], v[132:135], v[206:209], v[28:31]
	v_mfma_f32_16x16x32_bf16 v[24:27], v[140:143], v[206:209], v[24:27]
	v_mfma_f32_16x16x32_bf16 v[12:15], v[132:135], v[214:217], v[12:15]
	v_mfma_f32_16x16x32_bf16 v[8:11], v[140:143], v[214:217], v[8:11]
	s_setprio 0
	s_setprio 1
	v_mfma_f32_16x16x32_bf16 v[52:55], v[160:163], v[186:189], v[52:55]
	v_mfma_f32_16x16x32_bf16 v[48:51], v[178:181], v[186:189], v[48:51]
	v_mfma_f32_16x16x32_bf16 v[36:39], v[160:163], v[194:197], v[36:39]
	v_mfma_f32_16x16x32_bf16 v[32:35], v[178:181], v[194:197], v[32:35]
	v_mfma_f32_16x16x32_bf16 v[20:23], v[160:163], v[202:205], v[20:23]
	v_mfma_f32_16x16x32_bf16 v[16:19], v[178:181], v[202:205], v[16:19]
	v_mfma_f32_16x16x32_bf16 v[4:7], v[160:163], v[210:213], v[4:7]
	v_mfma_f32_16x16x32_bf16 v[0:3], v[178:181], v[210:213], v[0:3]
	v_mfma_f32_16x16x32_bf16 v[52:55], v[164:167], v[190:193], v[52:55]
	v_mfma_f32_16x16x32_bf16 v[48:51], v[182:185], v[190:193], v[48:51]
	v_mfma_f32_16x16x32_bf16 v[36:39], v[164:167], v[198:201], v[36:39]
	v_mfma_f32_16x16x32_bf16 v[32:35], v[182:185], v[198:201], v[32:35]
	v_mfma_f32_16x16x32_bf16 v[20:23], v[164:167], v[206:209], v[20:23]
	v_mfma_f32_16x16x32_bf16 v[16:19], v[182:185], v[206:209], v[16:19]
	v_mfma_f32_16x16x32_bf16 v[4:7], v[164:167], v[214:217], v[4:7]
	v_mfma_f32_16x16x32_bf16 v[0:3], v[182:185], v[214:217], v[0:3]
	s_setprio 0
	s_add_i32 s88, s88, 2
	s_add_u32 s86, s86, 0x100
	s_addc_u32 s87, s87, 0
	s_cmp_gt_u32 s88, 41
	s_mov_b64 s[72:73], s[74:75]
	s_barrier
	s_cbranch_scc0 .LBB0_705
	s_and_b64 vcc, exec, s[62:63]
	s_cbranch_vccz .LBB0_708
	s_barrier

; #define PG8_STAGE(bufoff, gbase, voff) do { _Pragma("unroll") for (int _i = 0; _i < 2; ++_i) \
;         __builtin_amdgcn_global_load_lds((const unsigned*)((const char*)(gbase) + (voff)[_i]), (LAS unsigned*)(lds + (bufoff) + ldsw + _i * 8192), 16, 0, 0); } while (0)
; #define PG8_LDA(dst, b, h) do { _Pragma("unroll") for (int m = 0; m < 4; ++m) _Pragma("unroll") for (int k = 0; k < 2; ++k) dst[m][k] = *(const LAS bf16x8*)(lds + PG8_SA(b, h) + aoff + m * 2048 + k * 1024); } while (0)
; #define PG8_LDB(dst, b, h) do { _Pragma("unroll") for (int n = 0; n < 2; ++n) _Pragma("unroll") for (int k = 0; k < 2; ++k) dst[n][k] = *(const LAS bf16x8*)(lds + PG8_SB(b, h) + boff + n * 2048 + k * 1024); } while (0)
; #define PG8_MMA(ai, bj, At, Bt) do { __builtin_amdgcn_s_setprio(1); _Pragma("unroll") for (int m = 0; m < 4; ++m) _Pragma("unroll") for (int n = 0; n < 2; ++n) _Pragma("unroll") for (int k = 0; k < 2; ++k) \
;         acc[ai][bj][m][n] = __builtin_amdgcn_mfma_f32_16x16x32_bf16(Bt[n][k], At[m][k], acc[ai][bj][m][n], 0, 0, 0); __builtin_amdgcn_s_setprio(0); } while (0)
; #define PG8_WAIT_V(n) asm volatile("s_waitcnt vmcnt(" #n ")" ::: "memory")
; #define PG8_WAIT_L(n) asm volatile("s_waitcnt lgkmcnt(" #n ")" ::: "memory")
; #define PG8_BAR __builtin_amdgcn_s_barrier()
; #define PG8_SCHED __builtin_amdgcn_sched_barrier(0)
; template <class Epi, class Sched, bool ALIGN_EPI = false, bool SP2 = false>
; __device__ __forceinline__ void gemm_phase(LAS unsigned char* lds, const Gemm g, const Sched S, const Epi E) {
;     ...
;             const char* a1 = cA + (size_t)(t + 1) * kstep;
;             const char* a2 = last ? nA : cA + (size_t)(t + 2) * kstep; const char* b2 = last ? nB : cB + (size_t)(t + 2) * kstep;
;             const char* a3 = a2 + kstep; const char* b3 = b2 + kstep;
;             if (last && has_next) S.a_ready(nxt);
;             if constexpr (SP2) {
;             PG8_LDB(B0, 0, 0); PG8_LDB(B1, 0, 1); PG8_SCHED; PG8_LDA(At, 0, 0); PG8_STAGE(PG8_SA(1, 1), a1 + hstepA, voffA);
;             PG8_WAIT_V(8); PG8_WAIT_L(0); PG8_BAR; PG8_MMA(0, 0, At, B0); PG8_MMA(0, 1, At, B1); PG8_BAR; PG8_SCHED;
;             PG8_LDA(At, 0, 1); PG8_STAGE(PG8_SB(0, 0), b2, voffB); PG8_STAGE(PG8_SB(0, 1), b2 + hstepB, voffB); PG8_STAGE(PG8_SA(0, 0), a2, voffA);
;             PG8_WAIT_V(8); PG8_WAIT_L(0); PG8_BAR; PG8_MMA(1, 0, At, B0); PG8_MMA(1, 1, At, B1); PG8_BAR; PG8_SCHED;
.LBB0_791:
	ds_read_b128 v[146:149], v153
	ds_read_b128 v[158:161], v153 offset:1024
	ds_read_b128 v[162:165], v153 offset:2048
	ds_read_b128 v[166:169], v153 offset:3072
	ds_read_b128 v[170:173], v154
	ds_read_b128 v[174:177], v154 offset:1024
	ds_read_b128 v[178:181], v154 offset:2048
	ds_read_b128 v[182:185], v154 offset:3072
	s_add_u32 s34, s72, 0xfff80080
	s_addc_u32 s35, s73, -1
	s_cmp_eq_u32 s88, 12
	s_cselect_b32 s77, s11, s35
	s_cselect_b32 s76, s63, s34
	s_cselect_b32 s75, s61, s87
	s_cselect_b32 s74, s71, s86
	s_add_i32 m0, s5, 0xc000
	ds_read_b128 v[186:189], v155
	ds_read_b128 v[190:193], v155 offset:1024
	ds_read_b128 v[194:197], v155 offset:2048
	ds_read_b128 v[198:201], v155 offset:3072
	ds_read_b128 v[202:205], v155 offset:4096
	ds_read_b128 v[206:209], v155 offset:5120
	ds_read_b128 v[210:213], v155 offset:6144
	ds_read_b128 v[214:217], v155 offset:7168
	global_load_lds_dwordx4 v138, s[72:73]
	s_add_i32 m0, s5, 0xe000
	s_nop 0
	global_load_lds_dwordx4 v140, s[72:73]
	s_waitcnt vmcnt(8)
	s_waitcnt lgkmcnt(0)
	s_barrier
	s_setprio 1
	s_waitcnt lgkmcnt(0)
	v_mfma_f32_16x16x32_bf16 v[124:127], v[146:149], v[186:189], v[124:127]
	v_mfma_f32_16x16x32_bf16 v[120:123], v[162:165], v[186:189], v[120:123]
	v_mfma_f32_16x16x32_bf16 v[108:111], v[146:149], v[194:197], v[108:111]
	v_mfma_f32_16x16x32_bf16 v[104:107], v[162:165], v[194:197], v[104:107]
	v_mfma_f32_16x16x32_bf16 v[92:95], v[146:149], v[202:205], v[92:95]
	v_mfma_f32_16x16x32_bf16 v[88:91], v[162:165], v[202:205], v[88:91]
	v_mfma_f32_16x16x32_bf16 v[76:79], v[146:149], v[210:213], v[76:79]
	v_mfma_f32_16x16x32_bf16 v[72:75], v[162:165], v[210:213], v[72:75]
	v_mfma_f32_16x16x32_bf16 v[124:127], v[158:161], v[190:193], v[124:127]
	v_mfma_f32_16x16x32_bf16 v[120:123], v[166:169], v[190:193], v[120:123]
	v_mfma_f32_16x16x32_bf16 v[108:111], v[158:161], v[198:201], v[108:111]
	v_mfma_f32_16x16x32_bf16 v[104:107], v[166:169], v[198:201], v[104:107]
	v_mfma_f32_16x16x32_bf16 v[92:95], v[158:161], v[206:209], v[92:95]
	v_mfma_f32_16x16x32_bf16 v[88:91], v[166:169], v[206:209], v[88:91]
	v_mfma_f32_16x16x32_bf16 v[76:79], v[158:161], v[214:217], v[76:79]
	v_mfma_f32_16x16x32_bf16 v[72:75], v[166:169], v[214:217], v[72:75]
	s_setprio 0
	s_setprio 1
	v_mfma_f32_16x16x32_bf16 v[116:119], v[170:173], v[186:189], v[116:119]
	v_mfma_f32_16x16x32_bf16 v[112:115], v[178:181], v[186:189], v[112:115]
	v_mfma_f32_16x16x32_bf16 v[100:103], v[170:173], v[194:197], v[100:103]
	v_mfma_f32_16x16x32_bf16 v[96:99], v[178:181], v[194:197], v[96:99]
	v_mfma_f32_16x16x32_bf16 v[84:87], v[170:173], v[202:205], v[84:87]
	v_mfma_f32_16x16x32_bf16 v[80:83], v[178:181], v[202:205], v[80:83]
	v_mfma_f32_16x16x32_bf16 v[68:71], v[170:173], v[210:213], v[68:71]
	v_mfma_f32_16x16x32_bf16 v[64:67], v[178:181], v[210:213], v[64:67]
	v_mfma_f32_16x16x32_bf16 v[116:119], v[174:177], v[190:193], v[116:119]
	v_mfma_f32_16x16x32_bf16 v[112:115], v[182:185], v[190:193], v[112:115]
	v_mfma_f32_16x16x32_bf16 v[100:103], v[174:177], v[198:201], v[100:103]
	v_mfma_f32_16x16x32_bf16 v[96:99], v[182:185], v[198:201], v[96:99]
	v_mfma_f32_16x16x32_bf16 v[84:87], v[174:177], v[206:209], v[84:87]
	v_mfma_f32_16x16x32_bf16 v[80:83], v[182:185], v[206:209], v[80:83]
	v_mfma_f32_16x16x32_bf16 v[68:71], v[174:177], v[214:217], v[68:71]
	v_mfma_f32_16x16x32_bf16 v[64:67], v[182:185], v[214:217], v[64:67]
	s_setprio 0
	s_barrier
	s_add_i32 s34, s80, s4
	v_lshl_add_u64 v[218:219], s[74:75], 0, v[130:131]
	s_mov_b32 m0, s34
	ds_read_b128 v[186:189], v155 offset:16384
	ds_read_b128 v[190:193], v155 offset:17408
	ds_read_b128 v[194:197], v155 offset:18432
	ds_read_b128 v[198:201], v155 offset:19456
	ds_read_b128 v[202:205], v155 offset:20480
	ds_read_b128 v[206:209], v155 offset:21504
	ds_read_b128 v[210:213], v155 offset:22528
	ds_read_b128 v[214:217], v155 offset:23552
	global_load_lds_dwordx4 v[218:219], off
	s_add_i32 m0, s34, 0x2000
	s_add_u32 s34, s74, 0x40000
	v_lshl_add_u64 v[220:221], s[74:75], 0, v[134:135]
	s_addc_u32 s35, s75, 0
	s_add_i32 s89, s81, s4
	global_load_lds_dwordx4 v[220:221], off
	s_mov_b32 m0, s89
	v_lshl_add_u64 v[224:225], s[76:77], 0, v[132:133]
	global_load_lds_dwordx4 v130, s[34:35]
	s_add_i32 m0, s89, 0x2000
	s_nop 0
	global_load_lds_dwordx4 v134, s[34:35]
	v_lshl_add_u64 v[222:223], s[76:77], 0, v[128:129]
	s_mov_b32 m0, s5
	s_nop 0
	global_load_lds_dwordx4 v[222:223], off
	s_mov_b32 m0, s20
	s_nop 0
	global_load_lds_dwordx4 v[224:225], off
	s_waitcnt vmcnt(8)
	s_waitcnt lgkmcnt(0)
	s_barrier
; #define PG8_STAGE(bufoff, gbase, voff) do { _Pragma("unroll") for (int _i = 0; _i < 2; ++_i) \
;         __builtin_amdgcn_global_load_lds((const unsigned*)((const char*)(gbase) + (voff)[_i]), (LAS unsigned*)(lds + (bufoff) + ldsw + _i * 8192), 16, 0, 0); } while (0)
; #define PG8_LDA(dst, b, h) do { _Pragma("unroll") for (int m = 0; m < 4; ++m) _Pragma("unroll") for (int k = 0; k < 2; ++k) dst[m][k] = *(const LAS bf16x8*)(lds + PG8_SA(b, h) + aoff + m * 2048 + k * 1024); } while (0)
; #define PG8_LDB(dst, b, h) do { _Pragma("unroll") for (int n = 0; n < 2; ++n) _Pragma("unroll") for (int k = 0; k < 2; ++k) dst[n][k] = *(const LAS bf16x8*)(lds + PG8_SB(b, h) + boff + n * 2048 + k * 1024); } while (0)
; #define PG8_MMA(ai, bj, At, Bt) do { __builtin_amdgcn_s_setprio(1); _Pragma("unroll") for (int m = 0; m < 4; ++m) _Pragma("unroll") for (int n = 0; n < 2; ++n) _Pragma("unroll") for (int k = 0; k < 2; ++k) \
;         acc[ai][bj][m][n] = __builtin_amdgcn_mfma_f32_16x16x32_bf16(Bt[n][k], At[m][k], acc[ai][bj][m][n], 0, 0, 0); __builtin_amdgcn_s_setprio(0); } while (0)
; #define PG8_WAIT_V(n) asm volatile("s_waitcnt vmcnt(" #n ")" ::: "memory")
; #define PG8_WAIT_L(n) asm volatile("s_waitcnt lgkmcnt(" #n ")" ::: "memory")
; #define PG8_BAR __builtin_amdgcn_s_barrier()
; #define PG8_SCHED __builtin_amdgcn_sched_barrier(0)
; template <class Epi, class Sched, bool ALIGN_EPI = false, bool SP2 = false>
; __device__ __forceinline__ void gemm_phase(LAS unsigned char* lds, const Gemm g, const Sched S, const Epi E) {
;     ...
;             PG8_WAIT_V(8); PG8_WAIT_L(0); PG8_BAR; PG8_MMA(1, 0, At, B0); PG8_MMA(1, 1, At, B1); PG8_BAR; PG8_SCHED;
;             PG8_LDB(B0, 1, 0); PG8_LDB(B1, 1, 1); PG8_SCHED; PG8_LDA(At, 1, 0); PG8_STAGE(PG8_SA(0, 1), a2 + hstepA, voffA);
;             PG8_WAIT_V(8); PG8_WAIT_L(0); PG8_BAR; PG8_MMA(0, 0, At, B0); PG8_MMA(0, 1, At, B1); PG8_BAR; PG8_SCHED;
	s_setprio 1
	s_waitcnt lgkmcnt(0)
	v_mfma_f32_16x16x32_bf16 v[60:63], v[146:149], v[186:189], v[60:63]
	v_mfma_f32_16x16x32_bf16 v[56:59], v[162:165], v[186:189], v[56:59]
	v_mfma_f32_16x16x32_bf16 v[44:47], v[146:149], v[194:197], v[44:47]
	v_mfma_f32_16x16x32_bf16 v[40:43], v[162:165], v[194:197], v[40:43]
	v_mfma_f32_16x16x32_bf16 v[28:31], v[146:149], v[202:205], v[28:31]
	v_mfma_f32_16x16x32_bf16 v[24:27], v[162:165], v[202:205], v[24:27]
	v_mfma_f32_16x16x32_bf16 v[12:15], v[146:149], v[210:213], v[12:15]
	v_mfma_f32_16x16x32_bf16 v[8:11], v[162:165], v[210:213], v[8:11]
	v_mfma_f32_16x16x32_bf16 v[60:63], v[158:161], v[190:193], v[60:63]
	v_mfma_f32_16x16x32_bf16 v[56:59], v[166:169], v[190:193], v[56:59]
	v_mfma_f32_16x16x32_bf16 v[44:47], v[158:161], v[198:201], v[44:47]
	v_mfma_f32_16x16x32_bf16 v[40:43], v[166:169], v[198:201], v[40:43]
	v_mfma_f32_16x16x32_bf16 v[28:31], v[158:161], v[206:209], v[28:31]
	v_mfma_f32_16x16x32_bf16 v[24:27], v[166:169], v[206:209], v[24:27]
	v_mfma_f32_16x16x32_bf16 v[12:15], v[158:161], v[214:217], v[12:15]
	v_mfma_f32_16x16x32_bf16 v[8:11], v[166:169], v[214:217], v[8:11]
	s_setprio 0
	s_setprio 1
	v_mfma_f32_16x16x32_bf16 v[52:55], v[170:173], v[186:189], v[52:55]
	v_mfma_f32_16x16x32_bf16 v[48:51], v[178:181], v[186:189], v[48:51]
	v_mfma_f32_16x16x32_bf16 v[36:39], v[170:173], v[194:197], v[36:39]
	v_mfma_f32_16x16x32_bf16 v[32:35], v[178:181], v[194:197], v[32:35]
	v_mfma_f32_16x16x32_bf16 v[20:23], v[170:173], v[202:205], v[20:23]
	v_mfma_f32_16x16x32_bf16 v[16:19], v[178:181], v[202:205], v[16:19]
	v_mfma_f32_16x16x32_bf16 v[4:7], v[170:173], v[210:213], v[4:7]
	v_mfma_f32_16x16x32_bf16 v[0:3], v[178:181], v[210:213], v[0:3]
	v_mfma_f32_16x16x32_bf16 v[52:55], v[174:177], v[190:193], v[52:55]
	v_mfma_f32_16x16x32_bf16 v[48:51], v[182:185], v[190:193], v[48:51]
	v_mfma_f32_16x16x32_bf16 v[36:39], v[174:177], v[198:201], v[36:39]
	v_mfma_f32_16x16x32_bf16 v[32:35], v[182:185], v[198:201], v[32:35]
	v_mfma_f32_16x16x32_bf16 v[20:23], v[174:177], v[206:209], v[20:23]
	v_mfma_f32_16x16x32_bf16 v[16:19], v[182:185], v[206:209], v[16:19]
	v_mfma_f32_16x16x32_bf16 v[4:7], v[174:177], v[214:217], v[4:7]
	v_mfma_f32_16x16x32_bf16 v[0:3], v[182:185], v[214:217], v[0:3]
	s_setprio 0
	s_barrier
	s_add_i32 s89, 0, 0x18000
	s_add_i32 s90, 0, 0x1c000
	v_add_u32_e32 v166, s89, v151
	v_add_u32_e32 v182, s90, v151
	ds_read_b128 v[146:149], v166
	ds_read_b128 v[158:161], v166 offset:1024
	ds_read_b128 v[162:165], v166 offset:2048
	ds_read_b128 v[166:169], v166 offset:3072
	ds_read_b128 v[170:173], v182
	ds_read_b128 v[174:177], v182 offset:1024
	ds_read_b128 v[178:181], v182 offset:2048
	ds_read_b128 v[182:185], v182 offset:3072
	s_add_u32 s34, s76, 0x80000
	s_addc_u32 s35, s77, 0
	s_mov_b32 m0, s21
	ds_read_b128 v[186:189], v155 offset:32768
	ds_read_b128 v[190:193], v155 offset:33792
	ds_read_b128 v[194:197], v155 offset:34816
	ds_read_b128 v[198:201], v155 offset:35840
	ds_read_b128 v[202:205], v155 offset:36864
	ds_read_b128 v[206:209], v155 offset:37888
	ds_read_b128 v[210:213], v155 offset:38912
	ds_read_b128 v[214:217], v155 offset:39936
	global_load_lds_dwordx4 v128, s[34:35]
	s_mov_b32 m0, s29
	s_nop 0
	global_load_lds_dwordx4 v132, s[34:35]
	s_waitcnt vmcnt(8)
	s_waitcnt lgkmcnt(0)
	s_barrier
	s_setprio 1
	s_waitcnt lgkmcnt(0)
	v_mfma_f32_16x16x32_bf16 v[124:127], v[146:149], v[186:189], v[124:127]
	v_mfma_f32_16x16x32_bf16 v[120:123], v[162:165], v[186:189], v[120:123]
	v_mfma_f32_16x16x32_bf16 v[108:111], v[146:149], v[194:197], v[108:111]
	v_mfma_f32_16x16x32_bf16 v[104:107], v[162:165], v[194:197], v[104:107]
	v_mfma_f32_16x16x32_bf16 v[92:95], v[146:149], v[202:205], v[92:95]
	v_mfma_f32_16x16x32_bf16 v[88:91], v[162:165], v[202:205], v[88:91]
	v_mfma_f32_16x16x32_bf16 v[76:79], v[146:149], v[210:213], v[76:79]
	v_mfma_f32_16x16x32_bf16 v[72:75], v[162:165], v[210:213], v[72:75]
	v_mfma_f32_16x16x32_bf16 v[124:127], v[158:161], v[190:193], v[124:127]
	v_mfma_f32_16x16x32_bf16 v[120:123], v[166:169], v[190:193], v[120:123]
	v_mfma_f32_16x16x32_bf16 v[108:111], v[158:161], v[198:201], v[108:111]
	v_mfma_f32_16x16x32_bf16 v[104:107], v[166:169], v[198:201], v[104:107]
	v_mfma_f32_16x16x32_bf16 v[92:95], v[158:161], v[206:209], v[92:95]
	v_mfma_f32_16x16x32_bf16 v[88:91], v[166:169], v[206:209], v[88:91]
	v_mfma_f32_16x16x32_bf16 v[76:79], v[158:161], v[214:217], v[76:79]
	v_mfma_f32_16x16x32_bf16 v[72:75], v[166:169], v[214:217], v[72:75]
	s_setprio 0
	s_setprio 1
	v_mfma_f32_16x16x32_bf16 v[116:119], v[170:173], v[186:189], v[116:119]
	v_mfma_f32_16x16x32_bf16 v[112:115], v[178:181], v[186:189], v[112:115]
	v_mfma_f32_16x16x32_bf16 v[100:103], v[170:173], v[194:197], v[100:103]
	v_mfma_f32_16x16x32_bf16 v[96:99], v[178:181], v[194:197], v[96:99]
	v_mfma_f32_16x16x32_bf16 v[84:87], v[170:173], v[202:205], v[84:87]
	v_mfma_f32_16x16x32_bf16 v[80:83], v[178:181], v[202:205], v[80:83]
	v_mfma_f32_16x16x32_bf16 v[68:71], v[170:173], v[210:213], v[68:71]
	v_mfma_f32_16x16x32_bf16 v[64:67], v[178:181], v[210:213], v[64:67]
	v_mfma_f32_16x16x32_bf16 v[116:119], v[174:177], v[190:193], v[116:119]
	v_mfma_f32_16x16x32_bf16 v[112:115], v[182:185], v[190:193], v[112:115]
	v_mfma_f32_16x16x32_bf16 v[100:103], v[174:177], v[198:201], v[100:103]
	v_mfma_f32_16x16x32_bf16 v[96:99], v[182:185], v[198:201], v[96:99]
	v_mfma_f32_16x16x32_bf16 v[84:87], v[174:177], v[206:209], v[84:87]
	v_mfma_f32_16x16x32_bf16 v[80:83], v[182:185], v[206:209], v[80:83]
	v_mfma_f32_16x16x32_bf16 v[68:71], v[174:177], v[214:217], v[68:71]
	v_mfma_f32_16x16x32_bf16 v[64:67], v[182:185], v[214:217], v[64:67]
	s_setprio 0
	s_barrier
; #define PG8_STAGE(bufoff, gbase, voff) do { _Pragma("unroll") for (int _i = 0; _i < 2; ++_i) \
;         __builtin_amdgcn_global_load_lds((const unsigned*)((const char*)(gbase) + (voff)[_i]), (LAS unsigned*)(lds + (bufoff) + ldsw + _i * 8192), 16, 0, 0); } while (0)
; #define PG8_LDA(dst, b, h) do { _Pragma("unroll") for (int m = 0; m < 4; ++m) _Pragma("unroll") for (int k = 0; k < 2; ++k) dst[m][k] = *(const LAS bf16x8*)(lds + PG8_SA(b, h) + aoff + m * 2048 + k * 1024); } while (0)
; #define PG8_MMA(ai, bj, At, Bt) do { __builtin_amdgcn_s_setprio(1); _Pragma("unroll") for (int m = 0; m < 4; ++m) _Pragma("unroll") for (int n = 0; n < 2; ++n) _Pragma("unroll") for (int k = 0; k < 2; ++k) \
;         acc[ai][bj][m][n] = __builtin_amdgcn_mfma_f32_16x16x32_bf16(Bt[n][k], At[m][k], acc[ai][bj][m][n], 0, 0, 0); __builtin_amdgcn_s_setprio(0); } while (0)
; #define PG8_WAIT_V(n) asm volatile("s_waitcnt vmcnt(" #n ")" ::: "memory")
; #define PG8_WAIT_L(n) asm volatile("s_waitcnt lgkmcnt(" #n ")" ::: "memory")
; #define PG8_BAR __builtin_amdgcn_s_barrier()
; #define PG8_SCHED __builtin_amdgcn_sched_barrier(0)
; template <class Epi, class Sched, bool ALIGN_EPI = false, bool SP2 = false>
; __device__ __forceinline__ void gemm_phase(LAS unsigned char* lds, const Gemm g, const Sched S, const Epi E) {
;     ...
;         for (int t = 0; t < nt; t += 2) {
;     ...
;             PG8_LDA(At, 1, 1); PG8_STAGE(PG8_SB(1, 0), b3, voffB); PG8_STAGE(PG8_SB(1, 1), b3 + hstepB, voffB); PG8_STAGE(PG8_SA(1, 0), a3, voffA);
;             PG8_WAIT_V(8); PG8_WAIT_L(0); PG8_BAR; PG8_MMA(1, 0, At, B0); PG8_MMA(1, 1, At, B1); PG8_BAR; PG8_SCHED;
	s_add_i32 s34, s89, s4
	v_lshl_add_u64 v[218:219], v[218:219], 0, s[14:15]
	s_mov_b32 m0, s34
	ds_read_b128 v[186:189], v155 offset:49152
	ds_read_b128 v[190:193], v155 offset:50176
	ds_read_b128 v[194:197], v155 offset:51200
	ds_read_b128 v[198:201], v155 offset:52224
	ds_read_b128 v[202:205], v155 offset:53248
	ds_read_b128 v[206:209], v155 offset:54272
	ds_read_b128 v[210:213], v155 offset:55296
	ds_read_b128 v[214:217], v155 offset:56320
	global_load_lds_dwordx4 v[218:219], off
	s_add_i32 m0, s34, 0x2000
	s_add_u32 s34, s74, 0x40080
	v_lshl_add_u64 v[218:219], v[220:221], 0, s[14:15]
	s_addc_u32 s35, s75, 0
	s_add_i32 s74, s90, s4
	global_load_lds_dwordx4 v[218:219], off
	s_mov_b32 m0, s74
	s_nop 0
	global_load_lds_dwordx4 v130, s[34:35]
	s_add_i32 m0, s74, 0x2000
	s_nop 0
	global_load_lds_dwordx4 v134, s[34:35]
	v_lshl_add_u64 v[218:219], v[222:223], 0, s[14:15]
	s_mov_b32 m0, s33
	s_nop 0
	global_load_lds_dwordx4 v[218:219], off
	v_lshl_add_u64 v[218:219], v[224:225], 0, s[14:15]
	s_mov_b32 m0, s44
	s_nop 0
	global_load_lds_dwordx4 v[218:219], off
	s_waitcnt vmcnt(8)
	s_waitcnt lgkmcnt(0)
	s_barrier
	s_setprio 1
	s_waitcnt lgkmcnt(0)
	v_mfma_f32_16x16x32_bf16 v[60:63], v[146:149], v[186:189], v[60:63]
	v_mfma_f32_16x16x32_bf16 v[56:59], v[162:165], v[186:189], v[56:59]
	v_mfma_f32_16x16x32_bf16 v[44:47], v[146:149], v[194:197], v[44:47]
	v_mfma_f32_16x16x32_bf16 v[40:43], v[162:165], v[194:197], v[40:43]
	v_mfma_f32_16x16x32_bf16 v[28:31], v[146:149], v[202:205], v[28:31]
	v_mfma_f32_16x16x32_bf16 v[24:27], v[162:165], v[202:205], v[24:27]
	v_mfma_f32_16x16x32_bf16 v[12:15], v[146:149], v[210:213], v[12:15]
	v_mfma_f32_16x16x32_bf16 v[8:11], v[162:165], v[210:213], v[8:11]
	v_mfma_f32_16x16x32_bf16 v[60:63], v[158:161], v[190:193], v[60:63]
	v_mfma_f32_16x16x32_bf16 v[56:59], v[166:169], v[190:193], v[56:59]
	v_mfma_f32_16x16x32_bf16 v[44:47], v[158:161], v[198:201], v[44:47]
	v_mfma_f32_16x16x32_bf16 v[40:43], v[166:169], v[198:201], v[40:43]
	v_mfma_f32_16x16x32_bf16 v[28:31], v[158:161], v[206:209], v[28:31]
	v_mfma_f32_16x16x32_bf16 v[24:27], v[166:169], v[206:209], v[24:27]
	v_mfma_f32_16x16x32_bf16 v[12:15], v[158:161], v[214:217], v[12:15]
	v_mfma_f32_16x16x32_bf16 v[8:11], v[166:169], v[214:217], v[8:11]
	s_setprio 0
	s_setprio 1
	v_mfma_f32_16x16x32_bf16 v[52:55], v[170:173], v[186:189], v[52:55]
	v_mfma_f32_16x16x32_bf16 v[48:51], v[178:181], v[186:189], v[48:51]
	v_mfma_f32_16x16x32_bf16 v[36:39], v[170:173], v[194:197], v[36:39]
	v_mfma_f32_16x16x32_bf16 v[32:35], v[178:181], v[194:197], v[32:35]
	v_mfma_f32_16x16x32_bf16 v[20:23], v[170:173], v[202:205], v[20:23]
	v_mfma_f32_16x16x32_bf16 v[16:19], v[178:181], v[202:205], v[16:19]
	v_mfma_f32_16x16x32_bf16 v[4:7], v[170:173], v[210:213], v[4:7]
	v_mfma_f32_16x16x32_bf16 v[0:3], v[178:181], v[210:213], v[0:3]
	v_mfma_f32_16x16x32_bf16 v[52:55], v[174:177], v[190:193], v[52:55]
	v_mfma_f32_16x16x32_bf16 v[48:51], v[182:185], v[190:193], v[48:51]
	v_mfma_f32_16x16x32_bf16 v[36:39], v[174:177], v[198:201], v[36:39]
	v_mfma_f32_16x16x32_bf16 v[32:35], v[182:185], v[198:201], v[32:35]
	v_mfma_f32_16x16x32_bf16 v[20:23], v[174:177], v[206:209], v[20:23]
	v_mfma_f32_16x16x32_bf16 v[16:19], v[182:185], v[206:209], v[16:19]
	v_mfma_f32_16x16x32_bf16 v[4:7], v[174:177], v[214:217], v[4:7]
	v_mfma_f32_16x16x32_bf16 v[0:3], v[182:185], v[214:217], v[0:3]
	s_setprio 0
	s_add_i32 s88, s88, 2
	s_add_u32 s72, s72, 0x100
	s_addc_u32 s73, s73, 0
	s_add_u32 s86, s86, 0x100
	s_addc_u32 s87, s87, 0
	s_cmp_gt_u32 s88, 13
	s_barrier
	s_cbranch_scc0 .LBB0_791
	s_and_b64 vcc, exec, s[50:51]
	s_cbranch_vccz .LBB0_794
	s_barrier

; #define PG8_STAGE(bufoff, gbase, voff) do { _Pragma("unroll") for (int _i = 0; _i < 2; ++_i) \
;         __builtin_amdgcn_global_load_lds((const unsigned*)((const char*)(gbase) + (voff)[_i]), (LAS unsigned*)(lds + (bufoff) + ldsw + _i * 8192), 16, 0, 0); } while (0)
; #define PG8_LDA(dst, b, h) do { _Pragma("unroll") for (int m = 0; m < 4; ++m) _Pragma("unroll") for (int k = 0; k < 2; ++k) dst[m][k] = *(const LAS bf16x8*)(lds + PG8_SA(b, h) + aoff + m * 2048 + k * 1024); } while (0)
; #define PG8_LDB(dst, b, h) do { _Pragma("unroll") for (int n = 0; n < 2; ++n) _Pragma("unroll") for (int k = 0; k < 2; ++k) dst[n][k] = *(const LAS bf16x8*)(lds + PG8_SB(b, h) + boff + n * 2048 + k * 1024); } while (0)
; #define PG8_MMA(ai, bj, At, Bt) do { __builtin_amdgcn_s_setprio(1); _Pragma("unroll") for (int m = 0; m < 4; ++m) _Pragma("unroll") for (int n = 0; n < 2; ++n) _Pragma("unroll") for (int k = 0; k < 2; ++k) \
;         acc[ai][bj][m][n] = __builtin_amdgcn_mfma_f32_16x16x32_bf16(Bt[n][k], At[m][k], acc[ai][bj][m][n], 0, 0, 0); __builtin_amdgcn_s_setprio(0); } while (0)
; #define PG8_WAIT_V(n) asm volatile("s_waitcnt vmcnt(" #n ")" ::: "memory")
; #define PG8_WAIT_L(n) asm volatile("s_waitcnt lgkmcnt(" #n ")" ::: "memory")
; #define PG8_BAR __builtin_amdgcn_s_barrier()
; #define PG8_SCHED __builtin_amdgcn_sched_barrier(0)
; template <class Epi, class Sched, bool ALIGN_EPI = false, bool SP2 = false>
; __device__ __forceinline__ void gemm_phase(LAS unsigned char* lds, const Gemm g, const Sched S, const Epi E) {
;     ...
;             const char* a1 = cA + (size_t)(t + 1) * kstep;
;             const char* a2 = last ? nA : cA + (size_t)(t + 2) * kstep; const char* b2 = last ? nB : cB + (size_t)(t + 2) * kstep;
;             const char* a3 = a2 + kstep; const char* b3 = b2 + kstep;
;             if (last && has_next) S.a_ready(nxt);
;             if constexpr (SP2) {
;             PG8_LDB(B0, 0, 0); PG8_LDB(B1, 0, 1); PG8_SCHED; PG8_LDA(At, 0, 0); PG8_STAGE(PG8_SA(1, 1), a1 + hstepA, voffA);
;             PG8_WAIT_V(8); PG8_WAIT_L(0); PG8_BAR; PG8_MMA(0, 0, At, B0); PG8_MMA(0, 1, At, B1); PG8_BAR; PG8_SCHED;
;             PG8_LDA(At, 0, 1); PG8_STAGE(PG8_SB(0, 0), b2, voffB); PG8_STAGE(PG8_SB(0, 1), b2 + hstepB, voffB); PG8_STAGE(PG8_SA(0, 0), a2, voffA);
;             PG8_WAIT_V(8); PG8_WAIT_L(0); PG8_BAR; PG8_MMA(1, 0, At, B0); PG8_MMA(1, 1, At, B1); PG8_BAR; PG8_SCHED;
.LBB0_1407:
	ds_read_b128 v[150:153], v180
	ds_read_b128 v[154:157], v180 offset:1024
	ds_read_b128 v[158:161], v180 offset:2048
	ds_read_b128 v[162:165], v180 offset:3072
	ds_read_b128 v[166:169], v181
	ds_read_b128 v[170:173], v181 offset:1024
	ds_read_b128 v[184:187], v181 offset:2048
	ds_read_b128 v[188:191], v181 offset:3072
	s_add_u32 s56, s64, 0x100
	s_addc_u32 s57, s65, 0
	s_cmp_eq_u32 s80, 2
	s_cselect_b32 s67, s9, s57
	s_cselect_b32 s66, s8, s56
	s_cselect_b32 s59, s19, s79
	s_cselect_b32 s58, s18, s78
	s_add_i32 m0, s29, 0xc000
	ds_read_b128 v[192:195], v182
	ds_read_b128 v[196:199], v182 offset:1024
	ds_read_b128 v[200:203], v182 offset:2048
	ds_read_b128 v[204:207], v182 offset:3072
	ds_read_b128 v[208:211], v182 offset:4096
	ds_read_b128 v[212:215], v182 offset:5120
	ds_read_b128 v[216:219], v182 offset:6144
	ds_read_b128 v[220:223], v182 offset:7168
	global_load_lds_dwordx4 v142, s[64:65]
	s_add_i32 m0, s29, 0xe000
	s_nop 0
	global_load_lds_dwordx4 v144, s[64:65]
	s_waitcnt vmcnt(8)
	s_waitcnt lgkmcnt(0)
	s_barrier
	s_setprio 1
	s_waitcnt lgkmcnt(0)
	v_mfma_f32_16x16x32_bf16 v[124:127], v[150:153], v[192:195], v[124:127]
	v_mfma_f32_16x16x32_bf16 v[120:123], v[158:161], v[192:195], v[120:123]
	v_mfma_f32_16x16x32_bf16 v[108:111], v[150:153], v[200:203], v[108:111]
	v_mfma_f32_16x16x32_bf16 v[104:107], v[158:161], v[200:203], v[104:107]
	v_mfma_f32_16x16x32_bf16 v[92:95], v[150:153], v[208:211], v[92:95]
	v_mfma_f32_16x16x32_bf16 v[88:91], v[158:161], v[208:211], v[88:91]
	v_mfma_f32_16x16x32_bf16 v[76:79], v[150:153], v[216:219], v[76:79]
	v_mfma_f32_16x16x32_bf16 v[72:75], v[158:161], v[216:219], v[72:75]
	v_mfma_f32_16x16x32_bf16 v[124:127], v[154:157], v[196:199], v[124:127]
	v_mfma_f32_16x16x32_bf16 v[120:123], v[162:165], v[196:199], v[120:123]
	v_mfma_f32_16x16x32_bf16 v[108:111], v[154:157], v[204:207], v[108:111]
	v_mfma_f32_16x16x32_bf16 v[104:107], v[162:165], v[204:207], v[104:107]
	v_mfma_f32_16x16x32_bf16 v[92:95], v[154:157], v[212:215], v[92:95]
	v_mfma_f32_16x16x32_bf16 v[88:91], v[162:165], v[212:215], v[88:91]
	v_mfma_f32_16x16x32_bf16 v[76:79], v[154:157], v[220:223], v[76:79]
	v_mfma_f32_16x16x32_bf16 v[72:75], v[162:165], v[220:223], v[72:75]
	s_setprio 0
	s_setprio 1
	v_mfma_f32_16x16x32_bf16 v[116:119], v[166:169], v[192:195], v[116:119]
	v_mfma_f32_16x16x32_bf16 v[112:115], v[184:187], v[192:195], v[112:115]
	v_mfma_f32_16x16x32_bf16 v[100:103], v[166:169], v[200:203], v[100:103]
	v_mfma_f32_16x16x32_bf16 v[96:99], v[184:187], v[200:203], v[96:99]
	v_mfma_f32_16x16x32_bf16 v[84:87], v[166:169], v[208:211], v[84:87]
	v_mfma_f32_16x16x32_bf16 v[80:83], v[184:187], v[208:211], v[80:83]
	v_mfma_f32_16x16x32_bf16 v[68:71], v[166:169], v[216:219], v[68:71]
	v_mfma_f32_16x16x32_bf16 v[64:67], v[184:187], v[216:219], v[64:67]
	v_mfma_f32_16x16x32_bf16 v[116:119], v[170:173], v[196:199], v[116:119]
	v_mfma_f32_16x16x32_bf16 v[112:115], v[188:191], v[196:199], v[112:115]
	v_mfma_f32_16x16x32_bf16 v[100:103], v[170:173], v[204:207], v[100:103]
	v_mfma_f32_16x16x32_bf16 v[96:99], v[188:191], v[204:207], v[96:99]
	v_mfma_f32_16x16x32_bf16 v[84:87], v[170:173], v[212:215], v[84:87]
	v_mfma_f32_16x16x32_bf16 v[80:83], v[188:191], v[212:215], v[80:83]
	v_mfma_f32_16x16x32_bf16 v[68:71], v[170:173], v[220:223], v[68:71]
	v_mfma_f32_16x16x32_bf16 v[64:67], v[188:191], v[220:223], v[64:67]
	s_setprio 0
	s_barrier
	s_add_i32 s34, s71, s20
	v_lshl_add_u64 v[176:177], s[58:59], 0, v[132:133]
	s_mov_b32 m0, s34
	ds_read_b128 v[192:195], v182 offset:16384
	ds_read_b128 v[196:199], v182 offset:17408
	ds_read_b128 v[200:203], v182 offset:18432
	ds_read_b128 v[204:207], v182 offset:19456
	ds_read_b128 v[208:211], v182 offset:20480
	ds_read_b128 v[212:215], v182 offset:21504
	ds_read_b128 v[216:219], v182 offset:22528
	ds_read_b128 v[220:223], v182 offset:23552
	global_load_lds_dwordx4 v[176:177], off
	s_add_i32 m0, s34, 0x2000
	s_add_u32 s34, s58, 0x18000
	v_lshl_add_u64 v[224:225], s[58:59], 0, v[128:129]
	s_addc_u32 s35, s59, 0
	s_add_i32 s64, s72, s20
	global_load_lds_dwordx4 v[224:225], off
	s_mov_b32 m0, s64
	v_lshl_add_u64 v[228:229], s[66:67], 0, v[130:131]
	global_load_lds_dwordx4 v132, s[34:35]
	s_add_i32 m0, s64, 0x2000
	s_nop 0
	global_load_lds_dwordx4 v128, s[34:35]
	v_lshl_add_u64 v[226:227], s[66:67], 0, v[134:135]
	s_mov_b32 m0, s29
	s_nop 0
	global_load_lds_dwordx4 v[226:227], off
	s_mov_b32 m0, s30
	s_nop 0
	global_load_lds_dwordx4 v[228:229], off
	s_waitcnt vmcnt(8)
	s_waitcnt lgkmcnt(0)
	s_barrier
; #define PG8_STAGE(bufoff, gbase, voff) do { _Pragma("unroll") for (int _i = 0; _i < 2; ++_i) \
;         __builtin_amdgcn_global_load_lds((const unsigned*)((const char*)(gbase) + (voff)[_i]), (LAS unsigned*)(lds + (bufoff) + ldsw + _i * 8192), 16, 0, 0); } while (0)
; #define PG8_LDA(dst, b, h) do { _Pragma("unroll") for (int m = 0; m < 4; ++m) _Pragma("unroll") for (int k = 0; k < 2; ++k) dst[m][k] = *(const LAS bf16x8*)(lds + PG8_SA(b, h) + aoff + m * 2048 + k * 1024); } while (0)
; #define PG8_LDB(dst, b, h) do { _Pragma("unroll") for (int n = 0; n < 2; ++n) _Pragma("unroll") for (int k = 0; k < 2; ++k) dst[n][k] = *(const LAS bf16x8*)(lds + PG8_SB(b, h) + boff + n * 2048 + k * 1024); } while (0)
; #define PG8_MMA(ai, bj, At, Bt) do { __builtin_amdgcn_s_setprio(1); _Pragma("unroll") for (int m = 0; m < 4; ++m) _Pragma("unroll") for (int n = 0; n < 2; ++n) _Pragma("unroll") for (int k = 0; k < 2; ++k) \
;         acc[ai][bj][m][n] = __builtin_amdgcn_mfma_f32_16x16x32_bf16(Bt[n][k], At[m][k], acc[ai][bj][m][n], 0, 0, 0); __builtin_amdgcn_s_setprio(0); } while (0)
; #define PG8_WAIT_V(n) asm volatile("s_waitcnt vmcnt(" #n ")" ::: "memory")
; #define PG8_WAIT_L(n) asm volatile("s_waitcnt lgkmcnt(" #n ")" ::: "memory")
; #define PG8_BAR __builtin_amdgcn_s_barrier()
; #define PG8_SCHED __builtin_amdgcn_sched_barrier(0)
; template <class Epi, class Sched, bool ALIGN_EPI = false, bool SP2 = false>
; __device__ __forceinline__ void gemm_phase(LAS unsigned char* lds, const Gemm g, const Sched S, const Epi E) {
;     ...
;             PG8_WAIT_V(8); PG8_WAIT_L(0); PG8_BAR; PG8_MMA(1, 0, At, B0); PG8_MMA(1, 1, At, B1); PG8_BAR; PG8_SCHED;
;             PG8_LDB(B0, 1, 0); PG8_LDB(B1, 1, 1); PG8_SCHED; PG8_LDA(At, 1, 0); PG8_STAGE(PG8_SA(0, 1), a2 + hstepA, voffA);
;             PG8_WAIT_V(8); PG8_WAIT_L(0); PG8_BAR; PG8_MMA(0, 0, At, B0); PG8_MMA(0, 1, At, B1); PG8_BAR; PG8_SCHED;
	s_setprio 1
	s_waitcnt lgkmcnt(0)
	v_mfma_f32_16x16x32_bf16 v[60:63], v[150:153], v[192:195], v[60:63]
	v_mfma_f32_16x16x32_bf16 v[56:59], v[158:161], v[192:195], v[56:59]
	v_mfma_f32_16x16x32_bf16 v[44:47], v[150:153], v[200:203], v[44:47]
	v_mfma_f32_16x16x32_bf16 v[40:43], v[158:161], v[200:203], v[40:43]
	v_mfma_f32_16x16x32_bf16 v[28:31], v[150:153], v[208:211], v[28:31]
	v_mfma_f32_16x16x32_bf16 v[24:27], v[158:161], v[208:211], v[24:27]
	v_mfma_f32_16x16x32_bf16 v[12:15], v[150:153], v[216:219], v[12:15]
	v_mfma_f32_16x16x32_bf16 v[8:11], v[158:161], v[216:219], v[8:11]
	v_mfma_f32_16x16x32_bf16 v[60:63], v[154:157], v[196:199], v[60:63]
	v_mfma_f32_16x16x32_bf16 v[56:59], v[162:165], v[196:199], v[56:59]
	v_mfma_f32_16x16x32_bf16 v[44:47], v[154:157], v[204:207], v[44:47]
	v_mfma_f32_16x16x32_bf16 v[40:43], v[162:165], v[204:207], v[40:43]
	v_mfma_f32_16x16x32_bf16 v[28:31], v[154:157], v[212:215], v[28:31]
	v_mfma_f32_16x16x32_bf16 v[24:27], v[162:165], v[212:215], v[24:27]
	v_mfma_f32_16x16x32_bf16 v[12:15], v[154:157], v[220:223], v[12:15]
	v_mfma_f32_16x16x32_bf16 v[8:11], v[162:165], v[220:223], v[8:11]
	s_setprio 0
	s_setprio 1
	v_mfma_f32_16x16x32_bf16 v[52:55], v[166:169], v[192:195], v[52:55]
	v_mfma_f32_16x16x32_bf16 v[48:51], v[184:187], v[192:195], v[48:51]
	v_mfma_f32_16x16x32_bf16 v[36:39], v[166:169], v[200:203], v[36:39]
	v_mfma_f32_16x16x32_bf16 v[32:35], v[184:187], v[200:203], v[32:35]
	v_mfma_f32_16x16x32_bf16 v[20:23], v[166:169], v[208:211], v[20:23]
	v_mfma_f32_16x16x32_bf16 v[16:19], v[184:187], v[208:211], v[16:19]
	v_mfma_f32_16x16x32_bf16 v[4:7], v[166:169], v[216:219], v[4:7]
	v_mfma_f32_16x16x32_bf16 v[0:3], v[184:187], v[216:219], v[0:3]
	v_mfma_f32_16x16x32_bf16 v[52:55], v[170:173], v[196:199], v[52:55]
	v_mfma_f32_16x16x32_bf16 v[48:51], v[188:191], v[196:199], v[48:51]
	v_mfma_f32_16x16x32_bf16 v[36:39], v[170:173], v[204:207], v[36:39]
	v_mfma_f32_16x16x32_bf16 v[32:35], v[188:191], v[204:207], v[32:35]
	v_mfma_f32_16x16x32_bf16 v[20:23], v[170:173], v[212:215], v[20:23]
	v_mfma_f32_16x16x32_bf16 v[16:19], v[188:191], v[212:215], v[16:19]
	v_mfma_f32_16x16x32_bf16 v[4:7], v[170:173], v[220:223], v[4:7]
	v_mfma_f32_16x16x32_bf16 v[0:3], v[188:191], v[220:223], v[0:3]
	s_setprio 0
	s_barrier
	s_add_i32 s64, 0, 0x18000
	s_add_i32 s65, 0, 0x1c000
	v_add_u32_e32 v162, s64, v178
	v_add_u32_e32 v174, s65, v178
	ds_read_b128 v[150:153], v162
	ds_read_b128 v[154:157], v162 offset:1024
	ds_read_b128 v[158:161], v162 offset:2048
	ds_read_b128 v[162:165], v162 offset:3072
	ds_read_b128 v[166:169], v174
	ds_read_b128 v[170:173], v174 offset:1024
	ds_read_b128 v[184:187], v174 offset:2048
	ds_read_b128 v[188:191], v174 offset:3072
	s_add_u32 s34, s66, 0x130000
	s_addc_u32 s35, s67, 0
	s_mov_b32 m0, s31
	ds_read_b128 v[192:195], v182 offset:32768
	ds_read_b128 v[196:199], v182 offset:33792
	ds_read_b128 v[200:203], v182 offset:34816
	ds_read_b128 v[204:207], v182 offset:35840
	ds_read_b128 v[208:211], v182 offset:36864
	ds_read_b128 v[212:215], v182 offset:37888
	ds_read_b128 v[216:219], v182 offset:38912
	ds_read_b128 v[220:223], v182 offset:39936
	global_load_lds_dwordx4 v134, s[34:35]
	s_mov_b32 m0, s33
	s_nop 0
	global_load_lds_dwordx4 v130, s[34:35]
	s_waitcnt vmcnt(8)
	s_waitcnt lgkmcnt(0)
	s_barrier
	s_setprio 1
	s_waitcnt lgkmcnt(0)
	v_mfma_f32_16x16x32_bf16 v[124:127], v[150:153], v[192:195], v[124:127]
	v_mfma_f32_16x16x32_bf16 v[120:123], v[158:161], v[192:195], v[120:123]
	v_mfma_f32_16x16x32_bf16 v[108:111], v[150:153], v[200:203], v[108:111]
	v_mfma_f32_16x16x32_bf16 v[104:107], v[158:161], v[200:203], v[104:107]
	v_mfma_f32_16x16x32_bf16 v[92:95], v[150:153], v[208:211], v[92:95]
	v_mfma_f32_16x16x32_bf16 v[88:91], v[158:161], v[208:211], v[88:91]
	v_mfma_f32_16x16x32_bf16 v[76:79], v[150:153], v[216:219], v[76:79]
	v_mfma_f32_16x16x32_bf16 v[72:75], v[158:161], v[216:219], v[72:75]
	v_mfma_f32_16x16x32_bf16 v[124:127], v[154:157], v[196:199], v[124:127]
	v_mfma_f32_16x16x32_bf16 v[120:123], v[162:165], v[196:199], v[120:123]
	v_mfma_f32_16x16x32_bf16 v[108:111], v[154:157], v[204:207], v[108:111]
	v_mfma_f32_16x16x32_bf16 v[104:107], v[162:165], v[204:207], v[104:107]
	v_mfma_f32_16x16x32_bf16 v[92:95], v[154:157], v[212:215], v[92:95]
	v_mfma_f32_16x16x32_bf16 v[88:91], v[162:165], v[212:215], v[88:91]
	v_mfma_f32_16x16x32_bf16 v[76:79], v[154:157], v[220:223], v[76:79]
	v_mfma_f32_16x16x32_bf16 v[72:75], v[162:165], v[220:223], v[72:75]
	s_setprio 0
	s_setprio 1
	v_mfma_f32_16x16x32_bf16 v[116:119], v[166:169], v[192:195], v[116:119]
	v_mfma_f32_16x16x32_bf16 v[112:115], v[184:187], v[192:195], v[112:115]
	v_mfma_f32_16x16x32_bf16 v[100:103], v[166:169], v[200:203], v[100:103]
	v_mfma_f32_16x16x32_bf16 v[96:99], v[184:187], v[200:203], v[96:99]
	v_mfma_f32_16x16x32_bf16 v[84:87], v[166:169], v[208:211], v[84:87]
	v_mfma_f32_16x16x32_bf16 v[80:83], v[184:187], v[208:211], v[80:83]
	v_mfma_f32_16x16x32_bf16 v[68:71], v[166:169], v[216:219], v[68:71]
	v_mfma_f32_16x16x32_bf16 v[64:67], v[184:187], v[216:219], v[64:67]
	v_mfma_f32_16x16x32_bf16 v[116:119], v[170:173], v[196:199], v[116:119]
	v_mfma_f32_16x16x32_bf16 v[112:115], v[188:191], v[196:199], v[112:115]
	v_mfma_f32_16x16x32_bf16 v[100:103], v[170:173], v[204:207], v[100:103]
	v_mfma_f32_16x16x32_bf16 v[96:99], v[188:191], v[204:207], v[96:99]
	v_mfma_f32_16x16x32_bf16 v[84:87], v[170:173], v[212:215], v[84:87]
	v_mfma_f32_16x16x32_bf16 v[80:83], v[188:191], v[212:215], v[80:83]
	v_mfma_f32_16x16x32_bf16 v[68:71], v[170:173], v[220:223], v[68:71]
	v_mfma_f32_16x16x32_bf16 v[64:67], v[188:191], v[220:223], v[64:67]
	s_setprio 0
	s_barrier
; #define PG8_STAGE(bufoff, gbase, voff) do { _Pragma("unroll") for (int _i = 0; _i < 2; ++_i) \
;         __builtin_amdgcn_global_load_lds((const unsigned*)((const char*)(gbase) + (voff)[_i]), (LAS unsigned*)(lds + (bufoff) + ldsw + _i * 8192), 16, 0, 0); } while (0)
; #define PG8_LDA(dst, b, h) do { _Pragma("unroll") for (int m = 0; m < 4; ++m) _Pragma("unroll") for (int k = 0; k < 2; ++k) dst[m][k] = *(const LAS bf16x8*)(lds + PG8_SA(b, h) + aoff + m * 2048 + k * 1024); } while (0)
; #define PG8_MMA(ai, bj, At, Bt) do { __builtin_amdgcn_s_setprio(1); _Pragma("unroll") for (int m = 0; m < 4; ++m) _Pragma("unroll") for (int n = 0; n < 2; ++n) _Pragma("unroll") for (int k = 0; k < 2; ++k) \
;         acc[ai][bj][m][n] = __builtin_amdgcn_mfma_f32_16x16x32_bf16(Bt[n][k], At[m][k], acc[ai][bj][m][n], 0, 0, 0); __builtin_amdgcn_s_setprio(0); } while (0)
; #define PG8_WAIT_V(n) asm volatile("s_waitcnt vmcnt(" #n ")" ::: "memory")
; #define PG8_WAIT_L(n) asm volatile("s_waitcnt lgkmcnt(" #n ")" ::: "memory")
; #define PG8_BAR __builtin_amdgcn_s_barrier()
; #define PG8_SCHED __builtin_amdgcn_sched_barrier(0)
; template <class Epi, class Sched, bool ALIGN_EPI = false, bool SP2 = false>
; __device__ __forceinline__ void gemm_phase(LAS unsigned char* lds, const Gemm g, const Sched S, const Epi E) {
;     ...
;         for (int t = 0; t < nt; t += 2) {
;     ...
;             PG8_LDA(At, 1, 1); PG8_STAGE(PG8_SB(1, 0), b3, voffB); PG8_STAGE(PG8_SB(1, 1), b3 + hstepB, voffB); PG8_STAGE(PG8_SA(1, 0), a3, voffA);
;             PG8_WAIT_V(8); PG8_WAIT_L(0); PG8_BAR; PG8_MMA(1, 0, At, B0); PG8_MMA(1, 1, At, B1); PG8_BAR; PG8_SCHED;
	s_add_i32 s34, s64, s20
	v_lshl_add_u64 v[176:177], v[176:177], 0, s[14:15]
	s_mov_b32 m0, s34
	ds_read_b128 v[192:195], v182 offset:49152
	ds_read_b128 v[196:199], v182 offset:50176
	ds_read_b128 v[200:203], v182 offset:51200
	ds_read_b128 v[204:207], v182 offset:52224
	ds_read_b128 v[208:211], v182 offset:53248
	ds_read_b128 v[212:215], v182 offset:54272
	ds_read_b128 v[216:219], v182 offset:55296
	ds_read_b128 v[220:223], v182 offset:56320
	global_load_lds_dwordx4 v[176:177], off
	s_add_i32 m0, s34, 0x2000
	s_add_u32 s34, s58, 0x18080
	v_lshl_add_u64 v[176:177], v[224:225], 0, s[14:15]
	s_addc_u32 s35, s59, 0
	s_add_i32 s58, s65, s20
	global_load_lds_dwordx4 v[176:177], off
	s_mov_b32 m0, s58
	s_nop 0
	global_load_lds_dwordx4 v132, s[34:35]
	s_add_i32 m0, s58, 0x2000
	s_nop 0
	global_load_lds_dwordx4 v128, s[34:35]
	v_lshl_add_u64 v[176:177], v[226:227], 0, s[14:15]
	s_mov_b32 m0, s44
	s_nop 0
	global_load_lds_dwordx4 v[176:177], off
	v_lshl_add_u64 v[176:177], v[228:229], 0, s[14:15]
	s_mov_b32 m0, s45
	s_nop 0
	global_load_lds_dwordx4 v[176:177], off
	s_waitcnt vmcnt(8)
	s_waitcnt lgkmcnt(0)
	s_barrier
	s_setprio 1
	s_waitcnt lgkmcnt(0)
	v_mfma_f32_16x16x32_bf16 v[60:63], v[150:153], v[192:195], v[60:63]
	v_mfma_f32_16x16x32_bf16 v[56:59], v[158:161], v[192:195], v[56:59]
	v_mfma_f32_16x16x32_bf16 v[44:47], v[150:153], v[200:203], v[44:47]
	v_mfma_f32_16x16x32_bf16 v[40:43], v[158:161], v[200:203], v[40:43]
	v_mfma_f32_16x16x32_bf16 v[28:31], v[150:153], v[208:211], v[28:31]
	v_mfma_f32_16x16x32_bf16 v[24:27], v[158:161], v[208:211], v[24:27]
	v_mfma_f32_16x16x32_bf16 v[12:15], v[150:153], v[216:219], v[12:15]
	v_mfma_f32_16x16x32_bf16 v[8:11], v[158:161], v[216:219], v[8:11]
	v_mfma_f32_16x16x32_bf16 v[60:63], v[154:157], v[196:199], v[60:63]
	v_mfma_f32_16x16x32_bf16 v[56:59], v[162:165], v[196:199], v[56:59]
	v_mfma_f32_16x16x32_bf16 v[44:47], v[154:157], v[204:207], v[44:47]
	v_mfma_f32_16x16x32_bf16 v[40:43], v[162:165], v[204:207], v[40:43]
	v_mfma_f32_16x16x32_bf16 v[28:31], v[154:157], v[212:215], v[28:31]
	v_mfma_f32_16x16x32_bf16 v[24:27], v[162:165], v[212:215], v[24:27]
	v_mfma_f32_16x16x32_bf16 v[12:15], v[154:157], v[220:223], v[12:15]
	v_mfma_f32_16x16x32_bf16 v[8:11], v[162:165], v[220:223], v[8:11]
	s_setprio 0
	s_setprio 1
	v_mfma_f32_16x16x32_bf16 v[52:55], v[166:169], v[192:195], v[52:55]
	v_mfma_f32_16x16x32_bf16 v[48:51], v[184:187], v[192:195], v[48:51]
	v_mfma_f32_16x16x32_bf16 v[36:39], v[166:169], v[200:203], v[36:39]
	v_mfma_f32_16x16x32_bf16 v[32:35], v[184:187], v[200:203], v[32:35]
	v_mfma_f32_16x16x32_bf16 v[20:23], v[166:169], v[208:211], v[20:23]
	v_mfma_f32_16x16x32_bf16 v[16:19], v[184:187], v[208:211], v[16:19]
	v_mfma_f32_16x16x32_bf16 v[4:7], v[166:169], v[216:219], v[4:7]
	v_mfma_f32_16x16x32_bf16 v[0:3], v[184:187], v[216:219], v[0:3]
	v_mfma_f32_16x16x32_bf16 v[52:55], v[170:173], v[196:199], v[52:55]
	v_mfma_f32_16x16x32_bf16 v[48:51], v[188:191], v[196:199], v[48:51]
	v_mfma_f32_16x16x32_bf16 v[36:39], v[170:173], v[204:207], v[36:39]
	v_mfma_f32_16x16x32_bf16 v[32:35], v[188:191], v[204:207], v[32:35]
	v_mfma_f32_16x16x32_bf16 v[20:23], v[170:173], v[212:215], v[20:23]
	v_mfma_f32_16x16x32_bf16 v[16:19], v[188:191], v[212:215], v[16:19]
	v_mfma_f32_16x16x32_bf16 v[4:7], v[170:173], v[220:223], v[4:7]
	v_mfma_f32_16x16x32_bf16 v[0:3], v[188:191], v[220:223], v[0:3]
	s_setprio 0
	s_add_i32 s80, s80, 2
	s_add_u32 s78, s78, 0x100
	s_addc_u32 s79, s79, 0
	s_cmp_gt_u32 s80, 3
	s_mov_b64 s[64:65], s[56:57]
	s_barrier
	s_cbranch_scc0 .LBB0_1407
	s_and_b64 vcc, exec, s[16:17]
	s_cbranch_vccz .LBB0_1410
	s_barrier

; #define PG8_STAGE(bufoff, gbase, voff) do { _Pragma("unroll") for (int _i = 0; _i < 2; ++_i) \
;         __builtin_amdgcn_global_load_lds((const unsigned*)((const char*)(gbase) + (voff)[_i]), (LAS unsigned*)(lds + (bufoff) + ldsw + _i * 8192), 16, 0, 0); } while (0)
; #define PG8_LDA(dst, b, h) do { _Pragma("unroll") for (int m = 0; m < 4; ++m) _Pragma("unroll") for (int k = 0; k < 2; ++k) dst[m][k] = *(const LAS bf16x8*)(lds + PG8_SA(b, h) + aoff + m * 2048 + k * 1024); } while (0)
; #define PG8_LDB(dst, b, h) do { _Pragma("unroll") for (int n = 0; n < 2; ++n) _Pragma("unroll") for (int k = 0; k < 2; ++k) dst[n][k] = *(const LAS bf16x8*)(lds + PG8_SB(b, h) + boff + n * 2048 + k * 1024); } while (0)
; #define PG8_MMA(ai, bj, At, Bt) do { __builtin_amdgcn_s_setprio(1); _Pragma("unroll") for (int m = 0; m < 4; ++m) _Pragma("unroll") for (int n = 0; n < 2; ++n) _Pragma("unroll") for (int k = 0; k < 2; ++k) \
;         acc[ai][bj][m][n] = __builtin_amdgcn_mfma_f32_16x16x32_bf16(Bt[n][k], At[m][k], acc[ai][bj][m][n], 0, 0, 0); __builtin_amdgcn_s_setprio(0); } while (0)
; #define PG8_WAIT_V(n) asm volatile("s_waitcnt vmcnt(" #n ")" ::: "memory")
; #define PG8_WAIT_L(n) asm volatile("s_waitcnt lgkmcnt(" #n ")" ::: "memory")
; #define PG8_BAR __builtin_amdgcn_s_barrier()
; #define PG8_SCHED __builtin_amdgcn_sched_barrier(0)
; template <class Epi, class Sched, bool ALIGN_EPI = false, bool SP2 = false>
; __device__ __forceinline__ void gemm_phase(LAS unsigned char* lds, const Gemm g, const Sched S, const Epi E) {
;     ...
;             const char* a1 = cA + (size_t)(t + 1) * kstep;
;             const char* a2 = last ? nA : cA + (size_t)(t + 2) * kstep; const char* b2 = last ? nB : cB + (size_t)(t + 2) * kstep;
;             const char* a3 = a2 + kstep; const char* b3 = b2 + kstep;
;             if (last && has_next) S.a_ready(nxt);
;             if constexpr (SP2) {
;             PG8_LDB(B0, 0, 0); PG8_LDB(B1, 0, 1); PG8_SCHED; PG8_LDA(At, 0, 0); PG8_STAGE(PG8_SA(1, 1), a1 + hstepA, voffA);
;             PG8_WAIT_V(8); PG8_WAIT_L(0); PG8_BAR; PG8_MMA(0, 0, At, B0); PG8_MMA(0, 1, At, B1); PG8_BAR; PG8_SCHED;
;             PG8_LDA(At, 0, 1); PG8_STAGE(PG8_SB(0, 0), b2, voffB); PG8_STAGE(PG8_SB(0, 1), b2 + hstepB, voffB); PG8_STAGE(PG8_SA(0, 0), a2, voffA);
;             PG8_WAIT_V(8); PG8_WAIT_L(0); PG8_BAR; PG8_MMA(1, 0, At, B0); PG8_MMA(1, 1, At, B1); PG8_BAR; PG8_SCHED;
.LBB0_1612:
	ds_read_b128 v[152:155], v149
	ds_read_b128 v[156:159], v149 offset:1024
	ds_read_b128 v[160:163], v149 offset:2048
	ds_read_b128 v[164:167], v149 offset:3072
	ds_read_b128 v[168:171], v150
	ds_read_b128 v[172:175], v150 offset:1024
	ds_read_b128 v[176:179], v150 offset:2048
	ds_read_b128 v[180:183], v150 offset:3072
	s_add_u32 s10, s54, 0x100
	s_addc_u32 s11, s55, 0
	s_cmp_eq_u32 s71, 12
	s_cselect_b32 s59, s49, s11
	s_cselect_b32 s58, s48, s10
	s_cselect_b32 s57, s19, s70
	s_cselect_b32 s56, s68, s69
	s_add_i32 m0, s21, 0xc000
	ds_read_b128 v[184:187], v151
	ds_read_b128 v[188:191], v151 offset:1024
	ds_read_b128 v[192:195], v151 offset:2048
	ds_read_b128 v[196:199], v151 offset:3072
	ds_read_b128 v[200:203], v151 offset:4096
	ds_read_b128 v[204:207], v151 offset:5120
	ds_read_b128 v[208:211], v151 offset:6144
	ds_read_b128 v[212:215], v151 offset:7168
	global_load_lds_dwordx4 v138, s[54:55]
	s_add_i32 m0, s21, 0xe000
	s_nop 0
	global_load_lds_dwordx4 v140, s[54:55]
	s_waitcnt vmcnt(8)
	s_waitcnt lgkmcnt(0)
	s_barrier
	s_setprio 1
	s_waitcnt lgkmcnt(0)
	v_mfma_f32_16x16x32_bf16 v[124:127], v[152:155], v[184:187], v[124:127]
	v_mfma_f32_16x16x32_bf16 v[120:123], v[160:163], v[184:187], v[120:123]
	v_mfma_f32_16x16x32_bf16 v[116:119], v[152:155], v[192:195], v[116:119]
	v_mfma_f32_16x16x32_bf16 v[112:115], v[160:163], v[192:195], v[112:115]
	v_mfma_f32_16x16x32_bf16 v[100:103], v[152:155], v[200:203], v[100:103]
	v_mfma_f32_16x16x32_bf16 v[96:99], v[160:163], v[200:203], v[96:99]
	v_mfma_f32_16x16x32_bf16 v[84:87], v[152:155], v[208:211], v[84:87]
	v_mfma_f32_16x16x32_bf16 v[80:83], v[160:163], v[208:211], v[80:83]
	v_mfma_f32_16x16x32_bf16 v[124:127], v[156:159], v[188:191], v[124:127]
	v_mfma_f32_16x16x32_bf16 v[120:123], v[164:167], v[188:191], v[120:123]
	v_mfma_f32_16x16x32_bf16 v[116:119], v[156:159], v[196:199], v[116:119]
	v_mfma_f32_16x16x32_bf16 v[112:115], v[164:167], v[196:199], v[112:115]
	v_mfma_f32_16x16x32_bf16 v[100:103], v[156:159], v[204:207], v[100:103]
	v_mfma_f32_16x16x32_bf16 v[96:99], v[164:167], v[204:207], v[96:99]
	v_mfma_f32_16x16x32_bf16 v[84:87], v[156:159], v[212:215], v[84:87]
	v_mfma_f32_16x16x32_bf16 v[80:83], v[164:167], v[212:215], v[80:83]
	s_setprio 0
	s_setprio 1
	v_mfma_f32_16x16x32_bf16 v[108:111], v[168:171], v[184:187], v[108:111]
	v_mfma_f32_16x16x32_bf16 v[104:107], v[176:179], v[184:187], v[104:107]
	v_mfma_f32_16x16x32_bf16 v[92:95], v[168:171], v[192:195], v[92:95]
	v_mfma_f32_16x16x32_bf16 v[88:91], v[176:179], v[192:195], v[88:91]
	v_mfma_f32_16x16x32_bf16 v[76:79], v[168:171], v[200:203], v[76:79]
	v_mfma_f32_16x16x32_bf16 v[72:75], v[176:179], v[200:203], v[72:75]
	v_mfma_f32_16x16x32_bf16 v[68:71], v[168:171], v[208:211], v[68:71]
	v_mfma_f32_16x16x32_bf16 v[64:67], v[176:179], v[208:211], v[64:67]
	v_mfma_f32_16x16x32_bf16 v[108:111], v[172:175], v[188:191], v[108:111]
	v_mfma_f32_16x16x32_bf16 v[104:107], v[180:183], v[188:191], v[104:107]
	v_mfma_f32_16x16x32_bf16 v[92:95], v[172:175], v[196:199], v[92:95]
	v_mfma_f32_16x16x32_bf16 v[88:91], v[180:183], v[196:199], v[88:91]
	v_mfma_f32_16x16x32_bf16 v[76:79], v[172:175], v[204:207], v[76:79]
	v_mfma_f32_16x16x32_bf16 v[72:75], v[180:183], v[204:207], v[72:75]
	v_mfma_f32_16x16x32_bf16 v[68:71], v[172:175], v[212:215], v[68:71]
	v_mfma_f32_16x16x32_bf16 v[64:67], v[180:183], v[212:215], v[64:67]
	s_setprio 0
	s_barrier
	s_add_i32 s34, s63, s20
	v_lshl_add_u64 v[216:217], s[56:57], 0, v[130:131]
	s_mov_b32 m0, s34
	ds_read_b128 v[184:187], v151 offset:16384
	ds_read_b128 v[188:191], v151 offset:17408
	ds_read_b128 v[192:195], v151 offset:18432
	ds_read_b128 v[196:199], v151 offset:19456
	ds_read_b128 v[200:203], v151 offset:20480
	ds_read_b128 v[204:207], v151 offset:21504
	ds_read_b128 v[208:211], v151 offset:22528
	ds_read_b128 v[212:215], v151 offset:23552
	global_load_lds_dwordx4 v[216:217], off
	s_add_i32 m0, s34, 0x2000
	s_add_u32 s34, s56, 0x40000
	v_lshl_add_u64 v[218:219], s[56:57], 0, v[134:135]
	s_addc_u32 s35, s57, 0
	s_add_i32 s54, s64, s20
	global_load_lds_dwordx4 v[218:219], off
	s_mov_b32 m0, s54
	v_lshl_add_u64 v[222:223], s[58:59], 0, v[132:133]
	global_load_lds_dwordx4 v130, s[34:35]
	s_add_i32 m0, s54, 0x2000
	s_nop 0
	global_load_lds_dwordx4 v134, s[34:35]
	v_lshl_add_u64 v[220:221], s[58:59], 0, v[128:129]
	s_mov_b32 m0, s21
	s_nop 0
	global_load_lds_dwordx4 v[220:221], off
	s_mov_b32 m0, s29
	s_nop 0
	global_load_lds_dwordx4 v[222:223], off
	s_waitcnt vmcnt(8)
	s_waitcnt lgkmcnt(0)
	s_barrier
; #define PG8_STAGE(bufoff, gbase, voff) do { _Pragma("unroll") for (int _i = 0; _i < 2; ++_i) \
;         __builtin_amdgcn_global_load_lds((const unsigned*)((const char*)(gbase) + (voff)[_i]), (LAS unsigned*)(lds + (bufoff) + ldsw + _i * 8192), 16, 0, 0); } while (0)
; #define PG8_LDA(dst, b, h) do { _Pragma("unroll") for (int m = 0; m < 4; ++m) _Pragma("unroll") for (int k = 0; k < 2; ++k) dst[m][k] = *(const LAS bf16x8*)(lds + PG8_SA(b, h) + aoff + m * 2048 + k * 1024); } while (0)
; #define PG8_LDB(dst, b, h) do { _Pragma("unroll") for (int n = 0; n < 2; ++n) _Pragma("unroll") for (int k = 0; k < 2; ++k) dst[n][k] = *(const LAS bf16x8*)(lds + PG8_SB(b, h) + boff + n * 2048 + k * 1024); } while (0)
; #define PG8_MMA(ai, bj, At, Bt) do { __builtin_amdgcn_s_setprio(1); _Pragma("unroll") for (int m = 0; m < 4; ++m) _Pragma("unroll") for (int n = 0; n < 2; ++n) _Pragma("unroll") for (int k = 0; k < 2; ++k) \
;         acc[ai][bj][m][n] = __builtin_amdgcn_mfma_f32_16x16x32_bf16(Bt[n][k], At[m][k], acc[ai][bj][m][n], 0, 0, 0); __builtin_amdgcn_s_setprio(0); } while (0)
; #define PG8_WAIT_V(n) asm volatile("s_waitcnt vmcnt(" #n ")" ::: "memory")
; #define PG8_WAIT_L(n) asm volatile("s_waitcnt lgkmcnt(" #n ")" ::: "memory")
; #define PG8_BAR __builtin_amdgcn_s_barrier()
; #define PG8_SCHED __builtin_amdgcn_sched_barrier(0)
; template <class Epi, class Sched, bool ALIGN_EPI = false, bool SP2 = false>
; __device__ __forceinline__ void gemm_phase(LAS unsigned char* lds, const Gemm g, const Sched S, const Epi E) {
;     ...
;             PG8_WAIT_V(8); PG8_WAIT_L(0); PG8_BAR; PG8_MMA(1, 0, At, B0); PG8_MMA(1, 1, At, B1); PG8_BAR; PG8_SCHED;
;             PG8_LDB(B0, 1, 0); PG8_LDB(B1, 1, 1); PG8_SCHED; PG8_LDA(At, 1, 0); PG8_STAGE(PG8_SA(0, 1), a2 + hstepA, voffA);
;             PG8_WAIT_V(8); PG8_WAIT_L(0); PG8_BAR; PG8_MMA(0, 0, At, B0); PG8_MMA(0, 1, At, B1); PG8_BAR; PG8_SCHED;
	s_setprio 1
	s_waitcnt lgkmcnt(0)
	v_mfma_f32_16x16x32_bf16 v[60:63], v[152:155], v[184:187], v[60:63]
	v_mfma_f32_16x16x32_bf16 v[56:59], v[160:163], v[184:187], v[56:59]
	v_mfma_f32_16x16x32_bf16 v[52:55], v[152:155], v[192:195], v[52:55]
	v_mfma_f32_16x16x32_bf16 v[48:51], v[160:163], v[192:195], v[48:51]
	v_mfma_f32_16x16x32_bf16 v[36:39], v[152:155], v[200:203], v[36:39]
	v_mfma_f32_16x16x32_bf16 v[32:35], v[160:163], v[200:203], v[32:35]
	v_mfma_f32_16x16x32_bf16 v[20:23], v[152:155], v[208:211], v[20:23]
	v_mfma_f32_16x16x32_bf16 v[16:19], v[160:163], v[208:211], v[16:19]
	v_mfma_f32_16x16x32_bf16 v[60:63], v[156:159], v[188:191], v[60:63]
	v_mfma_f32_16x16x32_bf16 v[56:59], v[164:167], v[188:191], v[56:59]
	v_mfma_f32_16x16x32_bf16 v[52:55], v[156:159], v[196:199], v[52:55]
	v_mfma_f32_16x16x32_bf16 v[48:51], v[164:167], v[196:199], v[48:51]
	v_mfma_f32_16x16x32_bf16 v[36:39], v[156:159], v[204:207], v[36:39]
	v_mfma_f32_16x16x32_bf16 v[32:35], v[164:167], v[204:207], v[32:35]
	v_mfma_f32_16x16x32_bf16 v[20:23], v[156:159], v[212:215], v[20:23]
	v_mfma_f32_16x16x32_bf16 v[16:19], v[164:167], v[212:215], v[16:19]
	s_setprio 0
	s_setprio 1
	v_mfma_f32_16x16x32_bf16 v[44:47], v[168:171], v[184:187], v[44:47]
	v_mfma_f32_16x16x32_bf16 v[40:43], v[176:179], v[184:187], v[40:43]
	v_mfma_f32_16x16x32_bf16 v[28:31], v[168:171], v[192:195], v[28:31]
	v_mfma_f32_16x16x32_bf16 v[24:27], v[176:179], v[192:195], v[24:27]
	v_mfma_f32_16x16x32_bf16 v[12:15], v[168:171], v[200:203], v[12:15]
	v_mfma_f32_16x16x32_bf16 v[8:11], v[176:179], v[200:203], v[8:11]
	v_mfma_f32_16x16x32_bf16 v[4:7], v[168:171], v[208:211], v[4:7]
	v_mfma_f32_16x16x32_bf16 v[0:3], v[176:179], v[208:211], v[0:3]
	v_mfma_f32_16x16x32_bf16 v[44:47], v[172:175], v[188:191], v[44:47]
	v_mfma_f32_16x16x32_bf16 v[40:43], v[180:183], v[188:191], v[40:43]
	v_mfma_f32_16x16x32_bf16 v[28:31], v[172:175], v[196:199], v[28:31]
	v_mfma_f32_16x16x32_bf16 v[24:27], v[180:183], v[196:199], v[24:27]
	v_mfma_f32_16x16x32_bf16 v[12:15], v[172:175], v[204:207], v[12:15]
	v_mfma_f32_16x16x32_bf16 v[8:11], v[180:183], v[204:207], v[8:11]
	v_mfma_f32_16x16x32_bf16 v[4:7], v[172:175], v[212:215], v[4:7]
	v_mfma_f32_16x16x32_bf16 v[0:3], v[180:183], v[212:215], v[0:3]
	s_setprio 0
	s_barrier
	s_add_i32 s54, 0, 0x18000
	v_add_u32_e32 v136, s54, v147
	s_add_i32 s55, 0, 0x1c000
	ds_read_b128 v[152:155], v136
	ds_read_b128 v[156:159], v136 offset:1024
	ds_read_b128 v[160:163], v136 offset:2048
	ds_read_b128 v[164:167], v136 offset:3072
	v_add_u32_e32 v136, s55, v147
	ds_read_b128 v[168:171], v136
	ds_read_b128 v[172:175], v136 offset:1024
	ds_read_b128 v[176:179], v136 offset:2048
	ds_read_b128 v[180:183], v136 offset:3072
	s_add_u32 s34, s58, 0x130000
	s_addc_u32 s35, s59, 0
	s_mov_b32 m0, s30
	ds_read_b128 v[184:187], v151 offset:32768
	ds_read_b128 v[188:191], v151 offset:33792
	ds_read_b128 v[192:195], v151 offset:34816
	ds_read_b128 v[196:199], v151 offset:35840
	ds_read_b128 v[200:203], v151 offset:36864
	ds_read_b128 v[204:207], v151 offset:37888
	ds_read_b128 v[208:211], v151 offset:38912
	ds_read_b128 v[212:215], v151 offset:39936
	global_load_lds_dwordx4 v128, s[34:35]
	s_mov_b32 m0, s31
	s_nop 0
	global_load_lds_dwordx4 v132, s[34:35]
	s_waitcnt vmcnt(8)
	s_waitcnt lgkmcnt(0)
	s_barrier
	s_setprio 1
	s_waitcnt lgkmcnt(0)
	v_mfma_f32_16x16x32_bf16 v[124:127], v[152:155], v[184:187], v[124:127]
	v_mfma_f32_16x16x32_bf16 v[120:123], v[160:163], v[184:187], v[120:123]
	v_mfma_f32_16x16x32_bf16 v[116:119], v[152:155], v[192:195], v[116:119]
	v_mfma_f32_16x16x32_bf16 v[112:115], v[160:163], v[192:195], v[112:115]
	v_mfma_f32_16x16x32_bf16 v[100:103], v[152:155], v[200:203], v[100:103]
	v_mfma_f32_16x16x32_bf16 v[96:99], v[160:163], v[200:203], v[96:99]
	v_mfma_f32_16x16x32_bf16 v[84:87], v[152:155], v[208:211], v[84:87]
	v_mfma_f32_16x16x32_bf16 v[80:83], v[160:163], v[208:211], v[80:83]
	v_mfma_f32_16x16x32_bf16 v[124:127], v[156:159], v[188:191], v[124:127]
	v_mfma_f32_16x16x32_bf16 v[120:123], v[164:167], v[188:191], v[120:123]
	v_mfma_f32_16x16x32_bf16 v[116:119], v[156:159], v[196:199], v[116:119]
	v_mfma_f32_16x16x32_bf16 v[112:115], v[164:167], v[196:199], v[112:115]
	v_mfma_f32_16x16x32_bf16 v[100:103], v[156:159], v[204:207], v[100:103]
	v_mfma_f32_16x16x32_bf16 v[96:99], v[164:167], v[204:207], v[96:99]
	v_mfma_f32_16x16x32_bf16 v[84:87], v[156:159], v[212:215], v[84:87]
	v_mfma_f32_16x16x32_bf16 v[80:83], v[164:167], v[212:215], v[80:83]
	s_setprio 0
	s_setprio 1
	v_mfma_f32_16x16x32_bf16 v[108:111], v[168:171], v[184:187], v[108:111]
	v_mfma_f32_16x16x32_bf16 v[104:107], v[176:179], v[184:187], v[104:107]
	v_mfma_f32_16x16x32_bf16 v[92:95], v[168:171], v[192:195], v[92:95]
	v_mfma_f32_16x16x32_bf16 v[88:91], v[176:179], v[192:195], v[88:91]
	v_mfma_f32_16x16x32_bf16 v[76:79], v[168:171], v[200:203], v[76:79]
	v_mfma_f32_16x16x32_bf16 v[72:75], v[176:179], v[200:203], v[72:75]
	v_mfma_f32_16x16x32_bf16 v[68:71], v[168:171], v[208:211], v[68:71]
	v_mfma_f32_16x16x32_bf16 v[64:67], v[176:179], v[208:211], v[64:67]
	v_mfma_f32_16x16x32_bf16 v[108:111], v[172:175], v[188:191], v[108:111]
	v_mfma_f32_16x16x32_bf16 v[104:107], v[180:183], v[188:191], v[104:107]
	v_mfma_f32_16x16x32_bf16 v[92:95], v[172:175], v[196:199], v[92:95]
	v_mfma_f32_16x16x32_bf16 v[88:91], v[180:183], v[196:199], v[88:91]
	v_mfma_f32_16x16x32_bf16 v[76:79], v[172:175], v[204:207], v[76:79]
	v_mfma_f32_16x16x32_bf16 v[72:75], v[180:183], v[204:207], v[72:75]
	v_mfma_f32_16x16x32_bf16 v[68:71], v[172:175], v[212:215], v[68:71]
	v_mfma_f32_16x16x32_bf16 v[64:67], v[180:183], v[212:215], v[64:67]
	s_setprio 0
	s_barrier
; #define PG8_STAGE(bufoff, gbase, voff) do { _Pragma("unroll") for (int _i = 0; _i < 2; ++_i) \
;         __builtin_amdgcn_global_load_lds((const unsigned*)((const char*)(gbase) + (voff)[_i]), (LAS unsigned*)(lds + (bufoff) + ldsw + _i * 8192), 16, 0, 0); } while (0)
; #define PG8_LDA(dst, b, h) do { _Pragma("unroll") for (int m = 0; m < 4; ++m) _Pragma("unroll") for (int k = 0; k < 2; ++k) dst[m][k] = *(const LAS bf16x8*)(lds + PG8_SA(b, h) + aoff + m * 2048 + k * 1024); } while (0)
; #define PG8_MMA(ai, bj, At, Bt) do { __builtin_amdgcn_s_setprio(1); _Pragma("unroll") for (int m = 0; m < 4; ++m) _Pragma("unroll") for (int n = 0; n < 2; ++n) _Pragma("unroll") for (int k = 0; k < 2; ++k) \
;         acc[ai][bj][m][n] = __builtin_amdgcn_mfma_f32_16x16x32_bf16(Bt[n][k], At[m][k], acc[ai][bj][m][n], 0, 0, 0); __builtin_amdgcn_s_setprio(0); } while (0)
; #define PG8_WAIT_V(n) asm volatile("s_waitcnt vmcnt(" #n ")" ::: "memory")
; #define PG8_WAIT_L(n) asm volatile("s_waitcnt lgkmcnt(" #n ")" ::: "memory")
; #define PG8_BAR __builtin_amdgcn_s_barrier()
; #define PG8_SCHED __builtin_amdgcn_sched_barrier(0)
; template <class Epi, class Sched, bool ALIGN_EPI = false, bool SP2 = false>
; __device__ __forceinline__ void gemm_phase(LAS unsigned char* lds, const Gemm g, const Sched S, const Epi E) {
;     ...
;         for (int t = 0; t < nt; t += 2) {
;     ...
;             PG8_LDA(At, 1, 1); PG8_STAGE(PG8_SB(1, 0), b3, voffB); PG8_STAGE(PG8_SB(1, 1), b3 + hstepB, voffB); PG8_STAGE(PG8_SA(1, 0), a3, voffA);
;             PG8_WAIT_V(8); PG8_WAIT_L(0); PG8_BAR; PG8_MMA(1, 0, At, B0); PG8_MMA(1, 1, At, B1); PG8_BAR; PG8_SCHED;
	s_add_i32 s34, s54, s20
	v_lshl_add_u64 v[216:217], v[216:217], 0, s[14:15]
	s_mov_b32 m0, s34
	ds_read_b128 v[184:187], v151 offset:49152
	ds_read_b128 v[188:191], v151 offset:50176
	ds_read_b128 v[192:195], v151 offset:51200
	ds_read_b128 v[196:199], v151 offset:52224
	ds_read_b128 v[200:203], v151 offset:53248
	ds_read_b128 v[204:207], v151 offset:54272
	ds_read_b128 v[208:211], v151 offset:55296
	ds_read_b128 v[212:215], v151 offset:56320
	global_load_lds_dwordx4 v[216:217], off
	s_add_i32 m0, s34, 0x2000
	s_add_u32 s34, s56, 0x40080
	v_lshl_add_u64 v[216:217], v[218:219], 0, s[14:15]
	s_addc_u32 s35, s57, 0
	s_add_i32 s54, s55, s20
	global_load_lds_dwordx4 v[216:217], off
	s_mov_b32 m0, s54
	s_nop 0
	global_load_lds_dwordx4 v130, s[34:35]
	s_add_i32 m0, s54, 0x2000
	s_nop 0
	global_load_lds_dwordx4 v134, s[34:35]
	v_lshl_add_u64 v[216:217], v[220:221], 0, s[14:15]
	s_mov_b32 m0, s45
	s_nop 0
	global_load_lds_dwordx4 v[216:217], off
	v_lshl_add_u64 v[216:217], v[222:223], 0, s[14:15]
	s_mov_b32 m0, s60
	s_nop 0
	global_load_lds_dwordx4 v[216:217], off
	s_waitcnt vmcnt(8)
	s_waitcnt lgkmcnt(0)
	s_barrier
	s_setprio 1
	s_waitcnt lgkmcnt(0)
	v_mfma_f32_16x16x32_bf16 v[60:63], v[152:155], v[184:187], v[60:63]
	v_mfma_f32_16x16x32_bf16 v[56:59], v[160:163], v[184:187], v[56:59]
	v_mfma_f32_16x16x32_bf16 v[52:55], v[152:155], v[192:195], v[52:55]
	v_mfma_f32_16x16x32_bf16 v[48:51], v[160:163], v[192:195], v[48:51]
	v_mfma_f32_16x16x32_bf16 v[36:39], v[152:155], v[200:203], v[36:39]
	v_mfma_f32_16x16x32_bf16 v[32:35], v[160:163], v[200:203], v[32:35]
	v_mfma_f32_16x16x32_bf16 v[20:23], v[152:155], v[208:211], v[20:23]
	v_mfma_f32_16x16x32_bf16 v[16:19], v[160:163], v[208:211], v[16:19]
	v_mfma_f32_16x16x32_bf16 v[60:63], v[156:159], v[188:191], v[60:63]
	v_mfma_f32_16x16x32_bf16 v[56:59], v[164:167], v[188:191], v[56:59]
	v_mfma_f32_16x16x32_bf16 v[52:55], v[156:159], v[196:199], v[52:55]
	v_mfma_f32_16x16x32_bf16 v[48:51], v[164:167], v[196:199], v[48:51]
	v_mfma_f32_16x16x32_bf16 v[36:39], v[156:159], v[204:207], v[36:39]
	v_mfma_f32_16x16x32_bf16 v[32:35], v[164:167], v[204:207], v[32:35]
	v_mfma_f32_16x16x32_bf16 v[20:23], v[156:159], v[212:215], v[20:23]
	v_mfma_f32_16x16x32_bf16 v[16:19], v[164:167], v[212:215], v[16:19]
	s_setprio 0
	s_setprio 1
	v_mfma_f32_16x16x32_bf16 v[44:47], v[168:171], v[184:187], v[44:47]
	v_mfma_f32_16x16x32_bf16 v[40:43], v[176:179], v[184:187], v[40:43]
	v_mfma_f32_16x16x32_bf16 v[28:31], v[168:171], v[192:195], v[28:31]
	v_mfma_f32_16x16x32_bf16 v[24:27], v[176:179], v[192:195], v[24:27]
	v_mfma_f32_16x16x32_bf16 v[12:15], v[168:171], v[200:203], v[12:15]
	v_mfma_f32_16x16x32_bf16 v[8:11], v[176:179], v[200:203], v[8:11]
	v_mfma_f32_16x16x32_bf16 v[4:7], v[168:171], v[208:211], v[4:7]
	v_mfma_f32_16x16x32_bf16 v[0:3], v[176:179], v[208:211], v[0:3]
	v_mfma_f32_16x16x32_bf16 v[44:47], v[172:175], v[188:191], v[44:47]
	v_mfma_f32_16x16x32_bf16 v[40:43], v[180:183], v[188:191], v[40:43]
	v_mfma_f32_16x16x32_bf16 v[28:31], v[172:175], v[196:199], v[28:31]
	v_mfma_f32_16x16x32_bf16 v[24:27], v[180:183], v[196:199], v[24:27]
	v_mfma_f32_16x16x32_bf16 v[12:15], v[172:175], v[204:207], v[12:15]
	v_mfma_f32_16x16x32_bf16 v[8:11], v[180:183], v[204:207], v[8:11]
	v_mfma_f32_16x16x32_bf16 v[4:7], v[172:175], v[212:215], v[4:7]
	v_mfma_f32_16x16x32_bf16 v[0:3], v[180:183], v[212:215], v[0:3]
	s_setprio 0
	s_add_i32 s71, s71, 2
	s_add_u32 s69, s69, 0x100
	s_addc_u32 s70, s70, 0
	s_cmp_gt_u32 s71, 13
	s_mov_b64 s[54:55], s[10:11]
	s_barrier
	s_cbranch_scc0 .LBB0_1612
	s_and_b64 vcc, exec, s[16:17]
	s_cbranch_vccz .LBB0_1615
	s_barrier

; #define PG8_STAGE(bufoff, gbase, voff) do { _Pragma("unroll") for (int _i = 0; _i < 2; ++_i) \
;         __builtin_amdgcn_global_load_lds((const unsigned*)((const char*)(gbase) + (voff)[_i]), (LAS unsigned*)(lds + (bufoff) + ldsw + _i * 8192), 16, 0, 0); } while (0)
; #define PG8_LDA(dst, b, h) do { _Pragma("unroll") for (int m = 0; m < 4; ++m) _Pragma("unroll") for (int k = 0; k < 2; ++k) dst[m][k] = *(const LAS bf16x8*)(lds + PG8_SA(b, h) + aoff + m * 2048 + k * 1024); } while (0)
; #define PG8_LDB(dst, b, h) do { _Pragma("unroll") for (int n = 0; n < 2; ++n) _Pragma("unroll") for (int k = 0; k < 2; ++k) dst[n][k] = *(const LAS bf16x8*)(lds + PG8_SB(b, h) + boff + n * 2048 + k * 1024); } while (0)
; #define PG8_MMA(ai, bj, At, Bt) do { __builtin_amdgcn_s_setprio(1); _Pragma("unroll") for (int m = 0; m < 4; ++m) _Pragma("unroll") for (int n = 0; n < 2; ++n) _Pragma("unroll") for (int k = 0; k < 2; ++k) \
;         acc[ai][bj][m][n] = __builtin_amdgcn_mfma_f32_16x16x32_bf16(Bt[n][k], At[m][k], acc[ai][bj][m][n], 0, 0, 0); __builtin_amdgcn_s_setprio(0); } while (0)
; #define PG8_WAIT_V(n) asm volatile("s_waitcnt vmcnt(" #n ")" ::: "memory")
; #define PG8_WAIT_L(n) asm volatile("s_waitcnt lgkmcnt(" #n ")" ::: "memory")
; #define PG8_BAR __builtin_amdgcn_s_barrier()
; #define PG8_SCHED __builtin_amdgcn_sched_barrier(0)
; template <class Epi, class Sched, bool ALIGN_EPI = false, bool SP2 = false>
; __device__ __forceinline__ void gemm_phase(LAS unsigned char* lds, const Gemm g, const Sched S, const Epi E) {
;     ...
;             const char* a1 = cA + (size_t)(t + 1) * kstep;
;             const char* a2 = last ? nA : cA + (size_t)(t + 2) * kstep; const char* b2 = last ? nB : cB + (size_t)(t + 2) * kstep;
;             const char* a3 = a2 + kstep; const char* b3 = b2 + kstep;
;             if (last && has_next) S.a_ready(nxt);
;             if constexpr (SP2) {
;             PG8_LDB(B0, 0, 0); PG8_LDB(B1, 0, 1); PG8_SCHED; PG8_LDA(At, 0, 0); PG8_STAGE(PG8_SA(1, 1), a1 + hstepA, voffA);
;             PG8_WAIT_V(8); PG8_WAIT_L(0); PG8_BAR; PG8_MMA(0, 0, At, B0); PG8_MMA(0, 1, At, B1); PG8_BAR; PG8_SCHED;
;             PG8_LDA(At, 0, 1); PG8_STAGE(PG8_SB(0, 0), b2, voffB); PG8_STAGE(PG8_SB(0, 1), b2 + hstepB, voffB); PG8_STAGE(PG8_SA(0, 0), a2, voffA);
;             PG8_WAIT_V(8); PG8_WAIT_L(0); PG8_BAR; PG8_MMA(1, 0, At, B0); PG8_MMA(1, 1, At, B1); PG8_BAR; PG8_SCHED;
.LBB0_1688:
	ds_read_b128 v[128:131], v167
	ds_read_b128 v[132:135], v167 offset:1024
	ds_read_b128 v[152:155], v167 offset:2048
	ds_read_b128 v[156:159], v167 offset:3072
	ds_read_b128 v[160:163], v168
	ds_read_b128 v[172:175], v168 offset:1024
	ds_read_b128 v[176:179], v168 offset:2048
	ds_read_b128 v[180:183], v168 offset:3072
	s_add_u32 s34, s52, 0xfff80080
	s_addc_u32 s35, s53, -1
	s_cmp_eq_u32 s66, 12
	s_cselect_b32 s57, s19, s35
	s_cselect_b32 s56, s62, s34
	s_cselect_b32 s55, s17, s65
	s_cselect_b32 s54, s63, s64
	s_add_i32 m0, s5, 0xc000
	ds_read_b128 v[184:187], v169
	ds_read_b128 v[188:191], v169 offset:1024
	ds_read_b128 v[192:195], v169 offset:2048
	ds_read_b128 v[196:199], v169 offset:3072
	ds_read_b128 v[200:203], v169 offset:4096
	ds_read_b128 v[204:207], v169 offset:5120
	ds_read_b128 v[208:211], v169 offset:6144
	ds_read_b128 v[212:215], v169 offset:7168
	global_load_lds_dwordx4 v144, s[52:53]
	s_add_i32 m0, s5, 0xe000
	s_nop 0
	global_load_lds_dwordx4 v146, s[52:53]
	s_waitcnt vmcnt(8)
	s_waitcnt lgkmcnt(0)
	s_barrier
	s_setprio 1
	s_waitcnt lgkmcnt(0)
	v_mfma_f32_16x16x32_bf16 v[124:127], v[128:131], v[184:187], v[124:127]
	v_mfma_f32_16x16x32_bf16 v[120:123], v[152:155], v[184:187], v[120:123]
	v_mfma_f32_16x16x32_bf16 v[108:111], v[128:131], v[192:195], v[108:111]
	v_mfma_f32_16x16x32_bf16 v[104:107], v[152:155], v[192:195], v[104:107]
	v_mfma_f32_16x16x32_bf16 v[92:95], v[128:131], v[200:203], v[92:95]
	v_mfma_f32_16x16x32_bf16 v[88:91], v[152:155], v[200:203], v[88:91]
	v_mfma_f32_16x16x32_bf16 v[76:79], v[128:131], v[208:211], v[76:79]
	v_mfma_f32_16x16x32_bf16 v[72:75], v[152:155], v[208:211], v[72:75]
	v_mfma_f32_16x16x32_bf16 v[124:127], v[132:135], v[188:191], v[124:127]
	v_mfma_f32_16x16x32_bf16 v[120:123], v[156:159], v[188:191], v[120:123]
	v_mfma_f32_16x16x32_bf16 v[108:111], v[132:135], v[196:199], v[108:111]
	v_mfma_f32_16x16x32_bf16 v[104:107], v[156:159], v[196:199], v[104:107]
	v_mfma_f32_16x16x32_bf16 v[92:95], v[132:135], v[204:207], v[92:95]
	v_mfma_f32_16x16x32_bf16 v[88:91], v[156:159], v[204:207], v[88:91]
	v_mfma_f32_16x16x32_bf16 v[76:79], v[132:135], v[212:215], v[76:79]
	v_mfma_f32_16x16x32_bf16 v[72:75], v[156:159], v[212:215], v[72:75]
	s_setprio 0
	s_setprio 1
	v_mfma_f32_16x16x32_bf16 v[116:119], v[160:163], v[184:187], v[116:119]
	v_mfma_f32_16x16x32_bf16 v[112:115], v[176:179], v[184:187], v[112:115]
	v_mfma_f32_16x16x32_bf16 v[100:103], v[160:163], v[192:195], v[100:103]
	v_mfma_f32_16x16x32_bf16 v[96:99], v[176:179], v[192:195], v[96:99]
	v_mfma_f32_16x16x32_bf16 v[84:87], v[160:163], v[200:203], v[84:87]
	v_mfma_f32_16x16x32_bf16 v[80:83], v[176:179], v[200:203], v[80:83]
	v_mfma_f32_16x16x32_bf16 v[68:71], v[160:163], v[208:211], v[68:71]
	v_mfma_f32_16x16x32_bf16 v[64:67], v[176:179], v[208:211], v[64:67]
	v_mfma_f32_16x16x32_bf16 v[116:119], v[172:175], v[188:191], v[116:119]
	v_mfma_f32_16x16x32_bf16 v[112:115], v[180:183], v[188:191], v[112:115]
	v_mfma_f32_16x16x32_bf16 v[100:103], v[172:175], v[196:199], v[100:103]
	v_mfma_f32_16x16x32_bf16 v[96:99], v[180:183], v[196:199], v[96:99]
	v_mfma_f32_16x16x32_bf16 v[84:87], v[172:175], v[204:207], v[84:87]
	v_mfma_f32_16x16x32_bf16 v[80:83], v[180:183], v[204:207], v[80:83]
	v_mfma_f32_16x16x32_bf16 v[68:71], v[172:175], v[212:215], v[68:71]
	v_mfma_f32_16x16x32_bf16 v[64:67], v[180:183], v[212:215], v[64:67]
	s_setprio 0
	s_barrier
	s_add_i32 s34, s58, s4
	v_lshl_add_u64 v[216:217], s[54:55], 0, v[138:139]
	s_mov_b32 m0, s34
	ds_read_b128 v[184:187], v169 offset:16384
	ds_read_b128 v[188:191], v169 offset:17408
	ds_read_b128 v[192:195], v169 offset:18432
	ds_read_b128 v[196:199], v169 offset:19456
	ds_read_b128 v[200:203], v169 offset:20480
	ds_read_b128 v[204:207], v169 offset:21504
	ds_read_b128 v[208:211], v169 offset:22528
	ds_read_b128 v[212:215], v169 offset:23552
	global_load_lds_dwordx4 v[216:217], off
	s_add_i32 m0, s34, 0x2000
	s_add_u32 s34, s54, 0x40000
	v_lshl_add_u64 v[218:219], s[54:55], 0, v[142:143]
	s_addc_u32 s35, s55, 0
	s_add_i32 s67, s59, s4
	global_load_lds_dwordx4 v[218:219], off
	s_mov_b32 m0, s67
	v_lshl_add_u64 v[222:223], s[56:57], 0, v[140:141]
	global_load_lds_dwordx4 v138, s[34:35]
	s_add_i32 m0, s67, 0x2000
	s_nop 0
	global_load_lds_dwordx4 v142, s[34:35]
	v_lshl_add_u64 v[220:221], s[56:57], 0, v[136:137]
	s_mov_b32 m0, s5
	s_nop 0
	global_load_lds_dwordx4 v[220:221], off
	s_mov_b32 m0, s20
	s_nop 0
	global_load_lds_dwordx4 v[222:223], off
	s_waitcnt vmcnt(8)
	s_waitcnt lgkmcnt(0)
	s_barrier
; #define PG8_STAGE(bufoff, gbase, voff) do { _Pragma("unroll") for (int _i = 0; _i < 2; ++_i) \
;         __builtin_amdgcn_global_load_lds((const unsigned*)((const char*)(gbase) + (voff)[_i]), (LAS unsigned*)(lds + (bufoff) + ldsw + _i * 8192), 16, 0, 0); } while (0)
; #define PG8_LDA(dst, b, h) do { _Pragma("unroll") for (int m = 0; m < 4; ++m) _Pragma("unroll") for (int k = 0; k < 2; ++k) dst[m][k] = *(const LAS bf16x8*)(lds + PG8_SA(b, h) + aoff + m * 2048 + k * 1024); } while (0)
; #define PG8_LDB(dst, b, h) do { _Pragma("unroll") for (int n = 0; n < 2; ++n) _Pragma("unroll") for (int k = 0; k < 2; ++k) dst[n][k] = *(const LAS bf16x8*)(lds + PG8_SB(b, h) + boff + n * 2048 + k * 1024); } while (0)
; #define PG8_MMA(ai, bj, At, Bt) do { __builtin_amdgcn_s_setprio(1); _Pragma("unroll") for (int m = 0; m < 4; ++m) _Pragma("unroll") for (int n = 0; n < 2; ++n) _Pragma("unroll") for (int k = 0; k < 2; ++k) \
;         acc[ai][bj][m][n] = __builtin_amdgcn_mfma_f32_16x16x32_bf16(Bt[n][k], At[m][k], acc[ai][bj][m][n], 0, 0, 0); __builtin_amdgcn_s_setprio(0); } while (0)
; #define PG8_WAIT_V(n) asm volatile("s_waitcnt vmcnt(" #n ")" ::: "memory")
; #define PG8_WAIT_L(n) asm volatile("s_waitcnt lgkmcnt(" #n ")" ::: "memory")
; #define PG8_BAR __builtin_amdgcn_s_barrier()
; #define PG8_SCHED __builtin_amdgcn_sched_barrier(0)
; template <class Epi, class Sched, bool ALIGN_EPI = false, bool SP2 = false>
; __device__ __forceinline__ void gemm_phase(LAS unsigned char* lds, const Gemm g, const Sched S, const Epi E) {
;     ...
;             PG8_WAIT_V(8); PG8_WAIT_L(0); PG8_BAR; PG8_MMA(1, 0, At, B0); PG8_MMA(1, 1, At, B1); PG8_BAR; PG8_SCHED;
;             PG8_LDB(B0, 1, 0); PG8_LDB(B1, 1, 1); PG8_SCHED; PG8_LDA(At, 1, 0); PG8_STAGE(PG8_SA(0, 1), a2 + hstepA, voffA);
;             PG8_WAIT_V(8); PG8_WAIT_L(0); PG8_BAR; PG8_MMA(0, 0, At, B0); PG8_MMA(0, 1, At, B1); PG8_BAR; PG8_SCHED;
	s_setprio 1
	s_waitcnt lgkmcnt(0)
	v_mfma_f32_16x16x32_bf16 v[60:63], v[128:131], v[184:187], v[60:63]
	v_mfma_f32_16x16x32_bf16 v[56:59], v[152:155], v[184:187], v[56:59]
	v_mfma_f32_16x16x32_bf16 v[44:47], v[128:131], v[192:195], v[44:47]
	v_mfma_f32_16x16x32_bf16 v[40:43], v[152:155], v[192:195], v[40:43]
	v_mfma_f32_16x16x32_bf16 v[28:31], v[128:131], v[200:203], v[28:31]
	v_mfma_f32_16x16x32_bf16 v[24:27], v[152:155], v[200:203], v[24:27]
	v_mfma_f32_16x16x32_bf16 v[12:15], v[128:131], v[208:211], v[12:15]
	v_mfma_f32_16x16x32_bf16 v[8:11], v[152:155], v[208:211], v[8:11]
	v_mfma_f32_16x16x32_bf16 v[60:63], v[132:135], v[188:191], v[60:63]
	v_mfma_f32_16x16x32_bf16 v[56:59], v[156:159], v[188:191], v[56:59]
	v_mfma_f32_16x16x32_bf16 v[44:47], v[132:135], v[196:199], v[44:47]
	v_mfma_f32_16x16x32_bf16 v[40:43], v[156:159], v[196:199], v[40:43]
	v_mfma_f32_16x16x32_bf16 v[28:31], v[132:135], v[204:207], v[28:31]
	v_mfma_f32_16x16x32_bf16 v[24:27], v[156:159], v[204:207], v[24:27]
	v_mfma_f32_16x16x32_bf16 v[12:15], v[132:135], v[212:215], v[12:15]
	v_mfma_f32_16x16x32_bf16 v[8:11], v[156:159], v[212:215], v[8:11]
	s_setprio 0
	s_setprio 1
	v_mfma_f32_16x16x32_bf16 v[52:55], v[160:163], v[184:187], v[52:55]
	v_mfma_f32_16x16x32_bf16 v[48:51], v[176:179], v[184:187], v[48:51]
	v_mfma_f32_16x16x32_bf16 v[36:39], v[160:163], v[192:195], v[36:39]
	v_mfma_f32_16x16x32_bf16 v[32:35], v[176:179], v[192:195], v[32:35]
	v_mfma_f32_16x16x32_bf16 v[20:23], v[160:163], v[200:203], v[20:23]
	v_mfma_f32_16x16x32_bf16 v[16:19], v[176:179], v[200:203], v[16:19]
	v_mfma_f32_16x16x32_bf16 v[4:7], v[160:163], v[208:211], v[4:7]
	v_mfma_f32_16x16x32_bf16 v[0:3], v[176:179], v[208:211], v[0:3]
	v_mfma_f32_16x16x32_bf16 v[52:55], v[172:175], v[188:191], v[52:55]
	v_mfma_f32_16x16x32_bf16 v[48:51], v[180:183], v[188:191], v[48:51]
	v_mfma_f32_16x16x32_bf16 v[36:39], v[172:175], v[196:199], v[36:39]
	v_mfma_f32_16x16x32_bf16 v[32:35], v[180:183], v[196:199], v[32:35]
	v_mfma_f32_16x16x32_bf16 v[20:23], v[172:175], v[204:207], v[20:23]
	v_mfma_f32_16x16x32_bf16 v[16:19], v[180:183], v[204:207], v[16:19]
	v_mfma_f32_16x16x32_bf16 v[4:7], v[172:175], v[212:215], v[4:7]
	v_mfma_f32_16x16x32_bf16 v[0:3], v[180:183], v[212:215], v[0:3]
	s_setprio 0
	s_barrier
	s_add_i32 s67, 0, 0x18000
	s_add_i32 s68, 0, 0x1c000
	v_add_u32_e32 v156, s67, v165
	v_add_u32_e32 v171, s68, v165
	ds_read_b128 v[128:131], v156
	ds_read_b128 v[132:135], v156 offset:1024
	ds_read_b128 v[152:155], v156 offset:2048
	ds_read_b128 v[156:159], v156 offset:3072
	ds_read_b128 v[160:163], v171
	ds_read_b128 v[172:175], v171 offset:1024
	ds_read_b128 v[176:179], v171 offset:2048
	ds_read_b128 v[180:183], v171 offset:3072
	s_add_u32 s34, s56, 0x80000
	s_addc_u32 s35, s57, 0
	s_mov_b32 m0, s21
	ds_read_b128 v[184:187], v169 offset:32768
	ds_read_b128 v[188:191], v169 offset:33792
	ds_read_b128 v[192:195], v169 offset:34816
	ds_read_b128 v[196:199], v169 offset:35840
	ds_read_b128 v[200:203], v169 offset:36864
	ds_read_b128 v[204:207], v169 offset:37888
	ds_read_b128 v[208:211], v169 offset:38912
	ds_read_b128 v[212:215], v169 offset:39936
	global_load_lds_dwordx4 v136, s[34:35]
	s_mov_b32 m0, s29
	s_nop 0
	global_load_lds_dwordx4 v140, s[34:35]
	s_waitcnt vmcnt(8)
	s_waitcnt lgkmcnt(0)
	s_barrier
	s_setprio 1
	s_waitcnt lgkmcnt(0)
	v_mfma_f32_16x16x32_bf16 v[124:127], v[128:131], v[184:187], v[124:127]
	v_mfma_f32_16x16x32_bf16 v[120:123], v[152:155], v[184:187], v[120:123]
	v_mfma_f32_16x16x32_bf16 v[108:111], v[128:131], v[192:195], v[108:111]
	v_mfma_f32_16x16x32_bf16 v[104:107], v[152:155], v[192:195], v[104:107]
	v_mfma_f32_16x16x32_bf16 v[92:95], v[128:131], v[200:203], v[92:95]
	v_mfma_f32_16x16x32_bf16 v[88:91], v[152:155], v[200:203], v[88:91]
	v_mfma_f32_16x16x32_bf16 v[76:79], v[128:131], v[208:211], v[76:79]
	v_mfma_f32_16x16x32_bf16 v[72:75], v[152:155], v[208:211], v[72:75]
	v_mfma_f32_16x16x32_bf16 v[124:127], v[132:135], v[188:191], v[124:127]
	v_mfma_f32_16x16x32_bf16 v[120:123], v[156:159], v[188:191], v[120:123]
	v_mfma_f32_16x16x32_bf16 v[108:111], v[132:135], v[196:199], v[108:111]
	v_mfma_f32_16x16x32_bf16 v[104:107], v[156:159], v[196:199], v[104:107]
	v_mfma_f32_16x16x32_bf16 v[92:95], v[132:135], v[204:207], v[92:95]
	v_mfma_f32_16x16x32_bf16 v[88:91], v[156:159], v[204:207], v[88:91]
	v_mfma_f32_16x16x32_bf16 v[76:79], v[132:135], v[212:215], v[76:79]
	v_mfma_f32_16x16x32_bf16 v[72:75], v[156:159], v[212:215], v[72:75]
	s_setprio 0
	s_setprio 1
	v_mfma_f32_16x16x32_bf16 v[116:119], v[160:163], v[184:187], v[116:119]
	v_mfma_f32_16x16x32_bf16 v[112:115], v[176:179], v[184:187], v[112:115]
	v_mfma_f32_16x16x32_bf16 v[100:103], v[160:163], v[192:195], v[100:103]
	v_mfma_f32_16x16x32_bf16 v[96:99], v[176:179], v[192:195], v[96:99]
	v_mfma_f32_16x16x32_bf16 v[84:87], v[160:163], v[200:203], v[84:87]
	v_mfma_f32_16x16x32_bf16 v[80:83], v[176:179], v[200:203], v[80:83]
	v_mfma_f32_16x16x32_bf16 v[68:71], v[160:163], v[208:211], v[68:71]
	v_mfma_f32_16x16x32_bf16 v[64:67], v[176:179], v[208:211], v[64:67]
	v_mfma_f32_16x16x32_bf16 v[116:119], v[172:175], v[188:191], v[116:119]
	v_mfma_f32_16x16x32_bf16 v[112:115], v[180:183], v[188:191], v[112:115]
	v_mfma_f32_16x16x32_bf16 v[100:103], v[172:175], v[196:199], v[100:103]
	v_mfma_f32_16x16x32_bf16 v[96:99], v[180:183], v[196:199], v[96:99]
	v_mfma_f32_16x16x32_bf16 v[84:87], v[172:175], v[204:207], v[84:87]
	v_mfma_f32_16x16x32_bf16 v[80:83], v[180:183], v[204:207], v[80:83]
	v_mfma_f32_16x16x32_bf16 v[68:71], v[172:175], v[212:215], v[68:71]
	v_mfma_f32_16x16x32_bf16 v[64:67], v[180:183], v[212:215], v[64:67]
	s_setprio 0
	s_barrier
; #define PG8_STAGE(bufoff, gbase, voff) do { _Pragma("unroll") for (int _i = 0; _i < 2; ++_i) \
;         __builtin_amdgcn_global_load_lds((const unsigned*)((const char*)(gbase) + (voff)[_i]), (LAS unsigned*)(lds + (bufoff) + ldsw + _i * 8192), 16, 0, 0); } while (0)
; #define PG8_LDA(dst, b, h) do { _Pragma("unroll") for (int m = 0; m < 4; ++m) _Pragma("unroll") for (int k = 0; k < 2; ++k) dst[m][k] = *(const LAS bf16x8*)(lds + PG8_SA(b, h) + aoff + m * 2048 + k * 1024); } while (0)
; #define PG8_MMA(ai, bj, At, Bt) do { __builtin_amdgcn_s_setprio(1); _Pragma("unroll") for (int m = 0; m < 4; ++m) _Pragma("unroll") for (int n = 0; n < 2; ++n) _Pragma("unroll") for (int k = 0; k < 2; ++k) \
;         acc[ai][bj][m][n] = __builtin_amdgcn_mfma_f32_16x16x32_bf16(Bt[n][k], At[m][k], acc[ai][bj][m][n], 0, 0, 0); __builtin_amdgcn_s_setprio(0); } while (0)
; #define PG8_WAIT_V(n) asm volatile("s_waitcnt vmcnt(" #n ")" ::: "memory")
; #define PG8_WAIT_L(n) asm volatile("s_waitcnt lgkmcnt(" #n ")" ::: "memory")
; #define PG8_BAR __builtin_amdgcn_s_barrier()
; #define PG8_SCHED __builtin_amdgcn_sched_barrier(0)
; template <class Epi, class Sched, bool ALIGN_EPI = false, bool SP2 = false>
; __device__ __forceinline__ void gemm_phase(LAS unsigned char* lds, const Gemm g, const Sched S, const Epi E) {
;     ...
;         for (int t = 0; t < nt; t += 2) {
;     ...
;             PG8_LDA(At, 1, 1); PG8_STAGE(PG8_SB(1, 0), b3, voffB); PG8_STAGE(PG8_SB(1, 1), b3 + hstepB, voffB); PG8_STAGE(PG8_SA(1, 0), a3, voffA);
;             PG8_WAIT_V(8); PG8_WAIT_L(0); PG8_BAR; PG8_MMA(1, 0, At, B0); PG8_MMA(1, 1, At, B1); PG8_BAR; PG8_SCHED;
	s_add_i32 s34, s67, s4
	v_lshl_add_u64 v[216:217], v[216:217], 0, s[12:13]
	s_mov_b32 m0, s34
	ds_read_b128 v[184:187], v169 offset:49152
	ds_read_b128 v[188:191], v169 offset:50176
	ds_read_b128 v[192:195], v169 offset:51200
	ds_read_b128 v[196:199], v169 offset:52224
	ds_read_b128 v[200:203], v169 offset:53248
	ds_read_b128 v[204:207], v169 offset:54272
	ds_read_b128 v[208:211], v169 offset:55296
	ds_read_b128 v[212:215], v169 offset:56320
	global_load_lds_dwordx4 v[216:217], off
	s_add_i32 m0, s34, 0x2000
	s_add_u32 s34, s54, 0x40080
	v_lshl_add_u64 v[216:217], v[218:219], 0, s[12:13]
	s_addc_u32 s35, s55, 0
	s_add_i32 s54, s68, s4
	global_load_lds_dwordx4 v[216:217], off
	s_mov_b32 m0, s54
	s_nop 0
	global_load_lds_dwordx4 v138, s[34:35]
	s_add_i32 m0, s54, 0x2000
	s_nop 0
	global_load_lds_dwordx4 v142, s[34:35]
	v_lshl_add_u64 v[216:217], v[220:221], 0, s[12:13]
	s_mov_b32 m0, s31
	s_nop 0
	global_load_lds_dwordx4 v[216:217], off
	v_lshl_add_u64 v[216:217], v[222:223], 0, s[12:13]
	s_mov_b32 m0, s33
	s_nop 0
	global_load_lds_dwordx4 v[216:217], off
	s_waitcnt vmcnt(8)
	s_waitcnt lgkmcnt(0)
	s_barrier
	s_setprio 1
	s_waitcnt lgkmcnt(0)
	v_mfma_f32_16x16x32_bf16 v[60:63], v[128:131], v[184:187], v[60:63]
	v_mfma_f32_16x16x32_bf16 v[56:59], v[152:155], v[184:187], v[56:59]
	v_mfma_f32_16x16x32_bf16 v[44:47], v[128:131], v[192:195], v[44:47]
	v_mfma_f32_16x16x32_bf16 v[40:43], v[152:155], v[192:195], v[40:43]
	v_mfma_f32_16x16x32_bf16 v[28:31], v[128:131], v[200:203], v[28:31]
	v_mfma_f32_16x16x32_bf16 v[24:27], v[152:155], v[200:203], v[24:27]
	v_mfma_f32_16x16x32_bf16 v[12:15], v[128:131], v[208:211], v[12:15]
	v_mfma_f32_16x16x32_bf16 v[8:11], v[152:155], v[208:211], v[8:11]
	v_mfma_f32_16x16x32_bf16 v[60:63], v[132:135], v[188:191], v[60:63]
	v_mfma_f32_16x16x32_bf16 v[56:59], v[156:159], v[188:191], v[56:59]
	v_mfma_f32_16x16x32_bf16 v[44:47], v[132:135], v[196:199], v[44:47]
	v_mfma_f32_16x16x32_bf16 v[40:43], v[156:159], v[196:199], v[40:43]
	v_mfma_f32_16x16x32_bf16 v[28:31], v[132:135], v[204:207], v[28:31]
	v_mfma_f32_16x16x32_bf16 v[24:27], v[156:159], v[204:207], v[24:27]
	v_mfma_f32_16x16x32_bf16 v[12:15], v[132:135], v[212:215], v[12:15]
	v_mfma_f32_16x16x32_bf16 v[8:11], v[156:159], v[212:215], v[8:11]
	s_setprio 0
	s_setprio 1
	v_mfma_f32_16x16x32_bf16 v[52:55], v[160:163], v[184:187], v[52:55]
	v_mfma_f32_16x16x32_bf16 v[48:51], v[176:179], v[184:187], v[48:51]
	v_mfma_f32_16x16x32_bf16 v[36:39], v[160:163], v[192:195], v[36:39]
	v_mfma_f32_16x16x32_bf16 v[32:35], v[176:179], v[192:195], v[32:35]
	v_mfma_f32_16x16x32_bf16 v[20:23], v[160:163], v[200:203], v[20:23]
	v_mfma_f32_16x16x32_bf16 v[16:19], v[176:179], v[200:203], v[16:19]
	v_mfma_f32_16x16x32_bf16 v[4:7], v[160:163], v[208:211], v[4:7]
	v_mfma_f32_16x16x32_bf16 v[0:3], v[176:179], v[208:211], v[0:3]
	v_mfma_f32_16x16x32_bf16 v[52:55], v[172:175], v[188:191], v[52:55]
	v_mfma_f32_16x16x32_bf16 v[48:51], v[180:183], v[188:191], v[48:51]
	v_mfma_f32_16x16x32_bf16 v[36:39], v[172:175], v[196:199], v[36:39]
	v_mfma_f32_16x16x32_bf16 v[32:35], v[180:183], v[196:199], v[32:35]
	v_mfma_f32_16x16x32_bf16 v[20:23], v[172:175], v[204:207], v[20:23]
	v_mfma_f32_16x16x32_bf16 v[16:19], v[180:183], v[204:207], v[16:19]
	v_mfma_f32_16x16x32_bf16 v[4:7], v[172:175], v[212:215], v[4:7]
	v_mfma_f32_16x16x32_bf16 v[0:3], v[180:183], v[212:215], v[0:3]
	s_setprio 0
	s_add_i32 s66, s66, 2
	s_add_u32 s52, s52, 0x100
	s_addc_u32 s53, s53, 0
	s_add_u32 s64, s64, 0x100
	s_addc_u32 s65, s65, 0
	s_cmp_gt_u32 s66, 13
	s_barrier
	s_cbranch_scc0 .LBB0_1688
	s_and_b64 vcc, exec, s[14:15]
	s_cbranch_vccz .LBB0_1691
	s_barrier

; #define PG8_STAGE(bufoff, gbase, voff) do { _Pragma("unroll") for (int _i = 0; _i < 2; ++_i) \
;         __builtin_amdgcn_global_load_lds((const unsigned*)((const char*)(gbase) + (voff)[_i]), (LAS unsigned*)(lds + (bufoff) + ldsw + _i * 8192), 16, 0, 0); } while (0)
; #define PG8_LDA(dst, b, h) do { _Pragma("unroll") for (int m = 0; m < 4; ++m) _Pragma("unroll") for (int k = 0; k < 2; ++k) dst[m][k] = *(const LAS bf16x8*)(lds + PG8_SA(b, h) + aoff + m * 2048 + k * 1024); } while (0)
; #define PG8_LDB(dst, b, h) do { _Pragma("unroll") for (int n = 0; n < 2; ++n) _Pragma("unroll") for (int k = 0; k < 2; ++k) dst[n][k] = *(const LAS bf16x8*)(lds + PG8_SB(b, h) + boff + n * 2048 + k * 1024); } while (0)
; #define PG8_MMA(ai, bj, At, Bt) do { __builtin_amdgcn_s_setprio(1); _Pragma("unroll") for (int m = 0; m < 4; ++m) _Pragma("unroll") for (int n = 0; n < 2; ++n) _Pragma("unroll") for (int k = 0; k < 2; ++k) \
;         acc[ai][bj][m][n] = __builtin_amdgcn_mfma_f32_16x16x32_bf16(Bt[n][k], At[m][k], acc[ai][bj][m][n], 0, 0, 0); __builtin_amdgcn_s_setprio(0); } while (0)
; #define PG8_WAIT_V(n) asm volatile("s_waitcnt vmcnt(" #n ")" ::: "memory")
; #define PG8_WAIT_L(n) asm volatile("s_waitcnt lgkmcnt(" #n ")" ::: "memory")
; #define PG8_BAR __builtin_amdgcn_s_barrier()
; #define PG8_SCHED __builtin_amdgcn_sched_barrier(0)
; template <class Epi, class Sched, bool ALIGN_EPI = false, bool SP2 = false>
; __device__ __forceinline__ void gemm_phase(LAS unsigned char* lds, const Gemm g, const Sched S, const Epi E) {
;     ...
;             const char* a1 = cA + (size_t)(t + 1) * kstep;
;             const char* a2 = last ? nA : cA + (size_t)(t + 2) * kstep; const char* b2 = last ? nB : cB + (size_t)(t + 2) * kstep;
;             const char* a3 = a2 + kstep; const char* b3 = b2 + kstep;
;             if (last && has_next) S.a_ready(nxt);
;             if constexpr (SP2) {
;             PG8_LDB(B0, 0, 0); PG8_LDB(B1, 0, 1); PG8_SCHED; PG8_LDA(At, 0, 0); PG8_STAGE(PG8_SA(1, 1), a1 + hstepA, voffA);
;             PG8_WAIT_V(8); PG8_WAIT_L(0); PG8_BAR; PG8_MMA(0, 0, At, B0); PG8_MMA(0, 1, At, B1); PG8_BAR; PG8_SCHED;
;             PG8_LDA(At, 0, 1); PG8_STAGE(PG8_SB(0, 0), b2, voffB); PG8_STAGE(PG8_SB(0, 1), b2 + hstepB, voffB); PG8_STAGE(PG8_SA(0, 0), a2, voffA);
;             PG8_WAIT_V(8); PG8_WAIT_L(0); PG8_BAR; PG8_MMA(1, 0, At, B0); PG8_MMA(1, 1, At, B1); PG8_BAR; PG8_SCHED;
.LBB0_1766:
	ds_read_b128 v[128:131], v173
	ds_read_b128 v[132:135], v173 offset:1024
	ds_read_b128 v[136:139], v173 offset:2048
	ds_read_b128 v[140:143], v173 offset:3072
	ds_read_b128 v[160:163], v174
	ds_read_b128 v[164:167], v174 offset:1024
	ds_read_b128 v[178:181], v174 offset:2048
	ds_read_b128 v[182:185], v174 offset:3072
	s_add_u32 s34, s56, 0xfffc0080
	s_addc_u32 s35, s57, -1
	s_cmp_eq_u32 s66, 12
	s_cselect_b32 s61, s19, s35
	s_cselect_b32 s60, s53, s34
	s_cselect_b32 s59, s17, s65
	s_cselect_b32 s58, s63, s64
	s_add_i32 m0, s5, 0xc000
	ds_read_b128 v[186:189], v175
	ds_read_b128 v[190:193], v175 offset:1024
	ds_read_b128 v[194:197], v175 offset:2048
	ds_read_b128 v[198:201], v175 offset:3072
	ds_read_b128 v[202:205], v175 offset:4096
	ds_read_b128 v[206:209], v175 offset:5120
	ds_read_b128 v[210:213], v175 offset:6144
	ds_read_b128 v[214:217], v175 offset:7168
	global_load_lds_dwordx4 v152, s[56:57]
	s_add_i32 m0, s5, 0xe000
	s_nop 0
	global_load_lds_dwordx4 v154, s[56:57]
	s_waitcnt vmcnt(8)
	s_waitcnt lgkmcnt(0)
	s_barrier
	s_setprio 1
	s_waitcnt lgkmcnt(0)
	v_mfma_f32_16x16x32_bf16 v[124:127], v[128:131], v[186:189], v[124:127]
	v_mfma_f32_16x16x32_bf16 v[120:123], v[136:139], v[186:189], v[120:123]
	v_mfma_f32_16x16x32_bf16 v[108:111], v[128:131], v[194:197], v[108:111]
	v_mfma_f32_16x16x32_bf16 v[104:107], v[136:139], v[194:197], v[104:107]
	v_mfma_f32_16x16x32_bf16 v[92:95], v[128:131], v[202:205], v[92:95]
	v_mfma_f32_16x16x32_bf16 v[88:91], v[136:139], v[202:205], v[88:91]
	v_mfma_f32_16x16x32_bf16 v[76:79], v[128:131], v[210:213], v[76:79]
	v_mfma_f32_16x16x32_bf16 v[72:75], v[136:139], v[210:213], v[72:75]
	v_mfma_f32_16x16x32_bf16 v[124:127], v[132:135], v[190:193], v[124:127]
	v_mfma_f32_16x16x32_bf16 v[120:123], v[140:143], v[190:193], v[120:123]
	v_mfma_f32_16x16x32_bf16 v[108:111], v[132:135], v[198:201], v[108:111]
	v_mfma_f32_16x16x32_bf16 v[104:107], v[140:143], v[198:201], v[104:107]
	v_mfma_f32_16x16x32_bf16 v[92:95], v[132:135], v[206:209], v[92:95]
	v_mfma_f32_16x16x32_bf16 v[88:91], v[140:143], v[206:209], v[88:91]
	v_mfma_f32_16x16x32_bf16 v[76:79], v[132:135], v[214:217], v[76:79]
	v_mfma_f32_16x16x32_bf16 v[72:75], v[140:143], v[214:217], v[72:75]
	s_setprio 0
	s_setprio 1
	v_mfma_f32_16x16x32_bf16 v[116:119], v[160:163], v[186:189], v[116:119]
	v_mfma_f32_16x16x32_bf16 v[112:115], v[178:181], v[186:189], v[112:115]
	v_mfma_f32_16x16x32_bf16 v[100:103], v[160:163], v[194:197], v[100:103]
	v_mfma_f32_16x16x32_bf16 v[96:99], v[178:181], v[194:197], v[96:99]
	v_mfma_f32_16x16x32_bf16 v[84:87], v[160:163], v[202:205], v[84:87]
	v_mfma_f32_16x16x32_bf16 v[80:83], v[178:181], v[202:205], v[80:83]
	v_mfma_f32_16x16x32_bf16 v[68:71], v[160:163], v[210:213], v[68:71]
	v_mfma_f32_16x16x32_bf16 v[64:67], v[178:181], v[210:213], v[64:67]
	v_mfma_f32_16x16x32_bf16 v[116:119], v[164:167], v[190:193], v[116:119]
	v_mfma_f32_16x16x32_bf16 v[112:115], v[182:185], v[190:193], v[112:115]
	v_mfma_f32_16x16x32_bf16 v[100:103], v[164:167], v[198:201], v[100:103]
	v_mfma_f32_16x16x32_bf16 v[96:99], v[182:185], v[198:201], v[96:99]
	v_mfma_f32_16x16x32_bf16 v[84:87], v[164:167], v[206:209], v[84:87]
	v_mfma_f32_16x16x32_bf16 v[80:83], v[182:185], v[206:209], v[80:83]
	v_mfma_f32_16x16x32_bf16 v[68:71], v[164:167], v[214:217], v[68:71]
	v_mfma_f32_16x16x32_bf16 v[64:67], v[182:185], v[214:217], v[64:67]
	s_setprio 0
	s_barrier
	s_add_i32 s34, s55, s4
	v_lshl_add_u64 v[168:169], s[58:59], 0, v[146:147]
	s_mov_b32 m0, s34
	ds_read_b128 v[186:189], v175 offset:16384
	ds_read_b128 v[190:193], v175 offset:17408
	ds_read_b128 v[194:197], v175 offset:18432
	ds_read_b128 v[198:201], v175 offset:19456
	ds_read_b128 v[202:205], v175 offset:20480
	ds_read_b128 v[206:209], v175 offset:21504
	ds_read_b128 v[210:213], v175 offset:22528
	ds_read_b128 v[214:217], v175 offset:23552
	global_load_lds_dwordx4 v[168:169], off
	s_add_i32 m0, s34, 0x2000
	s_add_u32 s34, s58, 0x40000
	v_lshl_add_u64 v[218:219], s[58:59], 0, v[150:151]
	s_addc_u32 s35, s59, 0
	s_add_i32 s67, s62, s4
	global_load_lds_dwordx4 v[218:219], off
	s_mov_b32 m0, s67
	v_lshl_add_u64 v[222:223], s[60:61], 0, v[148:149]
	global_load_lds_dwordx4 v146, s[34:35]
	s_add_i32 m0, s67, 0x2000
	s_nop 0
	global_load_lds_dwordx4 v150, s[34:35]
	v_lshl_add_u64 v[220:221], s[60:61], 0, v[144:145]
	s_mov_b32 m0, s5
	s_nop 0
	global_load_lds_dwordx4 v[220:221], off
	s_mov_b32 m0, s20
	s_nop 0
	global_load_lds_dwordx4 v[222:223], off
	s_waitcnt vmcnt(8)
	s_waitcnt lgkmcnt(0)
	s_barrier
; #define PG8_STAGE(bufoff, gbase, voff) do { _Pragma("unroll") for (int _i = 0; _i < 2; ++_i) \
;         __builtin_amdgcn_global_load_lds((const unsigned*)((const char*)(gbase) + (voff)[_i]), (LAS unsigned*)(lds + (bufoff) + ldsw + _i * 8192), 16, 0, 0); } while (0)
; #define PG8_LDA(dst, b, h) do { _Pragma("unroll") for (int m = 0; m < 4; ++m) _Pragma("unroll") for (int k = 0; k < 2; ++k) dst[m][k] = *(const LAS bf16x8*)(lds + PG8_SA(b, h) + aoff + m * 2048 + k * 1024); } while (0)
; #define PG8_LDB(dst, b, h) do { _Pragma("unroll") for (int n = 0; n < 2; ++n) _Pragma("unroll") for (int k = 0; k < 2; ++k) dst[n][k] = *(const LAS bf16x8*)(lds + PG8_SB(b, h) + boff + n * 2048 + k * 1024); } while (0)
; #define PG8_MMA(ai, bj, At, Bt) do { __builtin_amdgcn_s_setprio(1); _Pragma("unroll") for (int m = 0; m < 4; ++m) _Pragma("unroll") for (int n = 0; n < 2; ++n) _Pragma("unroll") for (int k = 0; k < 2; ++k) \
;         acc[ai][bj][m][n] = __builtin_amdgcn_mfma_f32_16x16x32_bf16(Bt[n][k], At[m][k], acc[ai][bj][m][n], 0, 0, 0); __builtin_amdgcn_s_setprio(0); } while (0)
; #define PG8_WAIT_V(n) asm volatile("s_waitcnt vmcnt(" #n ")" ::: "memory")
; #define PG8_WAIT_L(n) asm volatile("s_waitcnt lgkmcnt(" #n ")" ::: "memory")
; #define PG8_BAR __builtin_amdgcn_s_barrier()
; #define PG8_SCHED __builtin_amdgcn_sched_barrier(0)
; template <class Epi, class Sched, bool ALIGN_EPI = false, bool SP2 = false>
; __device__ __forceinline__ void gemm_phase(LAS unsigned char* lds, const Gemm g, const Sched S, const Epi E) {
;     ...
;             PG8_WAIT_V(8); PG8_WAIT_L(0); PG8_BAR; PG8_MMA(1, 0, At, B0); PG8_MMA(1, 1, At, B1); PG8_BAR; PG8_SCHED;
;             PG8_LDB(B0, 1, 0); PG8_LDB(B1, 1, 1); PG8_SCHED; PG8_LDA(At, 1, 0); PG8_STAGE(PG8_SA(0, 1), a2 + hstepA, voffA);
;             PG8_WAIT_V(8); PG8_WAIT_L(0); PG8_BAR; PG8_MMA(0, 0, At, B0); PG8_MMA(0, 1, At, B1); PG8_BAR; PG8_SCHED;
	s_setprio 1
	s_waitcnt lgkmcnt(0)
	v_mfma_f32_16x16x32_bf16 v[60:63], v[128:131], v[186:189], v[60:63]
	v_mfma_f32_16x16x32_bf16 v[56:59], v[136:139], v[186:189], v[56:59]
	v_mfma_f32_16x16x32_bf16 v[44:47], v[128:131], v[194:197], v[44:47]
	v_mfma_f32_16x16x32_bf16 v[40:43], v[136:139], v[194:197], v[40:43]
	v_mfma_f32_16x16x32_bf16 v[28:31], v[128:131], v[202:205], v[28:31]
	v_mfma_f32_16x16x32_bf16 v[24:27], v[136:139], v[202:205], v[24:27]
	v_mfma_f32_16x16x32_bf16 v[12:15], v[128:131], v[210:213], v[12:15]
	v_mfma_f32_16x16x32_bf16 v[8:11], v[136:139], v[210:213], v[8:11]
	v_mfma_f32_16x16x32_bf16 v[60:63], v[132:135], v[190:193], v[60:63]
	v_mfma_f32_16x16x32_bf16 v[56:59], v[140:143], v[190:193], v[56:59]
	v_mfma_f32_16x16x32_bf16 v[44:47], v[132:135], v[198:201], v[44:47]
	v_mfma_f32_16x16x32_bf16 v[40:43], v[140:143], v[198:201], v[40:43]
	v_mfma_f32_16x16x32_bf16 v[28:31], v[132:135], v[206:209], v[28:31]
	v_mfma_f32_16x16x32_bf16 v[24:27], v[140:143], v[206:209], v[24:27]
	v_mfma_f32_16x16x32_bf16 v[12:15], v[132:135], v[214:217], v[12:15]
	v_mfma_f32_16x16x32_bf16 v[8:11], v[140:143], v[214:217], v[8:11]
	s_setprio 0
	s_setprio 1
	v_mfma_f32_16x16x32_bf16 v[52:55], v[160:163], v[186:189], v[52:55]
	v_mfma_f32_16x16x32_bf16 v[48:51], v[178:181], v[186:189], v[48:51]
	v_mfma_f32_16x16x32_bf16 v[36:39], v[160:163], v[194:197], v[36:39]
	v_mfma_f32_16x16x32_bf16 v[32:35], v[178:181], v[194:197], v[32:35]
	v_mfma_f32_16x16x32_bf16 v[20:23], v[160:163], v[202:205], v[20:23]
	v_mfma_f32_16x16x32_bf16 v[16:19], v[178:181], v[202:205], v[16:19]
	v_mfma_f32_16x16x32_bf16 v[4:7], v[160:163], v[210:213], v[4:7]
	v_mfma_f32_16x16x32_bf16 v[0:3], v[178:181], v[210:213], v[0:3]
	v_mfma_f32_16x16x32_bf16 v[52:55], v[164:167], v[190:193], v[52:55]
	v_mfma_f32_16x16x32_bf16 v[48:51], v[182:185], v[190:193], v[48:51]
	v_mfma_f32_16x16x32_bf16 v[36:39], v[164:167], v[198:201], v[36:39]
	v_mfma_f32_16x16x32_bf16 v[32:35], v[182:185], v[198:201], v[32:35]
	v_mfma_f32_16x16x32_bf16 v[20:23], v[164:167], v[206:209], v[20:23]
	v_mfma_f32_16x16x32_bf16 v[16:19], v[182:185], v[206:209], v[16:19]
	v_mfma_f32_16x16x32_bf16 v[4:7], v[164:167], v[214:217], v[4:7]
	v_mfma_f32_16x16x32_bf16 v[0:3], v[182:185], v[214:217], v[0:3]
	s_setprio 0
	s_barrier
	s_add_i32 s67, 0, 0x18000
	s_add_i32 s68, 0, 0x1c000
	v_add_u32_e32 v140, s67, v171
	v_add_u32_e32 v177, s68, v171
	ds_read_b128 v[128:131], v140
	ds_read_b128 v[132:135], v140 offset:1024
	ds_read_b128 v[136:139], v140 offset:2048
	ds_read_b128 v[140:143], v140 offset:3072
	ds_read_b128 v[160:163], v177
	ds_read_b128 v[164:167], v177 offset:1024
	ds_read_b128 v[178:181], v177 offset:2048
	ds_read_b128 v[182:185], v177 offset:3072
	s_add_u32 s34, s60, 0x40000
	s_addc_u32 s35, s61, 0
	s_mov_b32 m0, s21
	ds_read_b128 v[186:189], v175 offset:32768
	ds_read_b128 v[190:193], v175 offset:33792
	ds_read_b128 v[194:197], v175 offset:34816
	ds_read_b128 v[198:201], v175 offset:35840
	ds_read_b128 v[202:205], v175 offset:36864
	ds_read_b128 v[206:209], v175 offset:37888
	ds_read_b128 v[210:213], v175 offset:38912
	ds_read_b128 v[214:217], v175 offset:39936
	global_load_lds_dwordx4 v144, s[34:35]
	s_mov_b32 m0, s29
	s_nop 0
	global_load_lds_dwordx4 v148, s[34:35]
	s_waitcnt vmcnt(8)
	s_waitcnt lgkmcnt(0)
	s_barrier
	s_setprio 1
	s_waitcnt lgkmcnt(0)
	v_mfma_f32_16x16x32_bf16 v[124:127], v[128:131], v[186:189], v[124:127]
	v_mfma_f32_16x16x32_bf16 v[120:123], v[136:139], v[186:189], v[120:123]
	v_mfma_f32_16x16x32_bf16 v[108:111], v[128:131], v[194:197], v[108:111]
	v_mfma_f32_16x16x32_bf16 v[104:107], v[136:139], v[194:197], v[104:107]
	v_mfma_f32_16x16x32_bf16 v[92:95], v[128:131], v[202:205], v[92:95]
	v_mfma_f32_16x16x32_bf16 v[88:91], v[136:139], v[202:205], v[88:91]
	v_mfma_f32_16x16x32_bf16 v[76:79], v[128:131], v[210:213], v[76:79]
	v_mfma_f32_16x16x32_bf16 v[72:75], v[136:139], v[210:213], v[72:75]
	v_mfma_f32_16x16x32_bf16 v[124:127], v[132:135], v[190:193], v[124:127]
	v_mfma_f32_16x16x32_bf16 v[120:123], v[140:143], v[190:193], v[120:123]
	v_mfma_f32_16x16x32_bf16 v[108:111], v[132:135], v[198:201], v[108:111]
	v_mfma_f32_16x16x32_bf16 v[104:107], v[140:143], v[198:201], v[104:107]
	v_mfma_f32_16x16x32_bf16 v[92:95], v[132:135], v[206:209], v[92:95]
	v_mfma_f32_16x16x32_bf16 v[88:91], v[140:143], v[206:209], v[88:91]
	v_mfma_f32_16x16x32_bf16 v[76:79], v[132:135], v[214:217], v[76:79]
	v_mfma_f32_16x16x32_bf16 v[72:75], v[140:143], v[214:217], v[72:75]
	s_setprio 0
	s_setprio 1
	v_mfma_f32_16x16x32_bf16 v[116:119], v[160:163], v[186:189], v[116:119]
	v_mfma_f32_16x16x32_bf16 v[112:115], v[178:181], v[186:189], v[112:115]
	v_mfma_f32_16x16x32_bf16 v[100:103], v[160:163], v[194:197], v[100:103]
	v_mfma_f32_16x16x32_bf16 v[96:99], v[178:181], v[194:197], v[96:99]
	v_mfma_f32_16x16x32_bf16 v[84:87], v[160:163], v[202:205], v[84:87]
	v_mfma_f32_16x16x32_bf16 v[80:83], v[178:181], v[202:205], v[80:83]
	v_mfma_f32_16x16x32_bf16 v[68:71], v[160:163], v[210:213], v[68:71]
	v_mfma_f32_16x16x32_bf16 v[64:67], v[178:181], v[210:213], v[64:67]
	v_mfma_f32_16x16x32_bf16 v[116:119], v[164:167], v[190:193], v[116:119]
	v_mfma_f32_16x16x32_bf16 v[112:115], v[182:185], v[190:193], v[112:115]
	v_mfma_f32_16x16x32_bf16 v[100:103], v[164:167], v[198:201], v[100:103]
	v_mfma_f32_16x16x32_bf16 v[96:99], v[182:185], v[198:201], v[96:99]
	v_mfma_f32_16x16x32_bf16 v[84:87], v[164:167], v[206:209], v[84:87]
	v_mfma_f32_16x16x32_bf16 v[80:83], v[182:185], v[206:209], v[80:83]
	v_mfma_f32_16x16x32_bf16 v[68:71], v[164:167], v[214:217], v[68:71]
	v_mfma_f32_16x16x32_bf16 v[64:67], v[182:185], v[214:217], v[64:67]
	s_setprio 0
	s_barrier
; #define PG8_STAGE(bufoff, gbase, voff) do { _Pragma("unroll") for (int _i = 0; _i < 2; ++_i) \
;         __builtin_amdgcn_global_load_lds((const unsigned*)((const char*)(gbase) + (voff)[_i]), (LAS unsigned*)(lds + (bufoff) + ldsw + _i * 8192), 16, 0, 0); } while (0)
; #define PG8_LDA(dst, b, h) do { _Pragma("unroll") for (int m = 0; m < 4; ++m) _Pragma("unroll") for (int k = 0; k < 2; ++k) dst[m][k] = *(const LAS bf16x8*)(lds + PG8_SA(b, h) + aoff + m * 2048 + k * 1024); } while (0)
; #define PG8_MMA(ai, bj, At, Bt) do { __builtin_amdgcn_s_setprio(1); _Pragma("unroll") for (int m = 0; m < 4; ++m) _Pragma("unroll") for (int n = 0; n < 2; ++n) _Pragma("unroll") for (int k = 0; k < 2; ++k) \
;         acc[ai][bj][m][n] = __builtin_amdgcn_mfma_f32_16x16x32_bf16(Bt[n][k], At[m][k], acc[ai][bj][m][n], 0, 0, 0); __builtin_amdgcn_s_setprio(0); } while (0)
; #define PG8_WAIT_V(n) asm volatile("s_waitcnt vmcnt(" #n ")" ::: "memory")
; #define PG8_WAIT_L(n) asm volatile("s_waitcnt lgkmcnt(" #n ")" ::: "memory")
; #define PG8_BAR __builtin_amdgcn_s_barrier()
; #define PG8_SCHED __builtin_amdgcn_sched_barrier(0)
; template <class Epi, class Sched, bool ALIGN_EPI = false, bool SP2 = false>
; __device__ __forceinline__ void gemm_phase(LAS unsigned char* lds, const Gemm g, const Sched S, const Epi E) {
;     ...
;         for (int t = 0; t < nt; t += 2) {
;     ...
;             PG8_LDA(At, 1, 1); PG8_STAGE(PG8_SB(1, 0), b3, voffB); PG8_STAGE(PG8_SB(1, 1), b3 + hstepB, voffB); PG8_STAGE(PG8_SA(1, 0), a3, voffA);
;             PG8_WAIT_V(8); PG8_WAIT_L(0); PG8_BAR; PG8_MMA(1, 0, At, B0); PG8_MMA(1, 1, At, B1); PG8_BAR; PG8_SCHED;
	s_add_i32 s34, s67, s4
	v_lshl_add_u64 v[168:169], v[168:169], 0, s[12:13]
	s_mov_b32 m0, s34
	ds_read_b128 v[186:189], v175 offset:49152
	ds_read_b128 v[190:193], v175 offset:50176
	ds_read_b128 v[194:197], v175 offset:51200
	ds_read_b128 v[198:201], v175 offset:52224
	ds_read_b128 v[202:205], v175 offset:53248
	ds_read_b128 v[206:209], v175 offset:54272
	ds_read_b128 v[210:213], v175 offset:55296
	ds_read_b128 v[214:217], v175 offset:56320
	global_load_lds_dwordx4 v[168:169], off
	s_add_i32 m0, s34, 0x2000
	s_add_u32 s34, s58, 0x40080
	v_lshl_add_u64 v[168:169], v[218:219], 0, s[12:13]
	s_addc_u32 s35, s59, 0
	s_add_i32 s58, s68, s4
	global_load_lds_dwordx4 v[168:169], off
	s_mov_b32 m0, s58
	s_nop 0
	global_load_lds_dwordx4 v146, s[34:35]
	s_add_i32 m0, s58, 0x2000
	s_nop 0
	global_load_lds_dwordx4 v150, s[34:35]
	v_lshl_add_u64 v[168:169], v[220:221], 0, s[12:13]
	s_mov_b32 m0, s31
	s_nop 0
	global_load_lds_dwordx4 v[168:169], off
	v_lshl_add_u64 v[168:169], v[222:223], 0, s[12:13]
	s_mov_b32 m0, s33
	s_nop 0
	global_load_lds_dwordx4 v[168:169], off
	s_waitcnt vmcnt(8)
	s_waitcnt lgkmcnt(0)
	s_barrier
	s_setprio 1
	s_waitcnt lgkmcnt(0)
	v_mfma_f32_16x16x32_bf16 v[60:63], v[128:131], v[186:189], v[60:63]
	v_mfma_f32_16x16x32_bf16 v[56:59], v[136:139], v[186:189], v[56:59]
	v_mfma_f32_16x16x32_bf16 v[44:47], v[128:131], v[194:197], v[44:47]
	v_mfma_f32_16x16x32_bf16 v[40:43], v[136:139], v[194:197], v[40:43]
	v_mfma_f32_16x16x32_bf16 v[28:31], v[128:131], v[202:205], v[28:31]
	v_mfma_f32_16x16x32_bf16 v[24:27], v[136:139], v[202:205], v[24:27]
	v_mfma_f32_16x16x32_bf16 v[12:15], v[128:131], v[210:213], v[12:15]
	v_mfma_f32_16x16x32_bf16 v[8:11], v[136:139], v[210:213], v[8:11]
	v_mfma_f32_16x16x32_bf16 v[60:63], v[132:135], v[190:193], v[60:63]
	v_mfma_f32_16x16x32_bf16 v[56:59], v[140:143], v[190:193], v[56:59]
	v_mfma_f32_16x16x32_bf16 v[44:47], v[132:135], v[198:201], v[44:47]
	v_mfma_f32_16x16x32_bf16 v[40:43], v[140:143], v[198:201], v[40:43]
	v_mfma_f32_16x16x32_bf16 v[28:31], v[132:135], v[206:209], v[28:31]
	v_mfma_f32_16x16x32_bf16 v[24:27], v[140:143], v[206:209], v[24:27]
	v_mfma_f32_16x16x32_bf16 v[12:15], v[132:135], v[214:217], v[12:15]
	v_mfma_f32_16x16x32_bf16 v[8:11], v[140:143], v[214:217], v[8:11]
	s_setprio 0
	s_setprio 1
	v_mfma_f32_16x16x32_bf16 v[52:55], v[160:163], v[186:189], v[52:55]
	v_mfma_f32_16x16x32_bf16 v[48:51], v[178:181], v[186:189], v[48:51]
	v_mfma_f32_16x16x32_bf16 v[36:39], v[160:163], v[194:197], v[36:39]
	v_mfma_f32_16x16x32_bf16 v[32:35], v[178:181], v[194:197], v[32:35]
	v_mfma_f32_16x16x32_bf16 v[20:23], v[160:163], v[202:205], v[20:23]
	v_mfma_f32_16x16x32_bf16 v[16:19], v[178:181], v[202:205], v[16:19]
	v_mfma_f32_16x16x32_bf16 v[4:7], v[160:163], v[210:213], v[4:7]
	v_mfma_f32_16x16x32_bf16 v[0:3], v[178:181], v[210:213], v[0:3]
	v_mfma_f32_16x16x32_bf16 v[52:55], v[164:167], v[190:193], v[52:55]
	v_mfma_f32_16x16x32_bf16 v[48:51], v[182:185], v[190:193], v[48:51]
	v_mfma_f32_16x16x32_bf16 v[36:39], v[164:167], v[198:201], v[36:39]
	v_mfma_f32_16x16x32_bf16 v[32:35], v[182:185], v[198:201], v[32:35]
	v_mfma_f32_16x16x32_bf16 v[20:23], v[164:167], v[206:209], v[20:23]
	v_mfma_f32_16x16x32_bf16 v[16:19], v[182:185], v[206:209], v[16:19]
	v_mfma_f32_16x16x32_bf16 v[4:7], v[164:167], v[214:217], v[4:7]
	v_mfma_f32_16x16x32_bf16 v[0:3], v[182:185], v[214:217], v[0:3]
	s_setprio 0
	s_add_i32 s66, s66, 2
	s_add_u32 s56, s56, 0x100
	s_addc_u32 s57, s57, 0
	s_add_u32 s64, s64, 0x100
	s_addc_u32 s65, s65, 0
	s_cmp_gt_u32 s66, 13
	s_barrier
	s_cbranch_scc0 .LBB0_1766
	s_and_b64 vcc, exec, s[14:15]
	s_cbranch_vccz .LBB0_1769
	s_barrier

; #define PG8_STAGE(bufoff, gbase, voff) do { _Pragma("unroll") for (int _i = 0; _i < 2; ++_i) \
;         __builtin_amdgcn_global_load_lds((const unsigned*)((const char*)(gbase) + (voff)[_i]), (LAS unsigned*)(lds + (bufoff) + ldsw + _i * 8192), 16, 0, 0); } while (0)
; #define PG8_LDA(dst, b, h) do { _Pragma("unroll") for (int m = 0; m < 4; ++m) _Pragma("unroll") for (int k = 0; k < 2; ++k) dst[m][k] = *(const LAS bf16x8*)(lds + PG8_SA(b, h) + aoff + m * 2048 + k * 1024); } while (0)
; #define PG8_LDB(dst, b, h) do { _Pragma("unroll") for (int n = 0; n < 2; ++n) _Pragma("unroll") for (int k = 0; k < 2; ++k) dst[n][k] = *(const LAS bf16x8*)(lds + PG8_SB(b, h) + boff + n * 2048 + k * 1024); } while (0)
; #define PG8_MMA(ai, bj, At, Bt) do { __builtin_amdgcn_s_setprio(1); _Pragma("unroll") for (int m = 0; m < 4; ++m) _Pragma("unroll") for (int n = 0; n < 2; ++n) _Pragma("unroll") for (int k = 0; k < 2; ++k) \
;         acc[ai][bj][m][n] = __builtin_amdgcn_mfma_f32_16x16x32_bf16(Bt[n][k], At[m][k], acc[ai][bj][m][n], 0, 0, 0); __builtin_amdgcn_s_setprio(0); } while (0)
; #define PG8_WAIT_V(n) asm volatile("s_waitcnt vmcnt(" #n ")" ::: "memory")
; #define PG8_WAIT_L(n) asm volatile("s_waitcnt lgkmcnt(" #n ")" ::: "memory")
; #define PG8_BAR __builtin_amdgcn_s_barrier()
; #define PG8_SCHED __builtin_amdgcn_sched_barrier(0)
; template <class Epi, class Sched, bool ALIGN_EPI = false, bool SP2 = false>
; __device__ __forceinline__ void gemm_phase(LAS unsigned char* lds, const Gemm g, const Sched S, const Epi E) {
;     ...
;             const char* a1 = cA + (size_t)(t + 1) * kstep;
;             const char* a2 = last ? nA : cA + (size_t)(t + 2) * kstep; const char* b2 = last ? nB : cB + (size_t)(t + 2) * kstep;
;             const char* a3 = a2 + kstep; const char* b3 = b2 + kstep;
;             if (last && has_next) S.a_ready(nxt);
;             if constexpr (SP2) {
;             PG8_LDB(B0, 0, 0); PG8_LDB(B1, 0, 1); PG8_SCHED; PG8_LDA(At, 0, 0); PG8_STAGE(PG8_SA(1, 1), a1 + hstepA, voffA);
;             PG8_WAIT_V(8); PG8_WAIT_L(0); PG8_BAR; PG8_MMA(0, 0, At, B0); PG8_MMA(0, 1, At, B1); PG8_BAR; PG8_SCHED;
;             PG8_LDA(At, 0, 1); PG8_STAGE(PG8_SB(0, 0), b2, voffB); PG8_STAGE(PG8_SB(0, 1), b2 + hstepB, voffB); PG8_STAGE(PG8_SA(0, 0), a2, voffA);
;             PG8_WAIT_V(8); PG8_WAIT_L(0); PG8_BAR; PG8_MMA(1, 0, At, B0); PG8_MMA(1, 1, At, B1); PG8_BAR; PG8_SCHED;
.LBB0_1850:
	ds_read_b128 v[166:169], v155
	ds_read_b128 v[170:173], v155 offset:1024
	ds_read_b128 v[174:177], v155 offset:2048
	ds_read_b128 v[178:181], v155 offset:3072
	ds_read_b128 v[182:185], v159
	ds_read_b128 v[186:189], v159 offset:1024
	ds_read_b128 v[190:193], v159 offset:2048
	ds_read_b128 v[194:197], v159 offset:3072
	s_add_u32 s12, s10, 0xfff80080
	s_addc_u32 s13, s11, -1
	s_cmp_eq_u32 s51, 12
	s_cselect_b32 s15, s16, s13
	s_cselect_b32 s14, s17, s12
	s_cselect_b32 s13, s18, s23
	s_cselect_b32 s12, s19, s22
	s_add_i32 m0, s20, 0xc000
	ds_read_b128 v[198:201], v163
	ds_read_b128 v[202:205], v163 offset:1024
	ds_read_b128 v[206:209], v163 offset:2048
	ds_read_b128 v[210:213], v163 offset:3072
	ds_read_b128 v[214:217], v163 offset:4096
	ds_read_b128 v[218:221], v163 offset:5120
	ds_read_b128 v[222:225], v163 offset:6144
	ds_read_b128 v[226:229], v163 offset:7168
	global_load_lds_dwordx4 v136, s[10:11]
	s_add_i32 m0, s20, 0xe000
	s_nop 0
	global_load_lds_dwordx4 v138, s[10:11]
	s_waitcnt vmcnt(8)
	s_waitcnt lgkmcnt(0)
	s_barrier
	s_setprio 1
	s_waitcnt lgkmcnt(0)
	v_mfma_f32_16x16x32_bf16 v[124:127], v[166:169], v[198:201], v[124:127]
	v_mfma_f32_16x16x32_bf16 v[120:123], v[174:177], v[198:201], v[120:123]
	v_mfma_f32_16x16x32_bf16 v[108:111], v[166:169], v[206:209], v[108:111]
	v_mfma_f32_16x16x32_bf16 v[104:107], v[174:177], v[206:209], v[104:107]
	v_mfma_f32_16x16x32_bf16 v[92:95], v[166:169], v[214:217], v[92:95]
	v_mfma_f32_16x16x32_bf16 v[88:91], v[174:177], v[214:217], v[88:91]
	v_mfma_f32_16x16x32_bf16 v[76:79], v[166:169], v[222:225], v[76:79]
	v_mfma_f32_16x16x32_bf16 v[72:75], v[174:177], v[222:225], v[72:75]
	v_mfma_f32_16x16x32_bf16 v[124:127], v[170:173], v[202:205], v[124:127]
	v_mfma_f32_16x16x32_bf16 v[120:123], v[178:181], v[202:205], v[120:123]
	v_mfma_f32_16x16x32_bf16 v[108:111], v[170:173], v[210:213], v[108:111]
	v_mfma_f32_16x16x32_bf16 v[104:107], v[178:181], v[210:213], v[104:107]
	v_mfma_f32_16x16x32_bf16 v[92:95], v[170:173], v[218:221], v[92:95]
	v_mfma_f32_16x16x32_bf16 v[88:91], v[178:181], v[218:221], v[88:91]
	v_mfma_f32_16x16x32_bf16 v[76:79], v[170:173], v[226:229], v[76:79]
	v_mfma_f32_16x16x32_bf16 v[72:75], v[178:181], v[226:229], v[72:75]
	s_setprio 0
	s_setprio 1
	v_mfma_f32_16x16x32_bf16 v[116:119], v[182:185], v[198:201], v[116:119]
	v_mfma_f32_16x16x32_bf16 v[112:115], v[190:193], v[198:201], v[112:115]
	v_mfma_f32_16x16x32_bf16 v[100:103], v[182:185], v[206:209], v[100:103]
	v_mfma_f32_16x16x32_bf16 v[96:99], v[190:193], v[206:209], v[96:99]
	v_mfma_f32_16x16x32_bf16 v[84:87], v[182:185], v[214:217], v[84:87]
	v_mfma_f32_16x16x32_bf16 v[80:83], v[190:193], v[214:217], v[80:83]
	v_mfma_f32_16x16x32_bf16 v[68:71], v[182:185], v[222:225], v[68:71]
	v_mfma_f32_16x16x32_bf16 v[64:67], v[190:193], v[222:225], v[64:67]
	v_mfma_f32_16x16x32_bf16 v[116:119], v[186:189], v[202:205], v[116:119]
	v_mfma_f32_16x16x32_bf16 v[112:115], v[194:197], v[202:205], v[112:115]
	v_mfma_f32_16x16x32_bf16 v[100:103], v[186:189], v[210:213], v[100:103]
	v_mfma_f32_16x16x32_bf16 v[96:99], v[194:197], v[210:213], v[96:99]
	v_mfma_f32_16x16x32_bf16 v[84:87], v[186:189], v[218:221], v[84:87]
	v_mfma_f32_16x16x32_bf16 v[80:83], v[194:197], v[218:221], v[80:83]
	v_mfma_f32_16x16x32_bf16 v[68:71], v[186:189], v[226:229], v[68:71]
	v_mfma_f32_16x16x32_bf16 v[64:67], v[194:197], v[226:229], v[64:67]
	s_setprio 0
	s_barrier
	s_add_i32 s34, s61, s4
	v_lshl_add_u64 v[144:145], s[12:13], 0, v[132:133]
	s_mov_b32 m0, s34
	ds_read_b128 v[198:201], v163 offset:16384
	ds_read_b128 v[202:205], v163 offset:17408
	ds_read_b128 v[206:209], v163 offset:18432
	ds_read_b128 v[210:213], v163 offset:19456
	ds_read_b128 v[214:217], v163 offset:20480
	ds_read_b128 v[218:221], v163 offset:21504
	ds_read_b128 v[222:225], v163 offset:22528
	ds_read_b128 v[226:229], v163 offset:23552
	global_load_lds_dwordx4 v[144:145], off
	s_add_i32 m0, s34, 0x2000
	s_add_u32 s34, s12, 0x40000
	v_lshl_add_u64 v[152:153], s[12:13], 0, v[128:129]
	s_addc_u32 s35, s13, 0
	s_add_i32 s53, s62, s4
	global_load_lds_dwordx4 v[152:153], off
	s_mov_b32 m0, s53
	v_lshl_add_u64 v[160:161], s[14:15], 0, v[130:131]
	global_load_lds_dwordx4 v132, s[34:35]
	s_add_i32 m0, s53, 0x2000
	s_nop 0
	global_load_lds_dwordx4 v128, s[34:35]
	v_lshl_add_u64 v[156:157], s[14:15], 0, v[134:135]
	s_mov_b32 m0, s20
	s_nop 0
	global_load_lds_dwordx4 v[156:157], off
	s_mov_b32 m0, s21
	s_nop 0
	global_load_lds_dwordx4 v[160:161], off
	s_waitcnt vmcnt(8)
	s_waitcnt lgkmcnt(0)
	s_barrier
; #define PG8_STAGE(bufoff, gbase, voff) do { _Pragma("unroll") for (int _i = 0; _i < 2; ++_i) \
;         __builtin_amdgcn_global_load_lds((const unsigned*)((const char*)(gbase) + (voff)[_i]), (LAS unsigned*)(lds + (bufoff) + ldsw + _i * 8192), 16, 0, 0); } while (0)
; #define PG8_LDA(dst, b, h) do { _Pragma("unroll") for (int m = 0; m < 4; ++m) _Pragma("unroll") for (int k = 0; k < 2; ++k) dst[m][k] = *(const LAS bf16x8*)(lds + PG8_SA(b, h) + aoff + m * 2048 + k * 1024); } while (0)
; #define PG8_LDB(dst, b, h) do { _Pragma("unroll") for (int n = 0; n < 2; ++n) _Pragma("unroll") for (int k = 0; k < 2; ++k) dst[n][k] = *(const LAS bf16x8*)(lds + PG8_SB(b, h) + boff + n * 2048 + k * 1024); } while (0)
; #define PG8_MMA(ai, bj, At, Bt) do { __builtin_amdgcn_s_setprio(1); _Pragma("unroll") for (int m = 0; m < 4; ++m) _Pragma("unroll") for (int n = 0; n < 2; ++n) _Pragma("unroll") for (int k = 0; k < 2; ++k) \
;         acc[ai][bj][m][n] = __builtin_amdgcn_mfma_f32_16x16x32_bf16(Bt[n][k], At[m][k], acc[ai][bj][m][n], 0, 0, 0); __builtin_amdgcn_s_setprio(0); } while (0)
; #define PG8_WAIT_V(n) asm volatile("s_waitcnt vmcnt(" #n ")" ::: "memory")
; #define PG8_WAIT_L(n) asm volatile("s_waitcnt lgkmcnt(" #n ")" ::: "memory")
; #define PG8_BAR __builtin_amdgcn_s_barrier()
; #define PG8_SCHED __builtin_amdgcn_sched_barrier(0)
; template <class Epi, class Sched, bool ALIGN_EPI = false, bool SP2 = false>
; __device__ __forceinline__ void gemm_phase(LAS unsigned char* lds, const Gemm g, const Sched S, const Epi E) {
;     ...
;             PG8_WAIT_V(8); PG8_WAIT_L(0); PG8_BAR; PG8_MMA(1, 0, At, B0); PG8_MMA(1, 1, At, B1); PG8_BAR; PG8_SCHED;
;             PG8_LDB(B0, 1, 0); PG8_LDB(B1, 1, 1); PG8_SCHED; PG8_LDA(At, 1, 0); PG8_STAGE(PG8_SA(0, 1), a2 + hstepA, voffA);
;             PG8_WAIT_V(8); PG8_WAIT_L(0); PG8_BAR; PG8_MMA(0, 0, At, B0); PG8_MMA(0, 1, At, B1); PG8_BAR; PG8_SCHED;
	s_setprio 1
	s_waitcnt lgkmcnt(0)
	v_mfma_f32_16x16x32_bf16 v[60:63], v[166:169], v[198:201], v[60:63]
	v_mfma_f32_16x16x32_bf16 v[56:59], v[174:177], v[198:201], v[56:59]
	v_mfma_f32_16x16x32_bf16 v[44:47], v[166:169], v[206:209], v[44:47]
	v_mfma_f32_16x16x32_bf16 v[40:43], v[174:177], v[206:209], v[40:43]
	v_mfma_f32_16x16x32_bf16 v[28:31], v[166:169], v[214:217], v[28:31]
	v_mfma_f32_16x16x32_bf16 v[24:27], v[174:177], v[214:217], v[24:27]
	v_mfma_f32_16x16x32_bf16 v[12:15], v[166:169], v[222:225], v[12:15]
	v_mfma_f32_16x16x32_bf16 v[8:11], v[174:177], v[222:225], v[8:11]
	v_mfma_f32_16x16x32_bf16 v[60:63], v[170:173], v[202:205], v[60:63]
	v_mfma_f32_16x16x32_bf16 v[56:59], v[178:181], v[202:205], v[56:59]
	v_mfma_f32_16x16x32_bf16 v[44:47], v[170:173], v[210:213], v[44:47]
	v_mfma_f32_16x16x32_bf16 v[40:43], v[178:181], v[210:213], v[40:43]
	v_mfma_f32_16x16x32_bf16 v[28:31], v[170:173], v[218:221], v[28:31]
	v_mfma_f32_16x16x32_bf16 v[24:27], v[178:181], v[218:221], v[24:27]
	v_mfma_f32_16x16x32_bf16 v[12:15], v[170:173], v[226:229], v[12:15]
	v_mfma_f32_16x16x32_bf16 v[8:11], v[178:181], v[226:229], v[8:11]
	s_setprio 0
	s_setprio 1
	v_mfma_f32_16x16x32_bf16 v[52:55], v[182:185], v[198:201], v[52:55]
	v_mfma_f32_16x16x32_bf16 v[48:51], v[190:193], v[198:201], v[48:51]
	v_mfma_f32_16x16x32_bf16 v[36:39], v[182:185], v[206:209], v[36:39]
	v_mfma_f32_16x16x32_bf16 v[32:35], v[190:193], v[206:209], v[32:35]
	v_mfma_f32_16x16x32_bf16 v[20:23], v[182:185], v[214:217], v[20:23]
	v_mfma_f32_16x16x32_bf16 v[16:19], v[190:193], v[214:217], v[16:19]
	v_mfma_f32_16x16x32_bf16 v[4:7], v[182:185], v[222:225], v[4:7]
	v_mfma_f32_16x16x32_bf16 v[0:3], v[190:193], v[222:225], v[0:3]
	v_mfma_f32_16x16x32_bf16 v[52:55], v[186:189], v[202:205], v[52:55]
	v_mfma_f32_16x16x32_bf16 v[48:51], v[194:197], v[202:205], v[48:51]
	v_mfma_f32_16x16x32_bf16 v[36:39], v[186:189], v[210:213], v[36:39]
	v_mfma_f32_16x16x32_bf16 v[32:35], v[194:197], v[210:213], v[32:35]
	v_mfma_f32_16x16x32_bf16 v[20:23], v[186:189], v[218:221], v[20:23]
	v_mfma_f32_16x16x32_bf16 v[16:19], v[194:197], v[218:221], v[16:19]
	v_mfma_f32_16x16x32_bf16 v[4:7], v[186:189], v[226:229], v[4:7]
	v_mfma_f32_16x16x32_bf16 v[0:3], v[194:197], v[226:229], v[0:3]
	s_setprio 0
	s_barrier
	s_add_i32 s34, 0, 0x18000
	v_add_u32_e32 v146, s34, v149
	s_add_i32 s35, 0, 0x1c000
	ds_read_b128 v[166:169], v146
	ds_read_b128 v[170:173], v146 offset:1024
	ds_read_b128 v[174:177], v146 offset:2048
	ds_read_b128 v[178:181], v146 offset:3072
	v_add_u32_e32 v146, s35, v149
	ds_read_b128 v[182:185], v146
	ds_read_b128 v[186:189], v146 offset:1024
	ds_read_b128 v[190:193], v146 offset:2048
	ds_read_b128 v[194:197], v146 offset:3072
	s_add_u32 s14, s14, 0x80000
	s_addc_u32 s15, s15, 0
	s_mov_b32 m0, s29
	ds_read_b128 v[198:201], v163 offset:32768
	ds_read_b128 v[202:205], v163 offset:33792
	ds_read_b128 v[206:209], v163 offset:34816
	ds_read_b128 v[210:213], v163 offset:35840
	ds_read_b128 v[214:217], v163 offset:36864
	ds_read_b128 v[218:221], v163 offset:37888
	ds_read_b128 v[222:225], v163 offset:38912
	ds_read_b128 v[226:229], v163 offset:39936
	global_load_lds_dwordx4 v134, s[14:15]
	s_mov_b32 m0, s30
	s_nop 0
	global_load_lds_dwordx4 v130, s[14:15]
	s_waitcnt vmcnt(8)
	s_waitcnt lgkmcnt(0)
	s_barrier
	s_setprio 1
	s_waitcnt lgkmcnt(0)
	v_mfma_f32_16x16x32_bf16 v[124:127], v[166:169], v[198:201], v[124:127]
	v_mfma_f32_16x16x32_bf16 v[120:123], v[174:177], v[198:201], v[120:123]
	v_mfma_f32_16x16x32_bf16 v[108:111], v[166:169], v[206:209], v[108:111]
	v_mfma_f32_16x16x32_bf16 v[104:107], v[174:177], v[206:209], v[104:107]
	v_mfma_f32_16x16x32_bf16 v[92:95], v[166:169], v[214:217], v[92:95]
	v_mfma_f32_16x16x32_bf16 v[88:91], v[174:177], v[214:217], v[88:91]
	v_mfma_f32_16x16x32_bf16 v[76:79], v[166:169], v[222:225], v[76:79]
	v_mfma_f32_16x16x32_bf16 v[72:75], v[174:177], v[222:225], v[72:75]
	v_mfma_f32_16x16x32_bf16 v[124:127], v[170:173], v[202:205], v[124:127]
	v_mfma_f32_16x16x32_bf16 v[120:123], v[178:181], v[202:205], v[120:123]
	v_mfma_f32_16x16x32_bf16 v[108:111], v[170:173], v[210:213], v[108:111]
	v_mfma_f32_16x16x32_bf16 v[104:107], v[178:181], v[210:213], v[104:107]
	v_mfma_f32_16x16x32_bf16 v[92:95], v[170:173], v[218:221], v[92:95]
	v_mfma_f32_16x16x32_bf16 v[88:91], v[178:181], v[218:221], v[88:91]
	v_mfma_f32_16x16x32_bf16 v[76:79], v[170:173], v[226:229], v[76:79]
	v_mfma_f32_16x16x32_bf16 v[72:75], v[178:181], v[226:229], v[72:75]
	s_setprio 0
	s_setprio 1
	v_mfma_f32_16x16x32_bf16 v[116:119], v[182:185], v[198:201], v[116:119]
	v_mfma_f32_16x16x32_bf16 v[112:115], v[190:193], v[198:201], v[112:115]
	v_mfma_f32_16x16x32_bf16 v[100:103], v[182:185], v[206:209], v[100:103]
	v_mfma_f32_16x16x32_bf16 v[96:99], v[190:193], v[206:209], v[96:99]
	v_mfma_f32_16x16x32_bf16 v[84:87], v[182:185], v[214:217], v[84:87]
	v_mfma_f32_16x16x32_bf16 v[80:83], v[190:193], v[214:217], v[80:83]
	v_mfma_f32_16x16x32_bf16 v[68:71], v[182:185], v[222:225], v[68:71]
	v_mfma_f32_16x16x32_bf16 v[64:67], v[190:193], v[222:225], v[64:67]
	v_mfma_f32_16x16x32_bf16 v[116:119], v[186:189], v[202:205], v[116:119]
	v_mfma_f32_16x16x32_bf16 v[112:115], v[194:197], v[202:205], v[112:115]
	v_mfma_f32_16x16x32_bf16 v[100:103], v[186:189], v[210:213], v[100:103]
	v_mfma_f32_16x16x32_bf16 v[96:99], v[194:197], v[210:213], v[96:99]
	v_mfma_f32_16x16x32_bf16 v[84:87], v[186:189], v[218:221], v[84:87]
	v_mfma_f32_16x16x32_bf16 v[80:83], v[194:197], v[218:221], v[80:83]
	v_mfma_f32_16x16x32_bf16 v[68:71], v[186:189], v[226:229], v[68:71]
	v_mfma_f32_16x16x32_bf16 v[64:67], v[194:197], v[226:229], v[64:67]
	s_setprio 0
	s_barrier
; #define PG8_STAGE(bufoff, gbase, voff) do { _Pragma("unroll") for (int _i = 0; _i < 2; ++_i) \
;         __builtin_amdgcn_global_load_lds((const unsigned*)((const char*)(gbase) + (voff)[_i]), (LAS unsigned*)(lds + (bufoff) + ldsw + _i * 8192), 16, 0, 0); } while (0)
; #define PG8_LDA(dst, b, h) do { _Pragma("unroll") for (int m = 0; m < 4; ++m) _Pragma("unroll") for (int k = 0; k < 2; ++k) dst[m][k] = *(const LAS bf16x8*)(lds + PG8_SA(b, h) + aoff + m * 2048 + k * 1024); } while (0)
; #define PG8_MMA(ai, bj, At, Bt) do { __builtin_amdgcn_s_setprio(1); _Pragma("unroll") for (int m = 0; m < 4; ++m) _Pragma("unroll") for (int n = 0; n < 2; ++n) _Pragma("unroll") for (int k = 0; k < 2; ++k) \
;         acc[ai][bj][m][n] = __builtin_amdgcn_mfma_f32_16x16x32_bf16(Bt[n][k], At[m][k], acc[ai][bj][m][n], 0, 0, 0); __builtin_amdgcn_s_setprio(0); } while (0)
; #define PG8_WAIT_V(n) asm volatile("s_waitcnt vmcnt(" #n ")" ::: "memory")
; #define PG8_WAIT_L(n) asm volatile("s_waitcnt lgkmcnt(" #n ")" ::: "memory")
; #define PG8_BAR __builtin_amdgcn_s_barrier()
; #define PG8_SCHED __builtin_amdgcn_sched_barrier(0)
; template <class Epi, class Sched, bool ALIGN_EPI = false, bool SP2 = false>
; __device__ __forceinline__ void gemm_phase(LAS unsigned char* lds, const Gemm g, const Sched S, const Epi E) {
;     ...
;         for (int t = 0; t < nt; t += 2) {
;     ...
;             PG8_LDA(At, 1, 1); PG8_STAGE(PG8_SB(1, 0), b3, voffB); PG8_STAGE(PG8_SB(1, 1), b3 + hstepB, voffB); PG8_STAGE(PG8_SA(1, 0), a3, voffA);
;             PG8_WAIT_V(8); PG8_WAIT_L(0); PG8_BAR; PG8_MMA(1, 0, At, B0); PG8_MMA(1, 1, At, B1); PG8_BAR; PG8_SCHED;
	s_add_i32 s14, s34, s4
	v_lshl_add_u64 v[144:145], v[144:145], 0, s[46:47]
	s_mov_b32 m0, s14
	ds_read_b128 v[198:201], v163 offset:49152
	ds_read_b128 v[202:205], v163 offset:50176
	ds_read_b128 v[206:209], v163 offset:51200
	ds_read_b128 v[210:213], v163 offset:52224
	ds_read_b128 v[214:217], v163 offset:53248
	ds_read_b128 v[218:221], v163 offset:54272
	ds_read_b128 v[222:225], v163 offset:55296
	ds_read_b128 v[226:229], v163 offset:56320
	global_load_lds_dwordx4 v[144:145], off
	s_add_i32 m0, s14, 0x2000
	s_add_u32 s12, s12, 0x40080
	v_lshl_add_u64 v[144:145], v[152:153], 0, s[46:47]
	s_addc_u32 s13, s13, 0
	s_add_i32 s14, s35, s4
	global_load_lds_dwordx4 v[144:145], off
	s_mov_b32 m0, s14
	s_nop 0
	global_load_lds_dwordx4 v132, s[12:13]
	s_add_i32 m0, s14, 0x2000
	s_nop 0
	global_load_lds_dwordx4 v128, s[12:13]
	v_lshl_add_u64 v[144:145], v[156:157], 0, s[46:47]
	s_mov_b32 m0, s33
	s_nop 0
	global_load_lds_dwordx4 v[144:145], off
	v_lshl_add_u64 v[144:145], v[160:161], 0, s[46:47]
	s_mov_b32 m0, s58
	s_nop 0
	global_load_lds_dwordx4 v[144:145], off
	s_waitcnt vmcnt(8)
	s_waitcnt lgkmcnt(0)
	s_barrier
	s_setprio 1
	s_waitcnt lgkmcnt(0)
	v_mfma_f32_16x16x32_bf16 v[60:63], v[166:169], v[198:201], v[60:63]
	v_mfma_f32_16x16x32_bf16 v[56:59], v[174:177], v[198:201], v[56:59]
	v_mfma_f32_16x16x32_bf16 v[44:47], v[166:169], v[206:209], v[44:47]
	v_mfma_f32_16x16x32_bf16 v[40:43], v[174:177], v[206:209], v[40:43]
	v_mfma_f32_16x16x32_bf16 v[28:31], v[166:169], v[214:217], v[28:31]
	v_mfma_f32_16x16x32_bf16 v[24:27], v[174:177], v[214:217], v[24:27]
	v_mfma_f32_16x16x32_bf16 v[12:15], v[166:169], v[222:225], v[12:15]
	v_mfma_f32_16x16x32_bf16 v[8:11], v[174:177], v[222:225], v[8:11]
	v_mfma_f32_16x16x32_bf16 v[60:63], v[170:173], v[202:205], v[60:63]
	v_mfma_f32_16x16x32_bf16 v[56:59], v[178:181], v[202:205], v[56:59]
	v_mfma_f32_16x16x32_bf16 v[44:47], v[170:173], v[210:213], v[44:47]
	v_mfma_f32_16x16x32_bf16 v[40:43], v[178:181], v[210:213], v[40:43]
	v_mfma_f32_16x16x32_bf16 v[28:31], v[170:173], v[218:221], v[28:31]
	v_mfma_f32_16x16x32_bf16 v[24:27], v[178:181], v[218:221], v[24:27]
	v_mfma_f32_16x16x32_bf16 v[12:15], v[170:173], v[226:229], v[12:15]
	v_mfma_f32_16x16x32_bf16 v[8:11], v[178:181], v[226:229], v[8:11]
	s_setprio 0
	s_setprio 1
	v_mfma_f32_16x16x32_bf16 v[52:55], v[182:185], v[198:201], v[52:55]
	v_mfma_f32_16x16x32_bf16 v[48:51], v[190:193], v[198:201], v[48:51]
	v_mfma_f32_16x16x32_bf16 v[36:39], v[182:185], v[206:209], v[36:39]
	v_mfma_f32_16x16x32_bf16 v[32:35], v[190:193], v[206:209], v[32:35]
	v_mfma_f32_16x16x32_bf16 v[20:23], v[182:185], v[214:217], v[20:23]
	v_mfma_f32_16x16x32_bf16 v[16:19], v[190:193], v[214:217], v[16:19]
	v_mfma_f32_16x16x32_bf16 v[4:7], v[182:185], v[222:225], v[4:7]
	v_mfma_f32_16x16x32_bf16 v[0:3], v[190:193], v[222:225], v[0:3]
	v_mfma_f32_16x16x32_bf16 v[52:55], v[186:189], v[202:205], v[52:55]
	v_mfma_f32_16x16x32_bf16 v[48:51], v[194:197], v[202:205], v[48:51]
	v_mfma_f32_16x16x32_bf16 v[36:39], v[186:189], v[210:213], v[36:39]
	v_mfma_f32_16x16x32_bf16 v[32:35], v[194:197], v[210:213], v[32:35]
	v_mfma_f32_16x16x32_bf16 v[20:23], v[186:189], v[218:221], v[20:23]
	v_mfma_f32_16x16x32_bf16 v[16:19], v[194:197], v[218:221], v[16:19]
	v_mfma_f32_16x16x32_bf16 v[4:7], v[186:189], v[226:229], v[4:7]
	v_mfma_f32_16x16x32_bf16 v[0:3], v[194:197], v[226:229], v[0:3]
	s_setprio 0
	s_add_i32 s51, s51, 2
	s_add_u32 s10, s10, 0x100
	s_addc_u32 s11, s11, 0
	s_add_u32 s22, s22, 0x100
	s_addc_u32 s23, s23, 0
	s_cmp_gt_u32 s51, 13
	s_barrier
	s_cbranch_scc0 .LBB0_1850
	s_and_b64 vcc, exec, s[48:49]
	s_cbranch_vccz .LBB0_1853
	s_barrier

; #define PG8_STAGE(bufoff, gbase, voff) do { _Pragma("unroll") for (int _i = 0; _i < 2; ++_i) \
;         __builtin_amdgcn_global_load_lds((const unsigned*)((const char*)(gbase) + (voff)[_i]), (LAS unsigned*)(lds + (bufoff) + ldsw + _i * 8192), 16, 0, 0); } while (0)
; #define PG8_LDA(dst, b, h) do { _Pragma("unroll") for (int m = 0; m < 4; ++m) _Pragma("unroll") for (int k = 0; k < 2; ++k) dst[m][k] = *(const LAS bf16x8*)(lds + PG8_SA(b, h) + aoff + m * 2048 + k * 1024); } while (0)
; #define PG8_LDB(dst, b, h) do { _Pragma("unroll") for (int n = 0; n < 2; ++n) _Pragma("unroll") for (int k = 0; k < 2; ++k) dst[n][k] = *(const LAS bf16x8*)(lds + PG8_SB(b, h) + boff + n * 2048 + k * 1024); } while (0)
; #define PG8_MMA(ai, bj, At, Bt) do { __builtin_amdgcn_s_setprio(1); _Pragma("unroll") for (int m = 0; m < 4; ++m) _Pragma("unroll") for (int n = 0; n < 2; ++n) _Pragma("unroll") for (int k = 0; k < 2; ++k) \
;         acc[ai][bj][m][n] = __builtin_amdgcn_mfma_f32_16x16x32_bf16(Bt[n][k], At[m][k], acc[ai][bj][m][n], 0, 0, 0); __builtin_amdgcn_s_setprio(0); } while (0)
; #define PG8_WAIT_V(n) asm volatile("s_waitcnt vmcnt(" #n ")" ::: "memory")
; #define PG8_WAIT_L(n) asm volatile("s_waitcnt lgkmcnt(" #n ")" ::: "memory")
; #define PG8_BAR __builtin_amdgcn_s_barrier()
; #define PG8_SCHED __builtin_amdgcn_sched_barrier(0)
; template <class Epi, class Sched, bool ALIGN_EPI = false, bool SP2 = false>
; __device__ __forceinline__ void gemm_phase(LAS unsigned char* lds, const Gemm g, const Sched S, const Epi E) {
;     ...
;             PG8_LDB(B0, 0, 0); PG8_LDB(B1, 0, 1); PG8_SCHED; PG8_LDA(At, 0, 0); PG8_STAGE(PG8_SA(1, 1), a1 + hstepA, voffA);
;             PG8_WAIT_V(8); PG8_WAIT_L(0); PG8_BAR; PG8_MMA(0, 0, At, B0); PG8_MMA(0, 1, At, B1); PG8_BAR; PG8_SCHED;
;             PG8_LDA(At, 0, 1); PG8_STAGE(PG8_SB(0, 0), b2, voffB); PG8_STAGE(PG8_SB(0, 1), b2 + hstepB, voffB); PG8_STAGE(PG8_SA(0, 0), a2, voffA);
;             PG8_WAIT_V(8); PG8_WAIT_L(0); PG8_BAR; PG8_MMA(1, 0, At, B0); PG8_MMA(1, 1, At, B1); PG8_BAR; PG8_SCHED;
.LBB0_1930:
	ds_read_b128 v[144:147], v155
	ds_read_b128 v[148:151], v155 offset:1024
	ds_read_b128 v[158:161], v155 offset:2048
	ds_read_b128 v[162:165], v155 offset:3072
	ds_read_b128 v[166:169], v156
	ds_read_b128 v[170:173], v156 offset:1024
	ds_read_b128 v[174:177], v156 offset:2048
	ds_read_b128 v[178:181], v156 offset:3072
	s_add_u32 s44, s42, 0x100
	s_addc_u32 s45, s43, 0
	s_cmp_eq_u32 s66, 40
	s_cselect_b32 s49, s7, s45
	s_cselect_b32 s48, s6, s44
	s_cselect_b32 s47, s39, s65
	s_cselect_b32 s46, s38, s64
	s_add_i32 m0, s21, 0xc000
	ds_read_b128 v[182:185], v157
	ds_read_b128 v[186:189], v157 offset:1024
	ds_read_b128 v[190:193], v157 offset:2048
	ds_read_b128 v[194:197], v157 offset:3072
	ds_read_b128 v[198:201], v157 offset:4096
	ds_read_b128 v[202:205], v157 offset:5120
	ds_read_b128 v[206:209], v157 offset:6144
	ds_read_b128 v[210:213], v157 offset:7168
	global_load_lds_dwordx4 v136, s[42:43]
	s_add_i32 m0, s21, 0xe000
	s_nop 0
	global_load_lds_dwordx4 v138, s[42:43]
	s_waitcnt vmcnt(8)
	s_waitcnt lgkmcnt(0)
	s_barrier
	s_setprio 1
	s_waitcnt lgkmcnt(0)
	v_mfma_f32_16x16x32_bf16 v[124:127], v[144:147], v[182:185], v[124:127]
	v_mfma_f32_16x16x32_bf16 v[120:123], v[158:161], v[182:185], v[120:123]
	v_mfma_f32_16x16x32_bf16 v[108:111], v[144:147], v[190:193], v[108:111]
	v_mfma_f32_16x16x32_bf16 v[104:107], v[158:161], v[190:193], v[104:107]
	v_mfma_f32_16x16x32_bf16 v[92:95], v[144:147], v[198:201], v[92:95]
	v_mfma_f32_16x16x32_bf16 v[88:91], v[158:161], v[198:201], v[88:91]
	v_mfma_f32_16x16x32_bf16 v[76:79], v[144:147], v[206:209], v[76:79]
	v_mfma_f32_16x16x32_bf16 v[72:75], v[158:161], v[206:209], v[72:75]
	v_mfma_f32_16x16x32_bf16 v[124:127], v[148:151], v[186:189], v[124:127]
	v_mfma_f32_16x16x32_bf16 v[120:123], v[162:165], v[186:189], v[120:123]
	v_mfma_f32_16x16x32_bf16 v[108:111], v[148:151], v[194:197], v[108:111]
	v_mfma_f32_16x16x32_bf16 v[104:107], v[162:165], v[194:197], v[104:107]
	v_mfma_f32_16x16x32_bf16 v[92:95], v[148:151], v[202:205], v[92:95]
	v_mfma_f32_16x16x32_bf16 v[88:91], v[162:165], v[202:205], v[88:91]
	v_mfma_f32_16x16x32_bf16 v[76:79], v[148:151], v[210:213], v[76:79]
	v_mfma_f32_16x16x32_bf16 v[72:75], v[162:165], v[210:213], v[72:75]
	s_setprio 0
	s_setprio 1
	v_mfma_f32_16x16x32_bf16 v[116:119], v[166:169], v[182:185], v[116:119]
	v_mfma_f32_16x16x32_bf16 v[112:115], v[174:177], v[182:185], v[112:115]
	v_mfma_f32_16x16x32_bf16 v[100:103], v[166:169], v[190:193], v[100:103]
	v_mfma_f32_16x16x32_bf16 v[96:99], v[174:177], v[190:193], v[96:99]
	v_mfma_f32_16x16x32_bf16 v[84:87], v[166:169], v[198:201], v[84:87]
	v_mfma_f32_16x16x32_bf16 v[80:83], v[174:177], v[198:201], v[80:83]
	v_mfma_f32_16x16x32_bf16 v[68:71], v[166:169], v[206:209], v[68:71]
	v_mfma_f32_16x16x32_bf16 v[64:67], v[174:177], v[206:209], v[64:67]
	v_mfma_f32_16x16x32_bf16 v[116:119], v[170:173], v[186:189], v[116:119]
	v_mfma_f32_16x16x32_bf16 v[112:115], v[178:181], v[186:189], v[112:115]
	v_mfma_f32_16x16x32_bf16 v[100:103], v[170:173], v[194:197], v[100:103]
	v_mfma_f32_16x16x32_bf16 v[96:99], v[178:181], v[194:197], v[96:99]
	v_mfma_f32_16x16x32_bf16 v[84:87], v[170:173], v[202:205], v[84:87]
	v_mfma_f32_16x16x32_bf16 v[80:83], v[178:181], v[202:205], v[80:83]
	v_mfma_f32_16x16x32_bf16 v[68:71], v[170:173], v[210:213], v[68:71]
	v_mfma_f32_16x16x32_bf16 v[64:67], v[178:181], v[210:213], v[64:67]
	s_setprio 0
	s_barrier
	s_add_i32 s34, s54, s20
	v_lshl_add_u64 v[214:215], s[46:47], 0, v[130:131]
	s_mov_b32 m0, s34
	ds_read_b128 v[182:185], v157 offset:16384
	ds_read_b128 v[186:189], v157 offset:17408
	ds_read_b128 v[190:193], v157 offset:18432
	ds_read_b128 v[194:197], v157 offset:19456
	ds_read_b128 v[198:201], v157 offset:20480
	ds_read_b128 v[202:205], v157 offset:21504
	ds_read_b128 v[206:209], v157 offset:22528
	ds_read_b128 v[210:213], v157 offset:23552
	global_load_lds_dwordx4 v[214:215], off
	s_add_i32 m0, s34, 0x2000
	s_add_u32 s34, s46, 0xb0000
	v_lshl_add_u64 v[216:217], s[46:47], 0, v[134:135]
	s_addc_u32 s35, s47, 0
	s_add_i32 s42, s55, s20
	global_load_lds_dwordx4 v[216:217], off
	s_mov_b32 m0, s42
	v_lshl_add_u64 v[220:221], s[48:49], 0, v[132:133]
	global_load_lds_dwordx4 v130, s[34:35]
	s_add_i32 m0, s42, 0x2000
	s_nop 0
	global_load_lds_dwordx4 v134, s[34:35]
	v_lshl_add_u64 v[218:219], s[48:49], 0, v[128:129]
	s_mov_b32 m0, s21
	s_nop 0
	global_load_lds_dwordx4 v[218:219], off
	s_mov_b32 m0, s29
	s_nop 0
	global_load_lds_dwordx4 v[220:221], off
	s_waitcnt vmcnt(8)
	s_waitcnt lgkmcnt(0)
	s_barrier
; #define PG8_STAGE(bufoff, gbase, voff) do { _Pragma("unroll") for (int _i = 0; _i < 2; ++_i) \
;         __builtin_amdgcn_global_load_lds((const unsigned*)((const char*)(gbase) + (voff)[_i]), (LAS unsigned*)(lds + (bufoff) + ldsw + _i * 8192), 16, 0, 0); } while (0)
; #define PG8_LDA(dst, b, h) do { _Pragma("unroll") for (int m = 0; m < 4; ++m) _Pragma("unroll") for (int k = 0; k < 2; ++k) dst[m][k] = *(const LAS bf16x8*)(lds + PG8_SA(b, h) + aoff + m * 2048 + k * 1024); } while (0)
; #define PG8_LDB(dst, b, h) do { _Pragma("unroll") for (int n = 0; n < 2; ++n) _Pragma("unroll") for (int k = 0; k < 2; ++k) dst[n][k] = *(const LAS bf16x8*)(lds + PG8_SB(b, h) + boff + n * 2048 + k * 1024); } while (0)
; #define PG8_MMA(ai, bj, At, Bt) do { __builtin_amdgcn_s_setprio(1); _Pragma("unroll") for (int m = 0; m < 4; ++m) _Pragma("unroll") for (int n = 0; n < 2; ++n) _Pragma("unroll") for (int k = 0; k < 2; ++k) \
;         acc[ai][bj][m][n] = __builtin_amdgcn_mfma_f32_16x16x32_bf16(Bt[n][k], At[m][k], acc[ai][bj][m][n], 0, 0, 0); __builtin_amdgcn_s_setprio(0); } while (0)
; #define PG8_WAIT_V(n) asm volatile("s_waitcnt vmcnt(" #n ")" ::: "memory")
; #define PG8_WAIT_L(n) asm volatile("s_waitcnt lgkmcnt(" #n ")" ::: "memory")
; #define PG8_BAR __builtin_amdgcn_s_barrier()
; #define PG8_SCHED __builtin_amdgcn_sched_barrier(0)
; template <class Epi, class Sched, bool ALIGN_EPI = false, bool SP2 = false>
; __device__ __forceinline__ void gemm_phase(LAS unsigned char* lds, const Gemm g, const Sched S, const Epi E) {
;     ...
;             PG8_WAIT_V(8); PG8_WAIT_L(0); PG8_BAR; PG8_MMA(1, 0, At, B0); PG8_MMA(1, 1, At, B1); PG8_BAR; PG8_SCHED;
;             PG8_LDB(B0, 1, 0); PG8_LDB(B1, 1, 1); PG8_SCHED; PG8_LDA(At, 1, 0); PG8_STAGE(PG8_SA(0, 1), a2 + hstepA, voffA);
;             PG8_WAIT_V(8); PG8_WAIT_L(0); PG8_BAR; PG8_MMA(0, 0, At, B0); PG8_MMA(0, 1, At, B1); PG8_BAR; PG8_SCHED;
	s_setprio 1
	s_waitcnt lgkmcnt(0)
	v_mfma_f32_16x16x32_bf16 v[60:63], v[144:147], v[182:185], v[60:63]
	v_mfma_f32_16x16x32_bf16 v[56:59], v[158:161], v[182:185], v[56:59]
	v_mfma_f32_16x16x32_bf16 v[44:47], v[144:147], v[190:193], v[44:47]
	v_mfma_f32_16x16x32_bf16 v[40:43], v[158:161], v[190:193], v[40:43]
	v_mfma_f32_16x16x32_bf16 v[28:31], v[144:147], v[198:201], v[28:31]
	v_mfma_f32_16x16x32_bf16 v[24:27], v[158:161], v[198:201], v[24:27]
	v_mfma_f32_16x16x32_bf16 v[12:15], v[144:147], v[206:209], v[12:15]
	v_mfma_f32_16x16x32_bf16 v[8:11], v[158:161], v[206:209], v[8:11]
	v_mfma_f32_16x16x32_bf16 v[60:63], v[148:151], v[186:189], v[60:63]
	v_mfma_f32_16x16x32_bf16 v[56:59], v[162:165], v[186:189], v[56:59]
	v_mfma_f32_16x16x32_bf16 v[44:47], v[148:151], v[194:197], v[44:47]
	v_mfma_f32_16x16x32_bf16 v[40:43], v[162:165], v[194:197], v[40:43]
	v_mfma_f32_16x16x32_bf16 v[28:31], v[148:151], v[202:205], v[28:31]
	v_mfma_f32_16x16x32_bf16 v[24:27], v[162:165], v[202:205], v[24:27]
	v_mfma_f32_16x16x32_bf16 v[12:15], v[148:151], v[210:213], v[12:15]
	v_mfma_f32_16x16x32_bf16 v[8:11], v[162:165], v[210:213], v[8:11]
	s_setprio 0
	s_setprio 1
	v_mfma_f32_16x16x32_bf16 v[52:55], v[166:169], v[182:185], v[52:55]
	v_mfma_f32_16x16x32_bf16 v[48:51], v[174:177], v[182:185], v[48:51]
	v_mfma_f32_16x16x32_bf16 v[36:39], v[166:169], v[190:193], v[36:39]
	v_mfma_f32_16x16x32_bf16 v[32:35], v[174:177], v[190:193], v[32:35]
	v_mfma_f32_16x16x32_bf16 v[20:23], v[166:169], v[198:201], v[20:23]
	v_mfma_f32_16x16x32_bf16 v[16:19], v[174:177], v[198:201], v[16:19]
	v_mfma_f32_16x16x32_bf16 v[4:7], v[166:169], v[206:209], v[4:7]
	v_mfma_f32_16x16x32_bf16 v[0:3], v[174:177], v[206:209], v[0:3]
	v_mfma_f32_16x16x32_bf16 v[52:55], v[170:173], v[186:189], v[52:55]
	v_mfma_f32_16x16x32_bf16 v[48:51], v[178:181], v[186:189], v[48:51]
	v_mfma_f32_16x16x32_bf16 v[36:39], v[170:173], v[194:197], v[36:39]
	v_mfma_f32_16x16x32_bf16 v[32:35], v[178:181], v[194:197], v[32:35]
	v_mfma_f32_16x16x32_bf16 v[20:23], v[170:173], v[202:205], v[20:23]
	v_mfma_f32_16x16x32_bf16 v[16:19], v[178:181], v[202:205], v[16:19]
	v_mfma_f32_16x16x32_bf16 v[4:7], v[170:173], v[210:213], v[4:7]
	v_mfma_f32_16x16x32_bf16 v[0:3], v[178:181], v[210:213], v[0:3]
	s_setprio 0
	s_barrier
	s_add_i32 s42, 0, 0x18000
	s_add_i32 s43, 0, 0x1c000
	v_add_u32_e32 v162, s42, v153
	v_add_u32_e32 v178, s43, v153
	ds_read_b128 v[144:147], v162
	ds_read_b128 v[148:151], v162 offset:1024
	ds_read_b128 v[158:161], v162 offset:2048
	ds_read_b128 v[162:165], v162 offset:3072
	ds_read_b128 v[166:169], v178
	ds_read_b128 v[170:173], v178 offset:1024
	ds_read_b128 v[174:177], v178 offset:2048
	ds_read_b128 v[178:181], v178 offset:3072
	s_add_u32 s34, s48, 0xb0000
	s_addc_u32 s35, s49, 0
	s_mov_b32 m0, s30
	ds_read_b128 v[182:185], v157 offset:32768
	ds_read_b128 v[186:189], v157 offset:33792
	ds_read_b128 v[190:193], v157 offset:34816
	ds_read_b128 v[194:197], v157 offset:35840
	ds_read_b128 v[198:201], v157 offset:36864
	ds_read_b128 v[202:205], v157 offset:37888
	ds_read_b128 v[206:209], v157 offset:38912
	ds_read_b128 v[210:213], v157 offset:39936
	global_load_lds_dwordx4 v128, s[34:35]
	s_mov_b32 m0, s31
	s_nop 0
	global_load_lds_dwordx4 v132, s[34:35]
	s_waitcnt vmcnt(8)
	s_waitcnt lgkmcnt(0)
	s_barrier
	s_setprio 1
	s_waitcnt lgkmcnt(0)
	v_mfma_f32_16x16x32_bf16 v[124:127], v[144:147], v[182:185], v[124:127]
	v_mfma_f32_16x16x32_bf16 v[120:123], v[158:161], v[182:185], v[120:123]
	v_mfma_f32_16x16x32_bf16 v[108:111], v[144:147], v[190:193], v[108:111]
	v_mfma_f32_16x16x32_bf16 v[104:107], v[158:161], v[190:193], v[104:107]
	v_mfma_f32_16x16x32_bf16 v[92:95], v[144:147], v[198:201], v[92:95]
	v_mfma_f32_16x16x32_bf16 v[88:91], v[158:161], v[198:201], v[88:91]
	v_mfma_f32_16x16x32_bf16 v[76:79], v[144:147], v[206:209], v[76:79]
	v_mfma_f32_16x16x32_bf16 v[72:75], v[158:161], v[206:209], v[72:75]
	v_mfma_f32_16x16x32_bf16 v[124:127], v[148:151], v[186:189], v[124:127]
	v_mfma_f32_16x16x32_bf16 v[120:123], v[162:165], v[186:189], v[120:123]
	v_mfma_f32_16x16x32_bf16 v[108:111], v[148:151], v[194:197], v[108:111]
	v_mfma_f32_16x16x32_bf16 v[104:107], v[162:165], v[194:197], v[104:107]
	v_mfma_f32_16x16x32_bf16 v[92:95], v[148:151], v[202:205], v[92:95]
	v_mfma_f32_16x16x32_bf16 v[88:91], v[162:165], v[202:205], v[88:91]
	v_mfma_f32_16x16x32_bf16 v[76:79], v[148:151], v[210:213], v[76:79]
	v_mfma_f32_16x16x32_bf16 v[72:75], v[162:165], v[210:213], v[72:75]
	s_setprio 0
	s_setprio 1
	v_mfma_f32_16x16x32_bf16 v[116:119], v[166:169], v[182:185], v[116:119]
	v_mfma_f32_16x16x32_bf16 v[112:115], v[174:177], v[182:185], v[112:115]
	v_mfma_f32_16x16x32_bf16 v[100:103], v[166:169], v[190:193], v[100:103]
	v_mfma_f32_16x16x32_bf16 v[96:99], v[174:177], v[190:193], v[96:99]
	v_mfma_f32_16x16x32_bf16 v[84:87], v[166:169], v[198:201], v[84:87]
	v_mfma_f32_16x16x32_bf16 v[80:83], v[174:177], v[198:201], v[80:83]
	v_mfma_f32_16x16x32_bf16 v[68:71], v[166:169], v[206:209], v[68:71]
	v_mfma_f32_16x16x32_bf16 v[64:67], v[174:177], v[206:209], v[64:67]
	v_mfma_f32_16x16x32_bf16 v[116:119], v[170:173], v[186:189], v[116:119]
	v_mfma_f32_16x16x32_bf16 v[112:115], v[178:181], v[186:189], v[112:115]
	v_mfma_f32_16x16x32_bf16 v[100:103], v[170:173], v[194:197], v[100:103]
	v_mfma_f32_16x16x32_bf16 v[96:99], v[178:181], v[194:197], v[96:99]
	v_mfma_f32_16x16x32_bf16 v[84:87], v[170:173], v[202:205], v[84:87]
	v_mfma_f32_16x16x32_bf16 v[80:83], v[178:181], v[202:205], v[80:83]
	v_mfma_f32_16x16x32_bf16 v[68:71], v[170:173], v[210:213], v[68:71]
	v_mfma_f32_16x16x32_bf16 v[64:67], v[178:181], v[210:213], v[64:67]
	s_setprio 0
	s_barrier
; #define PG8_STAGE(bufoff, gbase, voff) do { _Pragma("unroll") for (int _i = 0; _i < 2; ++_i) \
;         __builtin_amdgcn_global_load_lds((const unsigned*)((const char*)(gbase) + (voff)[_i]), (LAS unsigned*)(lds + (bufoff) + ldsw + _i * 8192), 16, 0, 0); } while (0)
; #define PG8_LDA(dst, b, h) do { _Pragma("unroll") for (int m = 0; m < 4; ++m) _Pragma("unroll") for (int k = 0; k < 2; ++k) dst[m][k] = *(const LAS bf16x8*)(lds + PG8_SA(b, h) + aoff + m * 2048 + k * 1024); } while (0)
; #define PG8_MMA(ai, bj, At, Bt) do { __builtin_amdgcn_s_setprio(1); _Pragma("unroll") for (int m = 0; m < 4; ++m) _Pragma("unroll") for (int n = 0; n < 2; ++n) _Pragma("unroll") for (int k = 0; k < 2; ++k) \
;         acc[ai][bj][m][n] = __builtin_amdgcn_mfma_f32_16x16x32_bf16(Bt[n][k], At[m][k], acc[ai][bj][m][n], 0, 0, 0); __builtin_amdgcn_s_setprio(0); } while (0)
; #define PG8_WAIT_V(n) asm volatile("s_waitcnt vmcnt(" #n ")" ::: "memory")
; #define PG8_WAIT_L(n) asm volatile("s_waitcnt lgkmcnt(" #n ")" ::: "memory")
; #define PG8_BAR __builtin_amdgcn_s_barrier()
; #define PG8_SCHED __builtin_amdgcn_sched_barrier(0)
; template <class Epi, class Sched, bool ALIGN_EPI = false, bool SP2 = false>
; __device__ __forceinline__ void gemm_phase(LAS unsigned char* lds, const Gemm g, const Sched S, const Epi E) {
;     ...
;         for (int t = 0; t < nt; t += 2) {
;             const bool last = (t == nt - 2);
;             const char* a1 = cA + (size_t)(t + 1) * kstep;
;             const char* a2 = last ? nA : cA + (size_t)(t + 2) * kstep; const char* b2 = last ? nB : cB + (size_t)(t + 2) * kstep;
;     ...
;             PG8_LDA(At, 1, 1); PG8_STAGE(PG8_SB(1, 0), b3, voffB); PG8_STAGE(PG8_SB(1, 1), b3 + hstepB, voffB); PG8_STAGE(PG8_SA(1, 0), a3, voffA);
;             PG8_WAIT_V(8); PG8_WAIT_L(0); PG8_BAR; PG8_MMA(1, 0, At, B0); PG8_MMA(1, 1, At, B1); PG8_BAR; PG8_SCHED;
	s_add_i32 s34, s42, s20
	v_lshl_add_u64 v[214:215], v[214:215], 0, s[12:13]
	s_mov_b32 m0, s34
	ds_read_b128 v[182:185], v157 offset:49152
	ds_read_b128 v[186:189], v157 offset:50176
	ds_read_b128 v[190:193], v157 offset:51200
	ds_read_b128 v[194:197], v157 offset:52224
	ds_read_b128 v[198:201], v157 offset:53248
	ds_read_b128 v[202:205], v157 offset:54272
	ds_read_b128 v[206:209], v157 offset:55296
	ds_read_b128 v[210:213], v157 offset:56320
	global_load_lds_dwordx4 v[214:215], off
	s_add_i32 m0, s34, 0x2000
	s_add_u32 s34, s46, 0xb0080
	v_lshl_add_u64 v[214:215], v[216:217], 0, s[12:13]
	s_addc_u32 s35, s47, 0
	s_add_i32 s42, s43, s20
	global_load_lds_dwordx4 v[214:215], off
	s_mov_b32 m0, s42
	s_nop 0
	global_load_lds_dwordx4 v130, s[34:35]
	s_add_i32 m0, s42, 0x2000
	s_nop 0
	global_load_lds_dwordx4 v134, s[34:35]
	v_lshl_add_u64 v[214:215], v[218:219], 0, s[12:13]
	s_mov_b32 m0, s50
	s_nop 0
	global_load_lds_dwordx4 v[214:215], off
	v_lshl_add_u64 v[214:215], v[220:221], 0, s[12:13]
	s_mov_b32 m0, s51
	s_nop 0
	global_load_lds_dwordx4 v[214:215], off
	s_waitcnt vmcnt(8)
	s_waitcnt lgkmcnt(0)
	s_barrier
	s_setprio 1
	s_waitcnt lgkmcnt(0)
	v_mfma_f32_16x16x32_bf16 v[60:63], v[144:147], v[182:185], v[60:63]
	v_mfma_f32_16x16x32_bf16 v[56:59], v[158:161], v[182:185], v[56:59]
	v_mfma_f32_16x16x32_bf16 v[44:47], v[144:147], v[190:193], v[44:47]
	v_mfma_f32_16x16x32_bf16 v[40:43], v[158:161], v[190:193], v[40:43]
	v_mfma_f32_16x16x32_bf16 v[28:31], v[144:147], v[198:201], v[28:31]
	v_mfma_f32_16x16x32_bf16 v[24:27], v[158:161], v[198:201], v[24:27]
	v_mfma_f32_16x16x32_bf16 v[12:15], v[144:147], v[206:209], v[12:15]
	v_mfma_f32_16x16x32_bf16 v[8:11], v[158:161], v[206:209], v[8:11]
	v_mfma_f32_16x16x32_bf16 v[60:63], v[148:151], v[186:189], v[60:63]
	v_mfma_f32_16x16x32_bf16 v[56:59], v[162:165], v[186:189], v[56:59]
	v_mfma_f32_16x16x32_bf16 v[44:47], v[148:151], v[194:197], v[44:47]
	v_mfma_f32_16x16x32_bf16 v[40:43], v[162:165], v[194:197], v[40:43]
	v_mfma_f32_16x16x32_bf16 v[28:31], v[148:151], v[202:205], v[28:31]
	v_mfma_f32_16x16x32_bf16 v[24:27], v[162:165], v[202:205], v[24:27]
	v_mfma_f32_16x16x32_bf16 v[12:15], v[148:151], v[210:213], v[12:15]
	v_mfma_f32_16x16x32_bf16 v[8:11], v[162:165], v[210:213], v[8:11]
	s_setprio 0
	s_setprio 1
	v_mfma_f32_16x16x32_bf16 v[52:55], v[166:169], v[182:185], v[52:55]
	v_mfma_f32_16x16x32_bf16 v[48:51], v[174:177], v[182:185], v[48:51]
	v_mfma_f32_16x16x32_bf16 v[36:39], v[166:169], v[190:193], v[36:39]
	v_mfma_f32_16x16x32_bf16 v[32:35], v[174:177], v[190:193], v[32:35]
	v_mfma_f32_16x16x32_bf16 v[20:23], v[166:169], v[198:201], v[20:23]
	v_mfma_f32_16x16x32_bf16 v[16:19], v[174:177], v[198:201], v[16:19]
	v_mfma_f32_16x16x32_bf16 v[4:7], v[166:169], v[206:209], v[4:7]
	v_mfma_f32_16x16x32_bf16 v[0:3], v[174:177], v[206:209], v[0:3]
	v_mfma_f32_16x16x32_bf16 v[52:55], v[170:173], v[186:189], v[52:55]
	v_mfma_f32_16x16x32_bf16 v[48:51], v[178:181], v[186:189], v[48:51]
	v_mfma_f32_16x16x32_bf16 v[36:39], v[170:173], v[194:197], v[36:39]
	v_mfma_f32_16x16x32_bf16 v[32:35], v[178:181], v[194:197], v[32:35]
	v_mfma_f32_16x16x32_bf16 v[20:23], v[170:173], v[202:205], v[20:23]
	v_mfma_f32_16x16x32_bf16 v[16:19], v[178:181], v[202:205], v[16:19]
	v_mfma_f32_16x16x32_bf16 v[4:7], v[170:173], v[210:213], v[4:7]
	v_mfma_f32_16x16x32_bf16 v[0:3], v[178:181], v[210:213], v[0:3]
	s_setprio 0
	s_add_i32 s66, s66, 2
	s_add_u32 s64, s64, 0x100
	s_addc_u32 s65, s65, 0
	s_cmp_gt_u32 s66, 41
	s_mov_b64 s[42:43], s[44:45]
	s_barrier
	s_cbranch_scc0 .LBB0_1930
	s_and_b64 vcc, exec, s[14:15]
	s_cbranch_vccz .LBB0_1933
	s_barrier
